# DPP for intra-wave movement: PEER pass-1 reduction network xor-1/2/4/8 exchanges via v_mov_dpp instead of ds_swizzle (both layer copies)
# baseline (speedup 1.0000x reference)
.LBB0_538:
	v_cmp_gt_i32_e32 vcc, s33, v2
	s_or_b64 s[16:17], s[16:17], exec
	s_and_saveexec_b64 s[18:19], vcc
	s_cbranch_execz .LBB0_537
	v_ashrrev_i32_e32 v3, 31, v2
	v_lshlrev_b64 v[4:5], 11, v[2:3]
	v_lshl_add_u64 v[8:9], v[60:61], 0, v[4:5]
	global_load_dwordx4 v[4:7], v[8:9], off offset:16
	s_nop 0
	global_load_dwordx4 v[8:11], v[8:9], off
	v_lshlrev_b64 v[110:111], 9, v[2:3]
	v_lshl_add_u64 v[110:111], v[62:63], 0, v[110:111]
	global_load_dword v112, v[110:111], off
	global_load_dword v113, v[110:111], off offset:64
	global_load_dword v114, v[110:111], off offset:128
	global_load_dword v115, v[110:111], off offset:192
	global_load_dword v116, v[110:111], off offset:256
	global_load_dword v117, v[110:111], off offset:320
	global_load_dword v118, v[110:111], off offset:384
	global_load_dword v119, v[110:111], off offset:448
	s_waitcnt lgkmcnt(0)
	v_add_u32_e32 v109, s20, v193
	s_waitcnt vmcnt(9)
	v_lshlrev_b32_e32 v13, 16, v4
	s_waitcnt vmcnt(8)
	v_lshlrev_b32_e32 v12, 16, v8
	v_and_b32_e32 v8, 0xffff0000, v8
	v_lshlrev_b32_e32 v14, 16, v9
	v_and_b32_e32 v15, 0xffff0000, v9
	v_max3_f32 v0, |v12|, 0, |v8|
	v_lshlrev_b32_e32 v17, 16, v10
	v_and_b32_e32 v10, 0xffff0000, v10
	v_max3_f32 v0, v0, |v14|, |v15|
	v_lshlrev_b32_e32 v19, 16, v11
	v_and_b32_e32 v11, 0xffff0000, v11
	v_max3_f32 v0, v0, |v17|, |v10|
	v_and_b32_e32 v4, 0xffff0000, v4
	v_max3_f32 v0, v0, |v19|, |v11|
	v_lshlrev_b32_e32 v16, 16, v5
	v_and_b32_e32 v5, 0xffff0000, v5
	v_max3_f32 v0, v0, |v13|, |v4|
	v_lshlrev_b32_e32 v18, 16, v6
	v_and_b32_e32 v6, 0xffff0000, v6
	v_max3_f32 v0, v0, |v16|, |v5|
	v_lshlrev_b32_e32 v20, 16, v7
	v_and_b32_e32 v7, 0xffff0000, v7
	v_max3_f32 v0, v0, |v18|, |v6|
	v_max3_f32 v9, v0, |v20|, |v7|
	v_and_b32_e32 v0, 64, v219
	v_add_u32_e32 v21, 64, v0
	v_xor_b32_e32 v0, 32, v219
	v_cmp_lt_i32_e32 vcc, v0, v21
	s_nop 1
	v_cndmask_b32_e32 v0, v219, v0, vcc
	v_lshlrev_b32_e32 v0, 2, v0
	ds_bpermute_b32 v22, v0, v9
	s_waitcnt lgkmcnt(0)
	v_max_f32_e32 v22, v22, v22
	v_max_f32_e32 v9, v9, v22
	v_xor_b32_e32 v22, 16, v219
	v_cmp_lt_i32_e32 vcc, v22, v21
	s_nop 1
	v_cndmask_b32_e32 v22, v219, v22, vcc
	v_lshlrev_b32_e32 v22, 2, v22
	ds_bpermute_b32 v22, v22, v9
	s_waitcnt lgkmcnt(0)
	v_max_f32_e32 v22, v22, v22
	v_max_f32_e32 v9, v9, v22
	v_xor_b32_e32 v22, 8, v219
	v_cmp_lt_i32_e32 vcc, v22, v21
	s_nop 1
	v_cndmask_b32_e32 v22, v219, v22, vcc
	v_lshlrev_b32_e32 v22, 2, v22
	ds_bpermute_b32 v22, v22, v9
	s_waitcnt lgkmcnt(0)
	v_max_f32_e32 v22, v22, v22
	v_max_f32_e32 v9, v9, v22
	v_xor_b32_e32 v22, 4, v219
	v_cmp_lt_i32_e32 vcc, v22, v21
	s_nop 1
	v_cndmask_b32_e32 v22, v219, v22, vcc
	v_lshlrev_b32_e32 v22, 2, v22
	ds_bpermute_b32 v22, v22, v9
	s_waitcnt lgkmcnt(0)
	v_max_f32_e32 v22, v22, v22
	v_max_f32_e32 v9, v9, v22
	v_xor_b32_e32 v22, 2, v219
	v_cmp_lt_i32_e32 vcc, v22, v21
	s_nop 1
	v_cndmask_b32_e32 v22, v219, v22, vcc
	v_lshlrev_b32_e32 v22, 2, v22
	ds_bpermute_b32 v22, v22, v9
	s_waitcnt lgkmcnt(0)
	v_max_f32_e32 v22, v22, v22
	v_max_f32_e32 v9, v9, v22
	v_xor_b32_e32 v22, 1, v219
	v_cmp_lt_i32_e32 vcc, v22, v21
	s_nop 1
	v_cndmask_b32_e32 v21, v219, v22, vcc
	v_lshlrev_b32_e32 v21, 2, v21
	ds_bpermute_b32 v21, v21, v9
	s_waitcnt lgkmcnt(0)
	v_max_f32_e32 v21, v21, v21
	v_max_f32_e32 v9, v9, v21
	v_div_scale_f32 v21, s[22:23], v9, v9, s69
	v_rcp_f32_e32 v22, v21
	v_cmp_lt_f32_e64 s[0:1], 0, v9
	v_fma_f32 v23, -v21, v22, 1.0
	v_fmac_f32_e32 v22, v23, v22
	v_div_scale_f32 v23, vcc, s69, v9, s69
	v_mul_f32_e32 v24, v23, v22
	v_fma_f32 v25, -v21, v24, v23
	v_fmac_f32_e32 v24, v25, v22
	v_fma_f32 v21, -v21, v24, v23
	v_div_fmas_f32 v21, v21, v22, v24
	v_div_fixup_f32 v21, v21, v9, s69
	v_cndmask_b32_e64 v21, 0, v21, s[0:1]
	v_mul_f32_e32 v12, v21, v12
	v_mul_f32_e32 v8, v21, v8
	v_rndne_f32_e32 v12, v12
	v_rndne_f32_e32 v8, v8
	v_cvt_i32_f32_e32 v12, v12
	v_cvt_i32_f32_e32 v8, v8
	v_mul_f32_e32 v14, v21, v14
	v_mul_f32_e32 v15, v21, v15
	v_rndne_f32_e32 v14, v14
	v_rndne_f32_e32 v15, v15
	v_cvt_i32_f32_e32 v14, v14
	v_cvt_i32_f32_e32 v15, v15
	v_mul_f32_e32 v17, v21, v17
	v_mul_f32_e32 v10, v21, v10
	v_rndne_f32_e32 v17, v17
	v_rndne_f32_e32 v10, v10
	v_add_u32_e32 v22, 8, v12
	v_add_u32_e32 v23, 8, v8
	v_cvt_i32_f32_e32 v17, v17
	v_cvt_i32_f32_e32 v10, v10
	v_mul_f32_e32 v11, v21, v11
	v_lshrrev_b32_e32 v22, 4, v22
	v_and_b32_e32 v23, 0xf0, v23
	v_mul_f32_e32 v19, v21, v19
	v_rndne_f32_e32 v11, v11
	v_and_or_b32 v22, v22, 15, v23
	v_lshl_add_u32 v23, v14, 4, v222
	v_lshl_add_u32 v24, v15, 8, v223
	v_rndne_f32_e32 v19, v19
	v_cvt_i32_f32_e32 v11, v11
	v_and_b32_e32 v23, 0xf00, v23
	v_and_b32_e32 v24, 0xf000, v24
	v_cvt_i32_f32_e32 v19, v19
	v_or3_b32 v22, v22, v23, v24
	v_lshl_add_u32 v23, v17, 12, v224
	v_lshl_add_u32 v24, v10, 16, v225
	v_and_b32_e32 v12, 15, v12
	v_lshlrev_b32_e32 v8, 4, v8
	v_lshlrev_b32_e32 v14, 8, v14
	v_and_b32_e32 v23, 0xf0000, v23
	v_and_b32_e32 v24, 0xf00000, v24
	v_and_b32_e32 v8, 0xf0, v8
	v_and_b32_e32 v14, 0xf00, v14
	v_lshlrev_b32_e32 v15, 12, v15
	v_lshlrev_b32_e32 v17, 16, v17
	v_or3_b32 v22, v22, v23, v24
	v_lshl_add_u32 v24, v11, 24, v227
	v_lshl_or_b32 v11, v11, 28, v12
	v_and_b32_e32 v15, 0xf000, v15
	v_and_b32_e32 v17, 0xf0000, v17
	v_lshlrev_b32_e32 v10, 20, v10
	v_lshl_add_u32 v23, v19, 20, v226
	v_lshlrev_b32_e32 v19, 24, v19
	v_or3_b32 v8, v11, v8, v14
	v_and_b32_e32 v10, 0xf00000, v10
	v_and_b32_e32 v19, 0xf000000, v19
	v_or3_b32 v8, v8, v15, v17
	v_or3_b32 v75, v8, v10, v19
	v_mul_f32_e32 v8, v21, v13
	v_mul_f32_e32 v4, v21, v4
	v_rndne_f32_e32 v8, v8
	v_rndne_f32_e32 v4, v4
	v_cvt_i32_f32_e32 v8, v8
	v_cvt_i32_f32_e32 v4, v4
	v_mul_f32_e32 v5, v21, v5
	v_rndne_f32_e32 v5, v5
	v_add_u32_e32 v10, 8, v8
	v_add_u32_e32 v11, 8, v4
	v_lshrrev_b32_e32 v10, 4, v10
	v_and_b32_e32 v11, 0xf0, v11
	v_and_or_b32 v10, v10, 15, v11
	v_mul_f32_e32 v11, v21, v16
	v_rndne_f32_e32 v11, v11
	v_cvt_i32_f32_e32 v11, v11
	v_cvt_i32_f32_e32 v5, v5
	v_mul_f32_e32 v6, v21, v6
	v_rndne_f32_e32 v6, v6
	v_lshl_add_u32 v12, v11, 4, v222
	v_lshl_add_u32 v13, v5, 8, v223
	v_and_b32_e32 v12, 0xf00, v12
	v_and_b32_e32 v13, 0xf000, v13
	v_or3_b32 v10, v10, v12, v13
	v_mul_f32_e32 v12, v21, v18
	v_rndne_f32_e32 v12, v12
	v_cvt_i32_f32_e32 v12, v12
	v_cvt_i32_f32_e32 v6, v6
	v_mul_f32_e32 v7, v21, v7
	v_rndne_f32_e32 v7, v7
	v_lshl_add_u32 v13, v12, 12, v224
	v_lshl_add_u32 v14, v6, 16, v225
	v_and_b32_e32 v13, 0xf0000, v13
	v_and_b32_e32 v14, 0xf00000, v14
	v_or3_b32 v10, v10, v13, v14
	v_mul_f32_e32 v13, v21, v20
	v_rndne_f32_e32 v13, v13
	v_cvt_i32_f32_e32 v7, v7
	v_cvt_i32_f32_e32 v13, v13
	v_and_b32_e32 v8, 15, v8
	v_lshlrev_b32_e32 v4, 4, v4
	v_lshlrev_b32_e32 v11, 8, v11
	v_and_b32_e32 v4, 0xf0, v4
	v_and_b32_e32 v11, 0xf00, v11
	v_lshlrev_b32_e32 v5, 12, v5
	v_lshlrev_b32_e32 v12, 16, v12
	v_lshl_add_u32 v15, v7, 24, v227
	v_lshl_or_b32 v7, v7, 28, v8
	v_and_b32_e32 v5, 0xf000, v5
	v_and_b32_e32 v12, 0xf0000, v12
	v_lshlrev_b32_e32 v6, 20, v6
	v_lshl_add_u32 v14, v13, 20, v226
	v_lshlrev_b32_e32 v13, 24, v13
	v_or3_b32 v4, v7, v4, v11
	v_and_b32_e32 v6, 0xf00000, v6
	v_and_b32_e32 v13, 0xf000000, v13
	v_or3_b32 v4, v4, v5, v12
	v_or3_b32 v108, v4, v6, v13
	v_lshlrev_b64 v[6:7], 9, v[2:3]
	v_and_b32_e32 v14, 0xf000000, v14
	v_and_b32_e32 v15, 0xf0000000, v15
	v_lshl_add_u64 v[4:5], v[62:63], 0, v[6:7]
	v_or3_b32 v77, v10, v14, v15
	s_waitcnt vmcnt(7)
	v_mov_b32_e32 v20, v112
	s_waitcnt vmcnt(6)
	v_mov_b32_e32 v18, v113
	s_waitcnt vmcnt(5)
	v_mov_b32_e32 v16, v114
	s_waitcnt vmcnt(4)
	v_mov_b32_e32 v14, v115
	s_waitcnt vmcnt(3)
	v_mov_b32_e32 v12, v116
	s_waitcnt vmcnt(2)
	v_mov_b32_e32 v10, v117
	s_waitcnt vmcnt(1)
	v_mov_b32_e32 v8, v118
	s_nop 0
	s_waitcnt vmcnt(0)
	v_mov_b32_e32 v4, v119
	v_and_b32_e32 v23, 0xf000000, v23
	v_and_b32_e32 v24, 0xf0000000, v24
	v_or3_b32 v73, v22, v23, v24
	v_mul_f32_e32 v3, 0x3c09ae41, v9
	v_lshl_add_u64 v[6:7], v[64:65], 0, v[6:7]
	v_readlane_b32 s0, v20, 0
	s_lshl_b32 s0, s0, 9
	s_nop 3
	buffer_load_dwordx2 v[100:101], v192, s[52:55], s0 offen
	v_readlane_b32 s0, v20, 1
	s_lshl_b32 s0, s0, 9
	s_nop 3
	buffer_load_dwordx2 v[102:103], v192, s[52:55], s0 offen
	v_readlane_b32 s0, v20, 2
	s_lshl_b32 s0, s0, 9
	s_nop 3
	buffer_load_dwordx2 v[98:99], v192, s[52:55], s0 offen
	v_readlane_b32 s0, v20, 3
	s_lshl_b32 s0, s0, 9
	s_nop 3
	buffer_load_dwordx2 v[104:105], v192, s[52:55], s0 offen
	v_readlane_b32 s0, v20, 4
	s_lshl_b32 s0, s0, 9
	s_nop 3
	buffer_load_dwordx2 v[94:95], v192, s[52:55], s0 offen
	v_readlane_b32 s0, v20, 5
	s_lshl_b32 s0, s0, 9
	s_nop 3
	buffer_load_dwordx2 v[86:87], v192, s[52:55], s0 offen
	v_readlane_b32 s0, v20, 6
	s_lshl_b32 s0, s0, 9
	s_nop 3
	buffer_load_dwordx2 v[84:85], v192, s[52:55], s0 offen
	v_readlane_b32 s0, v20, 7
	s_lshl_b32 s0, s0, 9
	s_nop 3
	buffer_load_dwordx2 v[90:91], v192, s[52:55], s0 offen
	v_readlane_b32 s0, v20, 8
	s_lshl_b32 s0, s0, 9
	s_nop 3
	buffer_load_dwordx2 v[78:79], v192, s[52:55], s0 offen
	v_readlane_b32 s0, v20, 9
	s_lshl_b32 s0, s0, 9
	s_nop 3
	buffer_load_dwordx2 v[50:51], v192, s[52:55], s0 offen
	v_readlane_b32 s0, v20, 10
	s_lshl_b32 s0, s0, 9
	s_nop 3
	buffer_load_dwordx2 v[48:49], v192, s[52:55], s0 offen
	v_readlane_b32 s0, v20, 11
	s_lshl_b32 s0, s0, 9
	s_nop 3
	buffer_load_dwordx2 v[54:55], v192, s[52:55], s0 offen
	v_readlane_b32 s0, v20, 12
	s_lshl_b32 s0, s0, 9
	s_nop 3
	buffer_load_dwordx2 v[42:43], v192, s[52:55], s0 offen
	v_readlane_b32 s0, v20, 13
	s_lshl_b32 s0, s0, 9
	s_nop 3
	buffer_load_dwordx2 v[34:35], v192, s[52:55], s0 offen
	v_readlane_b32 s0, v20, 14
	s_lshl_b32 s0, s0, 9
	s_nop 3
	buffer_load_dwordx2 v[32:33], v192, s[52:55], s0 offen
	v_readlane_b32 s0, v20, 15
	s_lshl_b32 s0, s0, 9
	s_nop 3
	buffer_load_dwordx2 v[38:39], v192, s[52:55], s0 offen
	v_lshlrev_b32_e32 v120, 2, v20
	v_lshlrev_b32_e32 v121, 2, v18
	v_lshlrev_b32_e32 v122, 2, v16
	v_lshlrev_b32_e32 v123, 2, v14
	v_lshlrev_b32_e32 v124, 2, v12
	v_lshlrev_b32_e32 v125, 2, v10
	v_lshlrev_b32_e32 v126, 2, v8
	v_lshlrev_b32_e32 v127, 2, v4
	global_load_dword v128, v120, s[8:9]
	global_load_dword v136, v120, s[10:11]
	global_load_dword v144, v[6:7], off
	global_load_dword v129, v121, s[8:9]
	global_load_dword v137, v121, s[10:11]
	global_load_dword v145, v[6:7], off offset:64
	global_load_dword v130, v122, s[8:9]
	global_load_dword v138, v122, s[10:11]
	global_load_dword v146, v[6:7], off offset:128
	global_load_dword v131, v123, s[8:9]
	global_load_dword v139, v123, s[10:11]
	global_load_dword v147, v[6:7], off offset:192
	global_load_dword v132, v124, s[8:9]
	global_load_dword v140, v124, s[10:11]
	global_load_dword v148, v[6:7], off offset:256
	global_load_dword v133, v125, s[8:9]
	global_load_dword v141, v125, s[10:11]
	global_load_dword v149, v[6:7], off offset:320
	global_load_dword v134, v126, s[8:9]
	global_load_dword v142, v126, s[10:11]
	global_load_dword v150, v[6:7], off offset:384
	global_load_dword v135, v127, s[8:9]
	global_load_dword v143, v127, s[10:11]
	global_load_dword v151, v[6:7], off offset:448
	s_nop 3
	s_waitcnt vmcnt(39)
	v_dot8_i32_i4 v5, v100, v73, 0
	s_nop 1
	v_dot8_i32_i4 v9, v100, v75, 0
	v_dot8_i32_i4 v5, v101, v77, v5
	v_dot8_i32_i4 v9, v101, v108, v9
	s_waitcnt vmcnt(38)
	v_dot8_i32_i4 v11, v102, v75, 0
	s_nop 0
	v_lshl_add_u32 v5, v5, 4, v9
	v_dot8_i32_i4 v9, v102, v73, 0
	v_dot8_i32_i4 v9, v103, v77, v9
	v_dot8_i32_i4 v11, v103, v108, v11
	s_waitcnt vmcnt(37)
	v_dot8_i32_i4 v13, v98, v75, 0
	s_nop 0
	v_lshl_add_u32 v9, v9, 4, v11
	v_dot8_i32_i4 v11, v98, v73, 0
	v_dot8_i32_i4 v11, v99, v77, v11
	v_dot8_i32_i4 v13, v99, v108, v13
	s_waitcnt vmcnt(36)
	v_dot8_i32_i4 v15, v104, v75, 0
	v_dot8_i32_i4 v15, v105, v108, v15
	v_lshl_add_u32 v11, v11, 4, v13
	v_dot8_i32_i4 v13, v104, v73, 0
	v_dot8_i32_i4 v13, v105, v77, v13
	s_nop 1
	s_nop 0
	v_lshl_add_u32 v13, v13, 4, v15
	s_nop 0
	s_waitcnt vmcnt(35)
	v_dot8_i32_i4 v15, v94, v73, 0
	s_nop 1
	v_dot8_i32_i4 v17, v94, v75, 0
	v_dot8_i32_i4 v15, v95, v77, v15
	v_dot8_i32_i4 v17, v95, v108, v17
	s_waitcnt vmcnt(34)
	v_dot8_i32_i4 v19, v86, v75, 0
	s_nop 0
	v_lshl_add_u32 v15, v15, 4, v17
	v_dot8_i32_i4 v17, v86, v73, 0
	v_dot8_i32_i4 v17, v87, v77, v17
	v_dot8_i32_i4 v19, v87, v108, v19
	s_waitcnt vmcnt(33)
	v_dot8_i32_i4 v21, v84, v75, 0
	v_dot8_i32_i4 v21, v85, v108, v21
	v_lshl_add_u32 v17, v17, 4, v19
	v_dot8_i32_i4 v19, v84, v73, 0
	v_dot8_i32_i4 v19, v85, v77, v19
	s_nop 1
	s_nop 0
	v_lshl_add_u32 v19, v19, 4, v21
	s_waitcnt vmcnt(32)
	v_dot8_i32_i4 v21, v90, v73, 0
	v_dot8_i32_i4 v84, v90, v75, 0
	v_dot8_i32_i4 v21, v91, v77, v21
	v_dot8_i32_i4 v84, v91, v108, v84
	v_readlane_b32 s0, v18, 0
	s_lshl_b32 s0, s0, 9
	s_nop 0
	v_lshl_add_u32 v21, v21, 4, v84
	s_waitcnt vmcnt(31)
	v_dot8_i32_i4 v84, v78, v73, 0
	v_dot8_i32_i4 v85, v78, v75, 0
	buffer_load_dwordx2 v[96:97], v192, s[52:55], s0 offen
	v_readlane_b32 s0, v18, 1
	s_lshl_b32 s0, s0, 9
	v_dot8_i32_i4 v84, v79, v77, v84
	v_dot8_i32_i4 v85, v79, v108, v85
	buffer_load_dwordx2 v[88:89], v192, s[52:55], s0 offen
	v_readlane_b32 s0, v18, 2
	s_lshl_b32 s0, s0, 9
	v_lshl_add_u32 v78, v84, 4, v85
	buffer_load_dwordx2 v[82:83], v192, s[52:55], s0 offen
	v_readlane_b32 s0, v18, 3
	s_lshl_b32 s0, s0, 9
	s_waitcnt vmcnt(33)
	v_dot8_i32_i4 v79, v50, v73, 0
	s_nop 0
	buffer_load_dwordx2 v[92:93], v192, s[52:55], s0 offen
	v_readlane_b32 s0, v18, 4
	s_lshl_b32 s0, s0, 9
	v_dot8_i32_i4 v84, v50, v75, 0
	v_dot8_i32_i4 v79, v51, v77, v79
	v_dot8_i32_i4 v84, v51, v108, v84
	buffer_load_dwordx2 v[80:81], v192, s[52:55], s0 offen
	v_readlane_b32 s0, v18, 5
	s_lshl_b32 s0, s0, 9
	v_lshl_add_u32 v50, v79, 4, v84
	s_waitcnt vmcnt(34)
	v_dot8_i32_i4 v51, v48, v73, 0
	v_dot8_i32_i4 v79, v48, v75, 0
	buffer_load_dwordx2 v[52:53], v192, s[52:55], s0 offen
	v_readlane_b32 s0, v18, 6
	s_lshl_b32 s0, s0, 9
	v_dot8_i32_i4 v51, v49, v77, v51
	v_dot8_i32_i4 v79, v49, v108, v79
	s_waitcnt vmcnt(34)
	v_dot8_i32_i4 v49, v54, v73, 0
	buffer_load_dwordx2 v[46:47], v192, s[52:55], s0 offen
	v_readlane_b32 s0, v18, 7
	s_lshl_b32 s0, s0, 9
	v_lshl_add_u32 v48, v51, 4, v79
	v_dot8_i32_i4 v51, v54, v75, 0
	v_dot8_i32_i4 v49, v55, v77, v49
	buffer_load_dwordx2 v[56:57], v192, s[52:55], s0 offen
	v_readlane_b32 s0, v18, 8
	s_lshl_b32 s0, s0, 9
	v_dot8_i32_i4 v51, v55, v108, v51
	s_waitcnt vmcnt(35)
	v_dot8_i32_i4 v54, v42, v75, 0
	v_dot8_i32_i4 v54, v43, v108, v54
	buffer_load_dwordx2 v[44:45], v192, s[52:55], s0 offen
	v_readlane_b32 s0, v18, 9
	s_lshl_b32 s0, s0, 9
	v_lshl_add_u32 v49, v49, 4, v51
	v_dot8_i32_i4 v51, v42, v73, 0
	v_dot8_i32_i4 v51, v43, v77, v51
	buffer_load_dwordx2 v[36:37], v192, s[52:55], s0 offen
	v_readlane_b32 s0, v18, 10
	s_lshl_b32 s0, s0, 9
	v_lshl_add_u32 v42, v51, 4, v54
	s_waitcnt vmcnt(36)
	v_dot8_i32_i4 v43, v34, v73, 0
	buffer_load_dwordx2 v[30:31], v192, s[52:55], s0 offen
	v_readlane_b32 s0, v18, 11
	s_lshl_b32 s0, s0, 9
	v_dot8_i32_i4 v51, v34, v75, 0
	v_dot8_i32_i4 v43, v35, v77, v43
	v_dot8_i32_i4 v51, v35, v108, v51
	buffer_load_dwordx2 v[40:41], v192, s[52:55], s0 offen
	v_readlane_b32 s0, v18, 12
	s_lshl_b32 s0, s0, 9
	v_lshl_add_u32 v34, v43, 4, v51
	s_waitcnt vmcnt(37)
	v_dot8_i32_i4 v35, v32, v73, 0
	v_dot8_i32_i4 v43, v32, v75, 0
	buffer_load_dwordx2 v[28:29], v192, s[52:55], s0 offen
	v_readlane_b32 s0, v18, 13
	s_lshl_b32 s0, s0, 9
	v_dot8_i32_i4 v35, v33, v77, v35
	v_dot8_i32_i4 v43, v33, v108, v43
	s_waitcnt vmcnt(37)
	v_dot8_i32_i4 v33, v38, v73, 0
	buffer_load_dwordx2 v[24:25], v192, s[52:55], s0 offen
	v_readlane_b32 s0, v18, 14
	s_lshl_b32 s0, s0, 9
	v_lshl_add_u32 v32, v35, 4, v43
	v_dot8_i32_i4 v35, v38, v75, 0
	v_dot8_i32_i4 v33, v39, v77, v33
	buffer_load_dwordx2 v[22:23], v192, s[52:55], s0 offen
	v_readlane_b32 s0, v18, 15
	s_lshl_b32 s0, s0, 9
	v_dot8_i32_i4 v35, v39, v108, v35
	buffer_load_dwordx2 v[26:27], v192, s[52:55], s0 offen
	s_nop 1
	v_lshl_add_u32 v33, v33, 4, v35
	s_nop 0
	v_cndmask_b32_e64 v35, v9, v5, s[40:41]
	v_cndmask_b32_e64 v5, v5, v9, s[40:41]
	v_cndmask_b32_e64 v9, v13, v11, s[40:41]
	v_cndmask_b32_e64 v11, v11, v13, s[40:41]
	s_nop 1
	v_mov_b32_dpp v11, v11 quad_perm:[1,0,3,2] row_mask:0xf bank_mask:0xf
	v_cndmask_b32_e64 v13, v15, v17, s[40:41]
	s_nop 1
	v_mov_b32_dpp v13, v13 quad_perm:[1,0,3,2] row_mask:0xf bank_mask:0xf
	s_waitcnt lgkmcnt(0)
	v_add_u32_e32 v9, v9, v11
	v_cndmask_b32_e64 v11, v17, v15, s[40:41]
	v_cndmask_b32_e64 v15, v19, v21, s[40:41]
	s_nop 1
	v_mov_b32_dpp v15, v15 quad_perm:[1,0,3,2] row_mask:0xf bank_mask:0xf
	v_cndmask_b32_e64 v17, v78, v50, s[40:41]
	s_waitcnt lgkmcnt(0)
	v_add_u32_e32 v11, v11, v13
	v_cndmask_b32_e64 v13, v21, v19, s[40:41]
	s_nop 1
	v_mov_b32_dpp v17, v17 quad_perm:[1,0,3,2] row_mask:0xf bank_mask:0xf
	v_cndmask_b32_e64 v19, v48, v49, s[40:41]
	s_nop 1
	v_mov_b32_dpp v19, v19 quad_perm:[1,0,3,2] row_mask:0xf bank_mask:0xf
	v_cndmask_b32_e64 v21, v42, v34, s[40:41]
	s_nop 1
	v_mov_b32_dpp v21, v21 quad_perm:[1,0,3,2] row_mask:0xf bank_mask:0xf
	s_waitcnt lgkmcnt(0)
	v_add_u32_e32 v13, v13, v15
	v_cndmask_b32_e64 v15, v50, v78, s[40:41]
	s_waitcnt lgkmcnt(0)
	v_add_u32_e32 v15, v15, v17
	v_cndmask_b32_e64 v17, v49, v48, s[40:41]
	s_waitcnt lgkmcnt(0)
	v_add_u32_e32 v17, v17, v19
	v_cndmask_b32_e64 v19, v34, v42, s[40:41]
	s_nop 1
	v_mov_b32_dpp v5, v5 quad_perm:[1,0,3,2] row_mask:0xf bank_mask:0xf
	s_waitcnt lgkmcnt(0)
	v_add_u32_e32 v19, v19, v21
	v_cndmask_b32_e64 v21, v33, v32, s[40:41]
	v_cndmask_b32_e64 v32, v32, v33, s[40:41]
	s_nop 1
	v_mov_b32_dpp v32, v32 quad_perm:[1,0,3,2] row_mask:0xf bank_mask:0xf
	s_waitcnt lgkmcnt(0)
	v_add_u32_e32 v5, v35, v5
	s_waitcnt lgkmcnt(0)
	v_add_u32_e32 v21, v21, v32
	v_cndmask_b32_e64 v32, v9, v5, s[42:43]
	v_cndmask_b32_e64 v5, v5, v9, s[42:43]
	v_cndmask_b32_e64 v9, v13, v11, s[42:43]
	v_cndmask_b32_e64 v11, v11, v13, s[42:43]
	s_nop 1
	v_mov_b32_dpp v11, v11 quad_perm:[2,3,0,1] row_mask:0xf bank_mask:0xf
	v_cndmask_b32_e64 v13, v15, v17, s[42:43]
	s_nop 1
	v_mov_b32_dpp v13, v13 quad_perm:[2,3,0,1] row_mask:0xf bank_mask:0xf
	s_nop 1
	v_mov_b32_dpp v5, v5 quad_perm:[2,3,0,1] row_mask:0xf bank_mask:0xf
	s_waitcnt lgkmcnt(0)
	v_add_u32_e32 v9, v9, v11
	v_cndmask_b32_e64 v11, v17, v15, s[42:43]
	v_cndmask_b32_e64 v15, v19, v21, s[42:43]
	s_nop 1
	v_mov_b32_dpp v15, v15 quad_perm:[2,3,0,1] row_mask:0xf bank_mask:0xf
	s_waitcnt lgkmcnt(0)
	v_add_u32_e32 v11, v11, v13
	v_cndmask_b32_e64 v13, v21, v19, s[42:43]
	s_waitcnt lgkmcnt(0)
	v_add_u32_e32 v5, v32, v5
	s_waitcnt lgkmcnt(0)
	v_add_u32_e32 v13, v13, v15
	v_cndmask_b32_e64 v15, v9, v5, s[44:45]
	v_cndmask_b32_e64 v5, v5, v9, s[44:45]
	v_cndmask_b32_e64 v9, v13, v11, s[44:45]
	v_cndmask_b32_e64 v11, v11, v13, s[44:45]
	s_nop 1
	v_mov_b32_dpp v5, v5 row_half_mirror row_mask:0xf bank_mask:0xf
	s_nop 1
	v_mov_b32_dpp v5, v5 quad_perm:[3,2,1,0] row_mask:0xf bank_mask:0xf
	s_nop 1
	v_mov_b32_dpp v11, v11 row_half_mirror row_mask:0xf bank_mask:0xf
	s_nop 1
	v_mov_b32_dpp v11, v11 quad_perm:[3,2,1,0] row_mask:0xf bank_mask:0xf
	s_waitcnt lgkmcnt(0)
	v_add_u32_e32 v5, v15, v5
	s_waitcnt lgkmcnt(0)
	v_add_u32_e32 v9, v9, v11
	v_cndmask_b32_e64 v11, v9, v5, s[46:47]
	v_cndmask_b32_e64 v5, v5, v9, s[46:47]
	s_nop 1
	v_mov_b32_dpp v5, v5 row_ror:8 row_mask:0xf bank_mask:0xf
	s_waitcnt lgkmcnt(0)
	v_add_u32_e32 v5, v11, v5
	ds_swizzle_b32 v9, v5 offset:swizzle(SWAP,16)
	s_waitcnt lgkmcnt(0)
	v_add_u32_e32 v5, v5, v9
	ds_bpermute_b32 v9, v0, v5
	s_and_saveexec_b64 s[0:1], s[48:49]
	s_cbranch_execz .LBB0_541
	v_ashrrev_i32_e32 v21, 31, v20
	v_lshlrev_b64 v[20:21], 2, v[20:21]
	v_lshl_add_u64 v[32:33], s[8:9], 0, v[20:21]
	s_waitcnt vmcnt(39)
	v_mov_b32_e32 v11, v128
	v_lshl_add_u64 v[20:21], s[10:11], 0, v[20:21]
	s_waitcnt vmcnt(37)
	v_mov_b32_e32 v13, v144
	v_mov_b32_e32 v15, v136
	s_waitcnt lgkmcnt(0)
	v_add_u32_e32 v5, v5, v9
	v_cvt_f32_i32_e32 v5, v5
	v_mul_f32_e32 v5, v5, v11
	v_mul_f32_e32 v5, v3, v5
	v_mul_f32_e32 v11, 0x3d372713, v5
	v_mul_f32_e32 v11, v5, v11
	v_mul_f32_e32 v9, 0.5, v5
	v_fmac_f32_e32 v5, v5, v11
	v_mul_f32_e32 v5, 0x3f4c422a, v5
	v_add_f32_e32 v5, v5, v5
	v_mul_f32_e32 v5, 0x3fb8aa3b, v5
	v_exp_f32_e32 v5, v5
	s_nop 0
	v_add_f32_e32 v5, 1.0, v5
	v_rcp_f32_e32 v5, v5
	s_nop 0
	v_fma_f32 v5, v5, -2.0, 1.0
	v_add_f32_e32 v5, 1.0, v5
	v_mul_f32_e32 v5, v9, v5
	v_mul_f32_e32 v5, v13, v5
	v_mul_f32_e32 v5, v15, v5
	ds_write_b32 v109, v5
.LBB0_541:
	s_or_b64 exec, exec, s[0:1]
	v_readlane_b32 s0, v16, 0
	s_lshl_b32 s0, s0, 9
	s_waitcnt lgkmcnt(0)
	s_waitcnt vmcnt(15)
	v_dot8_i32_i4 v5, v96, v73, 0
	v_dot8_i32_i4 v9, v96, v75, 0
	buffer_load_dwordx2 v[102:103], v192, s[52:55], s0 offen
	v_readlane_b32 s0, v16, 1
	s_lshl_b32 s0, s0, 9
	v_dot8_i32_i4 v5, v97, v77, v5
	v_dot8_i32_i4 v9, v97, v108, v9
	s_waitcnt vmcnt(15)
	v_dot8_i32_i4 v11, v88, v75, 0
	buffer_load_dwordx2 v[98:99], v192, s[52:55], s0 offen
	v_readlane_b32 s0, v16, 2
	s_lshl_b32 s0, s0, 9
	v_lshl_add_u32 v5, v5, 4, v9
	v_dot8_i32_i4 v9, v88, v73, 0
	v_dot8_i32_i4 v9, v89, v77, v9
	buffer_load_dwordx2 v[94:95], v192, s[52:55], s0 offen
	v_readlane_b32 s0, v16, 3
	s_lshl_b32 s0, s0, 9
	v_dot8_i32_i4 v11, v89, v108, v11
	s_waitcnt vmcnt(16)
	v_dot8_i32_i4 v13, v82, v75, 0
	v_dot8_i32_i4 v13, v83, v108, v13
	buffer_load_dwordx2 v[100:101], v192, s[52:55], s0 offen
	v_readlane_b32 s0, v16, 4
	s_lshl_b32 s0, s0, 9
	v_lshl_add_u32 v9, v9, 4, v11
	v_dot8_i32_i4 v11, v82, v73, 0
	v_dot8_i32_i4 v11, v83, v77, v11
	buffer_load_dwordx2 v[90:91], v192, s[52:55], s0 offen
	v_readlane_b32 s0, v16, 5
	s_lshl_b32 s0, s0, 9
	v_lshl_add_u32 v11, v11, 4, v13
	s_waitcnt vmcnt(17)
	v_dot8_i32_i4 v13, v92, v73, 0
	buffer_load_dwordx2 v[84:85], v192, s[52:55], s0 offen
	v_readlane_b32 s0, v16, 6
	s_lshl_b32 s0, s0, 9
	v_dot8_i32_i4 v15, v92, v75, 0
	v_dot8_i32_i4 v13, v93, v77, v13
	v_dot8_i32_i4 v15, v93, v108, v15
	buffer_load_dwordx2 v[78:79], v192, s[52:55], s0 offen
	v_readlane_b32 s0, v16, 7
	s_lshl_b32 s0, s0, 9
	v_lshl_add_u32 v13, v13, 4, v15
	s_waitcnt vmcnt(18)
	v_dot8_i32_i4 v15, v80, v73, 0
	v_dot8_i32_i4 v17, v80, v75, 0
	buffer_load_dwordx2 v[86:87], v192, s[52:55], s0 offen
	v_readlane_b32 s0, v16, 8
	s_lshl_b32 s0, s0, 9
	v_dot8_i32_i4 v15, v81, v77, v15
	v_dot8_i32_i4 v17, v81, v108, v17
	s_waitcnt vmcnt(18)
	v_dot8_i32_i4 v19, v52, v75, 0
	buffer_load_dwordx2 v[54:55], v192, s[52:55], s0 offen
	v_readlane_b32 s0, v16, 9
	s_lshl_b32 s0, s0, 9
	v_lshl_add_u32 v15, v15, 4, v17
	v_dot8_i32_i4 v17, v52, v73, 0
	v_dot8_i32_i4 v17, v53, v77, v17
	buffer_load_dwordx2 v[48:49], v192, s[52:55], s0 offen
	v_readlane_b32 s0, v16, 10
	s_lshl_b32 s0, s0, 9
	v_dot8_i32_i4 v19, v53, v108, v19
	s_waitcnt vmcnt(19)
	v_dot8_i32_i4 v52, v46, v75, 0
	v_dot8_i32_i4 v52, v47, v108, v52
	buffer_load_dwordx2 v[42:43], v192, s[52:55], s0 offen
	v_readlane_b32 s0, v16, 11
	s_lshl_b32 s0, s0, 9
	v_lshl_add_u32 v17, v17, 4, v19
	v_dot8_i32_i4 v19, v46, v73, 0
	v_dot8_i32_i4 v19, v47, v77, v19
	buffer_load_dwordx2 v[50:51], v192, s[52:55], s0 offen
	v_readlane_b32 s0, v16, 12
	s_lshl_b32 s0, s0, 9
	s_waitcnt vmcnt(20)
	v_dot8_i32_i4 v46, v56, v73, 0
	v_dot8_i32_i4 v47, v56, v75, 0
	buffer_load_dwordx2 v[38:39], v192, s[52:55], s0 offen
	v_readlane_b32 s0, v16, 13
	s_lshl_b32 s0, s0, 9
	v_dot8_i32_i4 v46, v57, v77, v46
	v_dot8_i32_i4 v47, v57, v108, v47
	v_lshl_add_u32 v19, v19, 4, v52
	buffer_load_dwordx2 v[32:33], v192, s[52:55], s0 offen
	v_readlane_b32 s0, v16, 14
	s_lshl_b32 s0, s0, 9
	v_lshl_add_u32 v46, v46, 4, v47
	s_waitcnt vmcnt(21)
	v_dot8_i32_i4 v47, v44, v73, 0
	v_dot8_i32_i4 v52, v44, v75, 0
	buffer_load_dwordx2 v[20:21], v192, s[52:55], s0 offen
	v_readlane_b32 s0, v16, 15
	s_lshl_b32 s0, s0, 9
	v_dot8_i32_i4 v47, v45, v77, v47
	v_dot8_i32_i4 v52, v45, v108, v52
	s_waitcnt vmcnt(21)
	v_dot8_i32_i4 v45, v36, v73, 0
	buffer_load_dwordx2 v[34:35], v192, s[52:55], s0 offen
	v_lshl_add_u32 v44, v47, 4, v52
	v_dot8_i32_i4 v47, v36, v75, 0
	v_dot8_i32_i4 v45, v37, v77, v45
	v_dot8_i32_i4 v47, v37, v108, v47
	s_waitcnt vmcnt(21)
	v_dot8_i32_i4 v37, v30, v73, 0
	v_dot8_i32_i4 v37, v31, v77, v37
	v_lshl_add_u32 v36, v45, 4, v47
	v_dot8_i32_i4 v45, v30, v75, 0
	v_dot8_i32_i4 v45, v31, v108, v45
	s_waitcnt vmcnt(20)
	v_dot8_i32_i4 v31, v40, v73, 0
	v_dot8_i32_i4 v31, v41, v77, v31
	v_lshl_add_u32 v30, v37, 4, v45
	v_dot8_i32_i4 v37, v40, v75, 0
	v_dot8_i32_i4 v37, v41, v108, v37
	s_waitcnt vmcnt(19)
	v_dot8_i32_i4 v40, v28, v75, 0
	v_dot8_i32_i4 v40, v29, v108, v40
	v_lshl_add_u32 v31, v31, 4, v37
	v_dot8_i32_i4 v37, v28, v73, 0
	v_dot8_i32_i4 v37, v29, v77, v37
	s_waitcnt vmcnt(18)
	v_dot8_i32_i4 v29, v24, v73, 0
	v_dot8_i32_i4 v29, v25, v77, v29
	v_lshl_add_u32 v28, v37, 4, v40
	v_dot8_i32_i4 v37, v24, v75, 0
	v_dot8_i32_i4 v37, v25, v108, v37
	s_waitcnt vmcnt(17)
	v_dot8_i32_i4 v25, v22, v73, 0
	s_nop 0
	v_lshl_add_u32 v24, v29, 4, v37
	v_dot8_i32_i4 v29, v22, v75, 0
	v_dot8_i32_i4 v25, v23, v77, v25
	v_dot8_i32_i4 v29, v23, v108, v29
	s_nop 0
	s_nop 0
	s_nop 0
	v_lshl_add_u32 v22, v25, 4, v29
	s_waitcnt vmcnt(16)
	v_dot8_i32_i4 v23, v26, v73, 0
	v_dot8_i32_i4 v25, v26, v75, 0
	v_dot8_i32_i4 v23, v27, v77, v23
	v_dot8_i32_i4 v25, v27, v108, v25
	s_nop 0
	s_nop 0
	s_nop 0
	v_lshl_add_u32 v23, v23, 4, v25
	s_nop 1
	v_cndmask_b32_e64 v25, v9, v5, s[40:41]
	v_cndmask_b32_e64 v5, v5, v9, s[40:41]
	v_cndmask_b32_e64 v9, v13, v11, s[40:41]
	v_cndmask_b32_e64 v11, v11, v13, s[40:41]
	s_nop 1
	v_mov_b32_dpp v11, v11 quad_perm:[1,0,3,2] row_mask:0xf bank_mask:0xf
	v_cndmask_b32_e64 v13, v15, v17, s[40:41]
	s_nop 1
	v_mov_b32_dpp v13, v13 quad_perm:[1,0,3,2] row_mask:0xf bank_mask:0xf
	s_waitcnt lgkmcnt(0)
	v_add_u32_e32 v9, v9, v11
	v_cndmask_b32_e64 v11, v17, v15, s[40:41]
	v_cndmask_b32_e64 v15, v19, v46, s[40:41]
	s_nop 1
	v_mov_b32_dpp v15, v15 quad_perm:[1,0,3,2] row_mask:0xf bank_mask:0xf
	v_cndmask_b32_e64 v17, v44, v36, s[40:41]
	s_waitcnt lgkmcnt(0)
	v_add_u32_e32 v11, v11, v13
	v_cndmask_b32_e64 v13, v46, v19, s[40:41]
	s_nop 1
	v_mov_b32_dpp v17, v17 quad_perm:[1,0,3,2] row_mask:0xf bank_mask:0xf
	v_cndmask_b32_e64 v19, v30, v31, s[40:41]
	s_nop 1
	v_mov_b32_dpp v19, v19 quad_perm:[1,0,3,2] row_mask:0xf bank_mask:0xf
	s_waitcnt lgkmcnt(0)
	v_add_u32_e32 v13, v13, v15
	v_cndmask_b32_e64 v15, v36, v44, s[40:41]
	s_waitcnt lgkmcnt(0)
	v_add_u32_e32 v15, v15, v17
	v_cndmask_b32_e64 v17, v31, v30, s[40:41]
	s_waitcnt lgkmcnt(0)
	v_add_u32_e32 v17, v17, v19
	v_cndmask_b32_e64 v19, v24, v28, s[40:41]
	v_cndmask_b32_e64 v24, v28, v24, s[40:41]
	s_nop 1
	v_mov_b32_dpp v5, v5 quad_perm:[1,0,3,2] row_mask:0xf bank_mask:0xf
	s_nop 1
	v_mov_b32_dpp v24, v24 quad_perm:[1,0,3,2] row_mask:0xf bank_mask:0xf
	s_waitcnt lgkmcnt(0)
	v_add_u32_e32 v5, v25, v5
	s_waitcnt lgkmcnt(0)
	v_add_u32_e32 v19, v19, v24
	v_cndmask_b32_e64 v24, v23, v22, s[40:41]
	v_cndmask_b32_e64 v22, v22, v23, s[40:41]
	s_nop 1
	v_mov_b32_dpp v22, v22 quad_perm:[1,0,3,2] row_mask:0xf bank_mask:0xf
	v_cndmask_b32_e64 v23, v9, v5, s[42:43]
	v_cndmask_b32_e64 v5, v5, v9, s[42:43]
	v_cndmask_b32_e64 v9, v13, v11, s[42:43]
	v_cndmask_b32_e64 v11, v11, v13, s[42:43]
	s_nop 1
	v_mov_b32_dpp v11, v11 quad_perm:[2,3,0,1] row_mask:0xf bank_mask:0xf
	s_waitcnt lgkmcnt(0)
	v_add_u32_e32 v22, v24, v22
	v_cndmask_b32_e64 v13, v15, v17, s[42:43]
	s_nop 1
	v_mov_b32_dpp v13, v13 quad_perm:[2,3,0,1] row_mask:0xf bank_mask:0xf
	s_nop 1
	v_mov_b32_dpp v5, v5 quad_perm:[2,3,0,1] row_mask:0xf bank_mask:0xf
	s_waitcnt lgkmcnt(0)
	v_add_u32_e32 v9, v9, v11
	v_cndmask_b32_e64 v11, v17, v15, s[42:43]
	v_cndmask_b32_e64 v15, v19, v22, s[42:43]
	s_nop 1
	v_mov_b32_dpp v15, v15 quad_perm:[2,3,0,1] row_mask:0xf bank_mask:0xf
	s_waitcnt lgkmcnt(0)
	v_add_u32_e32 v11, v11, v13
	v_cndmask_b32_e64 v13, v22, v19, s[42:43]
	s_waitcnt lgkmcnt(0)
	v_add_u32_e32 v5, v23, v5
	s_waitcnt lgkmcnt(0)
	v_add_u32_e32 v13, v13, v15
	v_cndmask_b32_e64 v15, v9, v5, s[44:45]
	v_cndmask_b32_e64 v5, v5, v9, s[44:45]
	v_cndmask_b32_e64 v9, v13, v11, s[44:45]
	v_cndmask_b32_e64 v11, v11, v13, s[44:45]
	s_nop 1
	v_mov_b32_dpp v5, v5 row_half_mirror row_mask:0xf bank_mask:0xf
	s_nop 1
	v_mov_b32_dpp v5, v5 quad_perm:[3,2,1,0] row_mask:0xf bank_mask:0xf
	s_nop 1
	v_mov_b32_dpp v11, v11 row_half_mirror row_mask:0xf bank_mask:0xf
	s_nop 1
	v_mov_b32_dpp v11, v11 quad_perm:[3,2,1,0] row_mask:0xf bank_mask:0xf
	s_waitcnt lgkmcnt(0)
	v_add_u32_e32 v5, v15, v5
	s_waitcnt lgkmcnt(0)
	v_add_u32_e32 v9, v9, v11
	v_cndmask_b32_e64 v11, v9, v5, s[46:47]
	v_cndmask_b32_e64 v5, v5, v9, s[46:47]
	s_nop 1
	v_mov_b32_dpp v5, v5 row_ror:8 row_mask:0xf bank_mask:0xf
	s_waitcnt lgkmcnt(0)
	v_add_u32_e32 v5, v11, v5
	ds_swizzle_b32 v9, v5 offset:swizzle(SWAP,16)
	s_waitcnt lgkmcnt(0)
	v_add_u32_e32 v5, v5, v9
	ds_bpermute_b32 v9, v0, v5
	s_and_saveexec_b64 s[0:1], s[48:49]
	s_cbranch_execz .LBB0_543
	v_ashrrev_i32_e32 v19, 31, v18
	v_lshlrev_b64 v[18:19], 2, v[18:19]
	v_lshl_add_u64 v[22:23], s[8:9], 0, v[18:19]
	v_mov_b32_e32 v11, v129
	v_lshl_add_u64 v[18:19], s[10:11], 0, v[18:19]
	v_mov_b32_e32 v13, v145
	v_mov_b32_e32 v15, v137
	s_waitcnt lgkmcnt(0)
	v_add_u32_e32 v5, v5, v9
	v_cvt_f32_i32_e32 v5, v5
	v_mul_f32_e32 v5, v5, v11
	v_mul_f32_e32 v5, v3, v5
	v_mul_f32_e32 v11, 0x3d372713, v5
	v_mul_f32_e32 v11, v5, v11
	v_mul_f32_e32 v9, 0.5, v5
	v_fmac_f32_e32 v5, v5, v11
	v_mul_f32_e32 v5, 0x3f4c422a, v5
	v_add_f32_e32 v5, v5, v5
	v_mul_f32_e32 v5, 0x3fb8aa3b, v5
	v_exp_f32_e32 v5, v5
	s_nop 0
	v_add_f32_e32 v5, 1.0, v5
	v_rcp_f32_e32 v5, v5
	s_nop 0
	v_fma_f32 v5, v5, -2.0, 1.0
	v_add_f32_e32 v5, 1.0, v5
	v_mul_f32_e32 v5, v9, v5
	v_mul_f32_e32 v5, v13, v5
	v_mul_f32_e32 v5, v15, v5
	ds_write_b32 v109, v5 offset:64
.LBB0_543:
	s_or_b64 exec, exec, s[0:1]
	v_readlane_b32 s0, v14, 0
	s_lshl_b32 s0, s0, 9
	s_waitcnt lgkmcnt(0)
	s_waitcnt vmcnt(15)
	v_dot8_i32_i4 v5, v102, v73, 0
	v_dot8_i32_i4 v9, v102, v75, 0
	buffer_load_dwordx2 v[96:97], v192, s[52:55], s0 offen
	v_readlane_b32 s0, v14, 1
	s_lshl_b32 s0, s0, 9
	v_dot8_i32_i4 v5, v103, v77, v5
	v_dot8_i32_i4 v9, v103, v108, v9
	s_waitcnt vmcnt(15)
	v_dot8_i32_i4 v11, v98, v75, 0
	buffer_load_dwordx2 v[104:105], v192, s[52:55], s0 offen
	v_readlane_b32 s0, v14, 2
	s_lshl_b32 s0, s0, 9
	v_lshl_add_u32 v5, v5, 4, v9
	v_dot8_i32_i4 v9, v98, v73, 0
	v_dot8_i32_i4 v9, v99, v77, v9
	buffer_load_dwordx2 v[92:93], v192, s[52:55], s0 offen
	v_readlane_b32 s0, v14, 3
	s_lshl_b32 s0, s0, 9
	v_dot8_i32_i4 v11, v99, v108, v11
	s_waitcnt vmcnt(16)
	v_dot8_i32_i4 v13, v94, v75, 0
	v_dot8_i32_i4 v13, v95, v108, v13
	buffer_load_dwordx2 v[106:107], v192, s[52:55], s0 offen
	v_readlane_b32 s0, v14, 4
	s_lshl_b32 s0, s0, 9
	v_lshl_add_u32 v9, v9, 4, v11
	v_dot8_i32_i4 v11, v94, v73, 0
	v_dot8_i32_i4 v11, v95, v77, v11
	buffer_load_dwordx2 v[88:89], v192, s[52:55], s0 offen
	v_readlane_b32 s0, v14, 5
	s_lshl_b32 s0, s0, 9
	v_lshl_add_u32 v11, v11, 4, v13
	s_waitcnt vmcnt(17)
	v_dot8_i32_i4 v13, v100, v73, 0
	buffer_load_dwordx2 v[80:81], v192, s[52:55], s0 offen
	v_readlane_b32 s0, v14, 6
	s_lshl_b32 s0, s0, 9
	v_dot8_i32_i4 v15, v100, v75, 0
	v_dot8_i32_i4 v13, v101, v77, v13
	v_dot8_i32_i4 v15, v101, v108, v15
	buffer_load_dwordx2 v[56:57], v192, s[52:55], s0 offen
	v_readlane_b32 s0, v14, 7
	s_lshl_b32 s0, s0, 9
	v_lshl_add_u32 v13, v13, 4, v15
	s_waitcnt vmcnt(18)
	v_dot8_i32_i4 v15, v90, v73, 0
	v_dot8_i32_i4 v17, v90, v75, 0
	buffer_load_dwordx2 v[82:83], v192, s[52:55], s0 offen
	v_readlane_b32 s0, v14, 8
	s_lshl_b32 s0, s0, 9
	v_dot8_i32_i4 v15, v91, v77, v15
	v_dot8_i32_i4 v17, v91, v108, v17
	s_waitcnt vmcnt(18)
	v_dot8_i32_i4 v22, v84, v75, 0
	buffer_load_dwordx2 v[52:53], v192, s[52:55], s0 offen
	v_readlane_b32 s0, v14, 9
	s_lshl_b32 s0, s0, 9
	v_lshl_add_u32 v15, v15, 4, v17
	v_dot8_i32_i4 v17, v84, v73, 0
	v_dot8_i32_i4 v17, v85, v77, v17
	buffer_load_dwordx2 v[44:45], v192, s[52:55], s0 offen
	v_readlane_b32 s0, v14, 10
	s_lshl_b32 s0, s0, 9
	v_dot8_i32_i4 v22, v85, v108, v22
	s_waitcnt vmcnt(19)
	v_dot8_i32_i4 v23, v78, v75, 0
	v_dot8_i32_i4 v23, v79, v108, v23
	buffer_load_dwordx2 v[40:41], v192, s[52:55], s0 offen
	v_readlane_b32 s0, v14, 11
	s_lshl_b32 s0, s0, 9
	v_lshl_add_u32 v17, v17, 4, v22
	v_dot8_i32_i4 v22, v78, v73, 0
	v_dot8_i32_i4 v22, v79, v77, v22
	buffer_load_dwordx2 v[46:47], v192, s[52:55], s0 offen
	v_readlane_b32 s0, v14, 12
	s_lshl_b32 s0, s0, 9
	v_lshl_add_u32 v22, v22, 4, v23
	s_waitcnt vmcnt(20)
	v_dot8_i32_i4 v23, v86, v73, 0
	buffer_load_dwordx2 v[36:37], v192, s[52:55], s0 offen
	v_readlane_b32 s0, v14, 13
	s_lshl_b32 s0, s0, 9
	v_dot8_i32_i4 v26, v86, v75, 0
	v_dot8_i32_i4 v23, v87, v77, v23
	v_dot8_i32_i4 v26, v87, v108, v26
	buffer_load_dwordx2 v[24:25], v192, s[52:55], s0 offen
	v_readlane_b32 s0, v14, 14
	s_lshl_b32 s0, s0, 9
	v_lshl_add_u32 v23, v23, 4, v26
	s_waitcnt vmcnt(21)
	v_dot8_i32_i4 v26, v54, v73, 0
	v_dot8_i32_i4 v27, v54, v75, 0
	buffer_load_dwordx2 v[18:19], v192, s[52:55], s0 offen
	v_readlane_b32 s0, v14, 15
	s_lshl_b32 s0, s0, 9
	v_dot8_i32_i4 v26, v55, v77, v26
	v_dot8_i32_i4 v27, v55, v108, v27
	s_waitcnt vmcnt(21)
	v_dot8_i32_i4 v30, v48, v75, 0
	buffer_load_dwordx2 v[28:29], v192, s[52:55], s0 offen
	v_lshl_add_u32 v26, v26, 4, v27
	v_dot8_i32_i4 v27, v48, v73, 0
	v_dot8_i32_i4 v27, v49, v77, v27
	v_dot8_i32_i4 v30, v49, v108, v30
	s_waitcnt vmcnt(21)
	v_dot8_i32_i4 v31, v42, v75, 0
	v_dot8_i32_i4 v31, v43, v108, v31
	v_lshl_add_u32 v27, v27, 4, v30
	v_dot8_i32_i4 v30, v42, v73, 0
	v_dot8_i32_i4 v30, v43, v77, v30
	s_waitcnt vmcnt(20)
	v_dot8_i32_i4 v42, v50, v75, 0
	v_dot8_i32_i4 v42, v51, v108, v42
	v_lshl_add_u32 v30, v30, 4, v31
	v_dot8_i32_i4 v31, v50, v73, 0
	v_dot8_i32_i4 v31, v51, v77, v31
	s_waitcnt vmcnt(19)
	v_dot8_i32_i4 v43, v38, v75, 0
	v_dot8_i32_i4 v43, v39, v108, v43
	v_lshl_add_u32 v31, v31, 4, v42
	v_dot8_i32_i4 v42, v38, v73, 0
	v_dot8_i32_i4 v42, v39, v77, v42
	s_waitcnt vmcnt(18)
	v_dot8_i32_i4 v39, v32, v73, 0
	v_dot8_i32_i4 v39, v33, v77, v39
	v_lshl_add_u32 v38, v42, 4, v43
	v_dot8_i32_i4 v42, v32, v75, 0
	v_dot8_i32_i4 v42, v33, v108, v42
	s_waitcnt vmcnt(17)
	v_dot8_i32_i4 v33, v20, v73, 0
	s_nop 0
	v_lshl_add_u32 v32, v39, 4, v42
	v_dot8_i32_i4 v39, v20, v75, 0
	v_dot8_i32_i4 v33, v21, v77, v33
	v_dot8_i32_i4 v39, v21, v108, v39
	s_nop 0
	s_nop 0
	s_nop 0
	v_lshl_add_u32 v20, v33, 4, v39
	s_waitcnt vmcnt(16)
	v_dot8_i32_i4 v21, v34, v73, 0
	v_dot8_i32_i4 v33, v34, v75, 0
	v_dot8_i32_i4 v21, v35, v77, v21
	v_dot8_i32_i4 v33, v35, v108, v33
	s_nop 0
	s_nop 0
	s_nop 0
	v_lshl_add_u32 v21, v21, 4, v33
	s_nop 1
	v_cndmask_b32_e64 v33, v9, v5, s[40:41]
	v_cndmask_b32_e64 v5, v5, v9, s[40:41]
	v_cndmask_b32_e64 v9, v13, v11, s[40:41]
	v_cndmask_b32_e64 v11, v11, v13, s[40:41]
	s_nop 1
	v_mov_b32_dpp v11, v11 quad_perm:[1,0,3,2] row_mask:0xf bank_mask:0xf
	v_cndmask_b32_e64 v13, v15, v17, s[40:41]
	s_nop 1
	v_mov_b32_dpp v13, v13 quad_perm:[1,0,3,2] row_mask:0xf bank_mask:0xf
	s_waitcnt lgkmcnt(0)
	v_add_u32_e32 v9, v9, v11
	v_cndmask_b32_e64 v11, v17, v15, s[40:41]
	v_cndmask_b32_e64 v15, v22, v23, s[40:41]
	s_nop 1
	v_mov_b32_dpp v15, v15 quad_perm:[1,0,3,2] row_mask:0xf bank_mask:0xf
	v_cndmask_b32_e64 v17, v26, v27, s[40:41]
	s_waitcnt lgkmcnt(0)
	v_add_u32_e32 v11, v11, v13
	v_cndmask_b32_e64 v13, v23, v22, s[40:41]
	s_nop 1
	v_mov_b32_dpp v17, v17 quad_perm:[1,0,3,2] row_mask:0xf bank_mask:0xf
	v_cndmask_b32_e64 v22, v30, v31, s[40:41]
	s_nop 1
	v_mov_b32_dpp v22, v22 quad_perm:[1,0,3,2] row_mask:0xf bank_mask:0xf
	v_cndmask_b32_e64 v23, v38, v32, s[40:41]
	s_nop 1
	v_mov_b32_dpp v5, v5 quad_perm:[1,0,3,2] row_mask:0xf bank_mask:0xf
	s_nop 1
	v_mov_b32_dpp v23, v23 quad_perm:[1,0,3,2] row_mask:0xf bank_mask:0xf
	s_waitcnt lgkmcnt(0)
	v_add_u32_e32 v13, v13, v15
	v_cndmask_b32_e64 v15, v27, v26, s[40:41]
	s_waitcnt lgkmcnt(0)
	v_add_u32_e32 v15, v15, v17
	v_cndmask_b32_e64 v17, v31, v30, s[40:41]
	s_waitcnt lgkmcnt(0)
	v_add_u32_e32 v17, v17, v22
	v_cndmask_b32_e64 v22, v32, v38, s[40:41]
	s_waitcnt lgkmcnt(0)
	v_add_u32_e32 v5, v33, v5
	s_waitcnt lgkmcnt(0)
	v_add_u32_e32 v22, v22, v23
	v_cndmask_b32_e64 v23, v21, v20, s[40:41]
	v_cndmask_b32_e64 v20, v20, v21, s[40:41]
	s_nop 1
	v_mov_b32_dpp v20, v20 quad_perm:[1,0,3,2] row_mask:0xf bank_mask:0xf
	v_cndmask_b32_e64 v21, v9, v5, s[42:43]
	v_cndmask_b32_e64 v5, v5, v9, s[42:43]
	v_cndmask_b32_e64 v9, v13, v11, s[42:43]
	v_cndmask_b32_e64 v11, v11, v13, s[42:43]
	s_nop 1
	v_mov_b32_dpp v11, v11 quad_perm:[2,3,0,1] row_mask:0xf bank_mask:0xf
	s_waitcnt lgkmcnt(0)
	v_add_u32_e32 v20, v23, v20
	v_cndmask_b32_e64 v13, v15, v17, s[42:43]
	s_nop 1
	v_mov_b32_dpp v13, v13 quad_perm:[2,3,0,1] row_mask:0xf bank_mask:0xf
	s_nop 1
	v_mov_b32_dpp v5, v5 quad_perm:[2,3,0,1] row_mask:0xf bank_mask:0xf
	s_waitcnt lgkmcnt(0)
	v_add_u32_e32 v9, v9, v11
	v_cndmask_b32_e64 v11, v17, v15, s[42:43]
	v_cndmask_b32_e64 v15, v22, v20, s[42:43]
	s_nop 1
	v_mov_b32_dpp v15, v15 quad_perm:[2,3,0,1] row_mask:0xf bank_mask:0xf
	s_waitcnt lgkmcnt(0)
	v_add_u32_e32 v11, v11, v13
	v_cndmask_b32_e64 v13, v20, v22, s[42:43]
	s_waitcnt lgkmcnt(0)
	v_add_u32_e32 v5, v21, v5
	s_waitcnt lgkmcnt(0)
	v_add_u32_e32 v13, v13, v15
	v_cndmask_b32_e64 v15, v9, v5, s[44:45]
	v_cndmask_b32_e64 v5, v5, v9, s[44:45]
	v_cndmask_b32_e64 v9, v13, v11, s[44:45]
	v_cndmask_b32_e64 v11, v11, v13, s[44:45]
	s_nop 1
	v_mov_b32_dpp v5, v5 row_half_mirror row_mask:0xf bank_mask:0xf
	s_nop 1
	v_mov_b32_dpp v5, v5 quad_perm:[3,2,1,0] row_mask:0xf bank_mask:0xf
	s_nop 1
	v_mov_b32_dpp v11, v11 row_half_mirror row_mask:0xf bank_mask:0xf
	s_nop 1
	v_mov_b32_dpp v11, v11 quad_perm:[3,2,1,0] row_mask:0xf bank_mask:0xf
	s_waitcnt lgkmcnt(0)
	v_add_u32_e32 v5, v15, v5
	s_waitcnt lgkmcnt(0)
	v_add_u32_e32 v9, v9, v11
	v_cndmask_b32_e64 v11, v9, v5, s[46:47]
	v_cndmask_b32_e64 v5, v5, v9, s[46:47]
	s_nop 1
	v_mov_b32_dpp v5, v5 row_ror:8 row_mask:0xf bank_mask:0xf
	s_waitcnt lgkmcnt(0)
	v_add_u32_e32 v5, v11, v5
	ds_swizzle_b32 v9, v5 offset:swizzle(SWAP,16)
	s_waitcnt lgkmcnt(0)
	v_add_u32_e32 v5, v5, v9
	ds_bpermute_b32 v9, v0, v5
	s_and_saveexec_b64 s[0:1], s[48:49]
	s_cbranch_execz .LBB0_545
	v_ashrrev_i32_e32 v17, 31, v16
	v_lshlrev_b64 v[16:17], 2, v[16:17]
	v_lshl_add_u64 v[20:21], s[8:9], 0, v[16:17]
	v_mov_b32_e32 v11, v130
	v_lshl_add_u64 v[16:17], s[10:11], 0, v[16:17]
	v_mov_b32_e32 v13, v146
	v_mov_b32_e32 v15, v138
	s_waitcnt lgkmcnt(0)
	v_add_u32_e32 v5, v5, v9
	v_cvt_f32_i32_e32 v5, v5
	v_mul_f32_e32 v5, v5, v11
	v_mul_f32_e32 v5, v3, v5
	v_mul_f32_e32 v11, 0x3d372713, v5
	v_mul_f32_e32 v11, v5, v11
	v_mul_f32_e32 v9, 0.5, v5
	v_fmac_f32_e32 v5, v5, v11
	v_mul_f32_e32 v5, 0x3f4c422a, v5
	v_add_f32_e32 v5, v5, v5
	v_mul_f32_e32 v5, 0x3fb8aa3b, v5
	v_exp_f32_e32 v5, v5
	s_nop 0
	v_add_f32_e32 v5, 1.0, v5
	v_rcp_f32_e32 v5, v5
	s_nop 0
	v_fma_f32 v5, v5, -2.0, 1.0
	v_add_f32_e32 v5, 1.0, v5
	v_mul_f32_e32 v5, v9, v5
	v_mul_f32_e32 v5, v13, v5
	v_mul_f32_e32 v5, v15, v5
	ds_write_b32 v109, v5 offset:128
.LBB0_545:
	s_or_b64 exec, exec, s[0:1]
	v_readlane_b32 s0, v12, 0
	s_lshl_b32 s0, s0, 9
	s_waitcnt lgkmcnt(0)
	s_waitcnt vmcnt(15)
	v_dot8_i32_i4 v5, v96, v73, 0
	v_dot8_i32_i4 v9, v96, v75, 0
	buffer_load_dwordx2 v[94:95], v192, s[52:55], s0 offen
	v_readlane_b32 s0, v12, 1
	s_lshl_b32 s0, s0, 9
	v_dot8_i32_i4 v5, v97, v77, v5
	v_dot8_i32_i4 v9, v97, v108, v9
	s_waitcnt vmcnt(15)
	v_dot8_i32_i4 v11, v104, v75, 0
	buffer_load_dwordx2 v[86:87], v192, s[52:55], s0 offen
	v_readlane_b32 s0, v12, 2
	s_lshl_b32 s0, s0, 9
	v_lshl_add_u32 v5, v5, 4, v9
	v_dot8_i32_i4 v9, v104, v73, 0
	v_dot8_i32_i4 v9, v105, v77, v9
	buffer_load_dwordx2 v[84:85], v192, s[52:55], s0 offen
	v_readlane_b32 s0, v12, 3
	s_lshl_b32 s0, s0, 9
	v_dot8_i32_i4 v11, v105, v108, v11
	s_waitcnt vmcnt(16)
	v_dot8_i32_i4 v13, v92, v75, 0
	v_dot8_i32_i4 v13, v93, v108, v13
	buffer_load_dwordx2 v[90:91], v192, s[52:55], s0 offen
	v_readlane_b32 s0, v12, 4
	s_lshl_b32 s0, s0, 9
	v_lshl_add_u32 v9, v9, 4, v11
	v_dot8_i32_i4 v11, v92, v73, 0
	v_dot8_i32_i4 v11, v93, v77, v11
	buffer_load_dwordx2 v[78:79], v192, s[52:55], s0 offen
	v_readlane_b32 s0, v12, 5
	s_lshl_b32 s0, s0, 9
	v_lshl_add_u32 v11, v11, 4, v13
	s_waitcnt vmcnt(17)
	v_dot8_i32_i4 v13, v106, v73, 0
	buffer_load_dwordx2 v[50:51], v192, s[52:55], s0 offen
	v_readlane_b32 s0, v12, 6
	s_lshl_b32 s0, s0, 9
	v_dot8_i32_i4 v15, v106, v75, 0
	v_dot8_i32_i4 v13, v107, v77, v13
	v_dot8_i32_i4 v15, v107, v108, v15
	buffer_load_dwordx2 v[48:49], v192, s[52:55], s0 offen
	v_readlane_b32 s0, v12, 7
	s_lshl_b32 s0, s0, 9
	v_lshl_add_u32 v13, v13, 4, v15
	s_waitcnt vmcnt(18)
	v_dot8_i32_i4 v15, v88, v73, 0
	v_dot8_i32_i4 v32, v88, v75, 0
	buffer_load_dwordx2 v[54:55], v192, s[52:55], s0 offen
	v_readlane_b32 s0, v12, 8
	s_lshl_b32 s0, s0, 9
	v_dot8_i32_i4 v15, v89, v77, v15
	v_dot8_i32_i4 v32, v89, v108, v32
	s_waitcnt vmcnt(18)
	v_dot8_i32_i4 v33, v80, v75, 0
	buffer_load_dwordx2 v[42:43], v192, s[52:55], s0 offen
	v_readlane_b32 s0, v12, 9
	s_lshl_b32 s0, s0, 9
	v_lshl_add_u32 v15, v15, 4, v32
	v_dot8_i32_i4 v32, v80, v73, 0
	v_dot8_i32_i4 v32, v81, v77, v32
	buffer_load_dwordx2 v[34:35], v192, s[52:55], s0 offen
	v_readlane_b32 s0, v12, 10
	s_lshl_b32 s0, s0, 9
	v_dot8_i32_i4 v33, v81, v108, v33
	s_waitcnt vmcnt(19)
	v_dot8_i32_i4 v80, v56, v75, 0
	v_dot8_i32_i4 v80, v57, v108, v80
	buffer_load_dwordx2 v[30:31], v192, s[52:55], s0 offen
	v_readlane_b32 s0, v12, 11
	s_lshl_b32 s0, s0, 9
	v_lshl_add_u32 v32, v32, 4, v33
	v_dot8_i32_i4 v33, v56, v73, 0
	v_dot8_i32_i4 v33, v57, v77, v33
	buffer_load_dwordx2 v[38:39], v192, s[52:55], s0 offen
	v_readlane_b32 s0, v12, 12
	s_lshl_b32 s0, s0, 9
	s_waitcnt vmcnt(20)
	v_dot8_i32_i4 v56, v82, v73, 0
	v_dot8_i32_i4 v57, v82, v75, 0
	buffer_load_dwordx2 v[26:27], v192, s[52:55], s0 offen
	v_readlane_b32 s0, v12, 13
	s_lshl_b32 s0, s0, 9
	v_dot8_i32_i4 v56, v83, v77, v56
	v_dot8_i32_i4 v57, v83, v108, v57
	v_lshl_add_u32 v33, v33, 4, v80
	buffer_load_dwordx2 v[20:21], v192, s[52:55], s0 offen
	v_readlane_b32 s0, v12, 14
	s_lshl_b32 s0, s0, 9
	v_lshl_add_u32 v56, v56, 4, v57
	s_waitcnt vmcnt(21)
	v_dot8_i32_i4 v57, v52, v73, 0
	v_dot8_i32_i4 v80, v52, v75, 0
	buffer_load_dwordx2 v[16:17], v192, s[52:55], s0 offen
	v_readlane_b32 s0, v12, 15
	s_lshl_b32 s0, s0, 9
	v_dot8_i32_i4 v57, v53, v77, v57
	v_dot8_i32_i4 v80, v53, v108, v80
	s_waitcnt vmcnt(21)
	v_dot8_i32_i4 v53, v44, v73, 0
	buffer_load_dwordx2 v[22:23], v192, s[52:55], s0 offen
	v_lshl_add_u32 v52, v57, 4, v80
	v_dot8_i32_i4 v57, v44, v75, 0
	v_dot8_i32_i4 v53, v45, v77, v53
	v_dot8_i32_i4 v57, v45, v108, v57
	s_waitcnt vmcnt(21)
	v_dot8_i32_i4 v45, v40, v73, 0
	v_dot8_i32_i4 v45, v41, v77, v45
	v_lshl_add_u32 v44, v53, 4, v57
	v_dot8_i32_i4 v53, v40, v75, 0
	v_dot8_i32_i4 v53, v41, v108, v53
	s_waitcnt vmcnt(20)
	v_dot8_i32_i4 v41, v46, v73, 0
	v_dot8_i32_i4 v41, v47, v77, v41
	v_lshl_add_u32 v40, v45, 4, v53
	v_dot8_i32_i4 v45, v46, v75, 0
	v_dot8_i32_i4 v45, v47, v108, v45
	s_waitcnt vmcnt(19)
	v_dot8_i32_i4 v46, v36, v75, 0
	v_dot8_i32_i4 v46, v37, v108, v46
	v_lshl_add_u32 v41, v41, 4, v45
	v_dot8_i32_i4 v45, v36, v73, 0
	v_dot8_i32_i4 v45, v37, v77, v45
	s_waitcnt vmcnt(18)
	v_dot8_i32_i4 v37, v24, v73, 0
	v_dot8_i32_i4 v37, v25, v77, v37
	v_lshl_add_u32 v36, v45, 4, v46
	v_dot8_i32_i4 v45, v24, v75, 0
	v_dot8_i32_i4 v45, v25, v108, v45
	s_waitcnt vmcnt(17)
	v_dot8_i32_i4 v25, v18, v73, 0
	s_nop 0
	v_lshl_add_u32 v24, v37, 4, v45
	v_dot8_i32_i4 v37, v18, v75, 0
	v_dot8_i32_i4 v25, v19, v77, v25
	v_dot8_i32_i4 v37, v19, v108, v37
	s_waitcnt vmcnt(16)
	v_dot8_i32_i4 v19, v28, v73, 0
	v_dot8_i32_i4 v19, v29, v77, v19
	v_lshl_add_u32 v18, v25, 4, v37
	v_dot8_i32_i4 v25, v28, v75, 0
	v_dot8_i32_i4 v25, v29, v108, v25
	s_nop 1
	s_nop 0
	v_lshl_add_u32 v19, v19, 4, v25
	s_nop 0
	v_cndmask_b32_e64 v25, v9, v5, s[40:41]
	v_cndmask_b32_e64 v5, v5, v9, s[40:41]
	v_cndmask_b32_e64 v9, v13, v11, s[40:41]
	v_cndmask_b32_e64 v11, v11, v13, s[40:41]
	s_nop 1
	v_mov_b32_dpp v11, v11 quad_perm:[1,0,3,2] row_mask:0xf bank_mask:0xf
	s_nop 1
	v_mov_b32_dpp v5, v5 quad_perm:[1,0,3,2] row_mask:0xf bank_mask:0xf
	v_cndmask_b32_e64 v13, v15, v32, s[40:41]
	s_waitcnt lgkmcnt(0)
	v_add_u32_e32 v9, v9, v11
	v_cndmask_b32_e64 v11, v32, v15, s[40:41]
	s_nop 1
	v_mov_b32_dpp v13, v13 quad_perm:[1,0,3,2] row_mask:0xf bank_mask:0xf
	v_cndmask_b32_e64 v15, v33, v56, s[40:41]
	s_waitcnt lgkmcnt(0)
	v_add_u32_e32 v5, v25, v5
	s_nop 1
	v_mov_b32_dpp v15, v15 quad_perm:[1,0,3,2] row_mask:0xf bank_mask:0xf
	v_cndmask_b32_e64 v25, v52, v44, s[40:41]
	s_nop 1
	v_mov_b32_dpp v25, v25 quad_perm:[1,0,3,2] row_mask:0xf bank_mask:0xf
	v_cndmask_b32_e64 v28, v40, v41, s[40:41]
	s_nop 1
	v_mov_b32_dpp v28, v28 quad_perm:[1,0,3,2] row_mask:0xf bank_mask:0xf
	s_waitcnt lgkmcnt(0)
	v_add_u32_e32 v11, v11, v13
	v_cndmask_b32_e64 v13, v56, v33, s[40:41]
	s_waitcnt lgkmcnt(0)
	v_add_u32_e32 v13, v13, v15
	v_cndmask_b32_e64 v15, v44, v52, s[40:41]
	s_waitcnt lgkmcnt(0)
	v_add_u32_e32 v15, v15, v25
	v_cndmask_b32_e64 v25, v41, v40, s[40:41]
	s_waitcnt lgkmcnt(0)
	v_add_u32_e32 v25, v25, v28
	v_cndmask_b32_e64 v28, v24, v36, s[40:41]
	v_cndmask_b32_e64 v24, v36, v24, s[40:41]
	s_nop 1
	v_mov_b32_dpp v24, v24 quad_perm:[1,0,3,2] row_mask:0xf bank_mask:0xf
	s_waitcnt lgkmcnt(0)
	v_add_u32_e32 v24, v28, v24
	v_cndmask_b32_e64 v28, v19, v18, s[40:41]
	v_cndmask_b32_e64 v18, v18, v19, s[40:41]
	s_nop 1
	v_mov_b32_dpp v18, v18 quad_perm:[1,0,3,2] row_mask:0xf bank_mask:0xf
	v_cndmask_b32_e64 v19, v9, v5, s[42:43]
	v_cndmask_b32_e64 v5, v5, v9, s[42:43]
	v_cndmask_b32_e64 v9, v13, v11, s[42:43]
	v_cndmask_b32_e64 v11, v11, v13, s[42:43]
	s_nop 1
	v_mov_b32_dpp v11, v11 quad_perm:[2,3,0,1] row_mask:0xf bank_mask:0xf
	s_waitcnt lgkmcnt(0)
	v_add_u32_e32 v18, v28, v18
	v_cndmask_b32_e64 v13, v15, v25, s[42:43]
	s_nop 1
	v_mov_b32_dpp v13, v13 quad_perm:[2,3,0,1] row_mask:0xf bank_mask:0xf
	s_nop 1
	v_mov_b32_dpp v5, v5 quad_perm:[2,3,0,1] row_mask:0xf bank_mask:0xf
	s_waitcnt lgkmcnt(0)
	v_add_u32_e32 v9, v9, v11
	v_cndmask_b32_e64 v11, v25, v15, s[42:43]
	v_cndmask_b32_e64 v15, v24, v18, s[42:43]
	s_nop 1
	v_mov_b32_dpp v15, v15 quad_perm:[2,3,0,1] row_mask:0xf bank_mask:0xf
	s_waitcnt lgkmcnt(0)
	v_add_u32_e32 v11, v11, v13
	v_cndmask_b32_e64 v13, v18, v24, s[42:43]
	s_waitcnt lgkmcnt(0)
	v_add_u32_e32 v5, v19, v5
	s_waitcnt lgkmcnt(0)
	v_add_u32_e32 v13, v13, v15
	v_cndmask_b32_e64 v15, v9, v5, s[44:45]
	v_cndmask_b32_e64 v5, v5, v9, s[44:45]
	v_cndmask_b32_e64 v9, v13, v11, s[44:45]
	v_cndmask_b32_e64 v11, v11, v13, s[44:45]
	s_nop 1
	v_mov_b32_dpp v5, v5 row_half_mirror row_mask:0xf bank_mask:0xf
	s_nop 1
	v_mov_b32_dpp v5, v5 quad_perm:[3,2,1,0] row_mask:0xf bank_mask:0xf
	s_nop 1
	v_mov_b32_dpp v11, v11 row_half_mirror row_mask:0xf bank_mask:0xf
	s_nop 1
	v_mov_b32_dpp v11, v11 quad_perm:[3,2,1,0] row_mask:0xf bank_mask:0xf
	s_waitcnt lgkmcnt(0)
	v_add_u32_e32 v5, v15, v5
	s_waitcnt lgkmcnt(0)
	v_add_u32_e32 v9, v9, v11
	v_cndmask_b32_e64 v11, v9, v5, s[46:47]
	v_cndmask_b32_e64 v5, v5, v9, s[46:47]
	s_nop 1
	v_mov_b32_dpp v5, v5 row_ror:8 row_mask:0xf bank_mask:0xf
	s_waitcnt lgkmcnt(0)
	v_add_u32_e32 v5, v11, v5
	ds_swizzle_b32 v9, v5 offset:swizzle(SWAP,16)
	s_waitcnt lgkmcnt(0)
	v_add_u32_e32 v5, v5, v9
	ds_bpermute_b32 v9, v0, v5
	s_and_saveexec_b64 s[0:1], s[48:49]
	s_cbranch_execz .LBB0_547
	v_ashrrev_i32_e32 v15, 31, v14
	v_lshlrev_b64 v[14:15], 2, v[14:15]
	v_lshl_add_u64 v[18:19], s[8:9], 0, v[14:15]
	v_mov_b32_e32 v11, v131
	v_lshl_add_u64 v[14:15], s[10:11], 0, v[14:15]
	v_mov_b32_e32 v13, v147
	s_nop 0
	v_mov_b32_e32 v14, v139
	s_waitcnt lgkmcnt(0)
	v_add_u32_e32 v5, v5, v9
	v_cvt_f32_i32_e32 v5, v5
	v_mul_f32_e32 v5, v5, v11
	v_mul_f32_e32 v5, v3, v5
	v_mul_f32_e32 v11, 0x3d372713, v5
	v_mul_f32_e32 v11, v5, v11
	v_mul_f32_e32 v9, 0.5, v5
	v_fmac_f32_e32 v5, v5, v11
	v_mul_f32_e32 v5, 0x3f4c422a, v5
	v_add_f32_e32 v5, v5, v5
	v_mul_f32_e32 v5, 0x3fb8aa3b, v5
	v_exp_f32_e32 v5, v5
	s_nop 0
	v_add_f32_e32 v5, 1.0, v5
	v_rcp_f32_e32 v5, v5
	s_nop 0
	v_fma_f32 v5, v5, -2.0, 1.0
	v_add_f32_e32 v5, 1.0, v5
	v_mul_f32_e32 v5, v9, v5
	v_mul_f32_e32 v5, v13, v5
	v_mul_f32_e32 v5, v14, v5
	ds_write_b32 v109, v5 offset:192
.LBB0_547:
	s_or_b64 exec, exec, s[0:1]
	v_readlane_b32 s0, v10, 0
	s_lshl_b32 s0, s0, 9
	s_waitcnt lgkmcnt(0)
	s_waitcnt vmcnt(15)
	v_dot8_i32_i4 v5, v94, v73, 0
	v_dot8_i32_i4 v9, v94, v75, 0
	buffer_load_dwordx2 v[92:93], v192, s[52:55], s0 offen
	v_readlane_b32 s0, v10, 1
	s_lshl_b32 s0, s0, 9
	v_dot8_i32_i4 v5, v95, v77, v5
	v_dot8_i32_i4 v9, v95, v108, v9
	s_waitcnt vmcnt(15)
	v_dot8_i32_i4 v11, v86, v75, 0
	buffer_load_dwordx2 v[96:97], v192, s[52:55], s0 offen
	v_readlane_b32 s0, v10, 2
	s_lshl_b32 s0, s0, 9
	v_lshl_add_u32 v5, v5, 4, v9
	v_dot8_i32_i4 v9, v86, v73, 0
	v_dot8_i32_i4 v9, v87, v77, v9
	buffer_load_dwordx2 v[88:89], v192, s[52:55], s0 offen
	v_readlane_b32 s0, v10, 3
	s_lshl_b32 s0, s0, 9
	v_dot8_i32_i4 v11, v87, v108, v11
	s_waitcnt vmcnt(16)
	v_dot8_i32_i4 v13, v84, v75, 0
	v_dot8_i32_i4 v13, v85, v108, v13
	buffer_load_dwordx2 v[98:99], v192, s[52:55], s0 offen
	v_readlane_b32 s0, v10, 4
	s_lshl_b32 s0, s0, 9
	v_lshl_add_u32 v9, v9, 4, v11
	v_dot8_i32_i4 v11, v84, v73, 0
	v_dot8_i32_i4 v11, v85, v77, v11
	buffer_load_dwordx2 v[82:83], v192, s[52:55], s0 offen
	v_readlane_b32 s0, v10, 5
	s_lshl_b32 s0, s0, 9
	v_lshl_add_u32 v11, v11, 4, v13
	s_waitcnt vmcnt(17)
	v_dot8_i32_i4 v13, v90, v73, 0
	buffer_load_dwordx2 v[56:57], v192, s[52:55], s0 offen
	v_readlane_b32 s0, v10, 6
	s_lshl_b32 s0, s0, 9
	v_dot8_i32_i4 v18, v90, v75, 0
	v_dot8_i32_i4 v13, v91, v77, v13
	v_dot8_i32_i4 v18, v91, v108, v18
	buffer_load_dwordx2 v[52:53], v192, s[52:55], s0 offen
	v_readlane_b32 s0, v10, 7
	s_lshl_b32 s0, s0, 9
	v_lshl_add_u32 v13, v13, 4, v18
	s_waitcnt vmcnt(18)
	v_dot8_i32_i4 v18, v78, v73, 0
	v_dot8_i32_i4 v19, v78, v75, 0
	buffer_load_dwordx2 v[80:81], v192, s[52:55], s0 offen
	v_readlane_b32 s0, v10, 8
	s_lshl_b32 s0, s0, 9
	v_dot8_i32_i4 v18, v79, v77, v18
	v_dot8_i32_i4 v19, v79, v108, v19
	s_waitcnt vmcnt(18)
	v_dot8_i32_i4 v78, v50, v75, 0
	buffer_load_dwordx2 v[46:47], v192, s[52:55], s0 offen
	v_readlane_b32 s0, v10, 9
	s_lshl_b32 s0, s0, 9
	v_lshl_add_u32 v18, v18, 4, v19
	v_dot8_i32_i4 v19, v50, v73, 0
	v_dot8_i32_i4 v19, v51, v77, v19
	buffer_load_dwordx2 v[40:41], v192, s[52:55], s0 offen
	v_readlane_b32 s0, v10, 10
	s_lshl_b32 s0, s0, 9
	v_dot8_i32_i4 v78, v51, v108, v78
	s_waitcnt vmcnt(19)
	v_dot8_i32_i4 v50, v48, v73, 0
	buffer_load_dwordx2 v[36:37], v192, s[52:55], s0 offen
	v_readlane_b32 s0, v10, 11
	s_lshl_b32 s0, s0, 9
	v_dot8_i32_i4 v51, v48, v75, 0
	v_dot8_i32_i4 v50, v49, v77, v50
	v_dot8_i32_i4 v51, v49, v108, v51
	buffer_load_dwordx2 v[44:45], v192, s[52:55], s0 offen
	v_readlane_b32 s0, v10, 12
	s_lshl_b32 s0, s0, 9
	v_lshl_add_u32 v48, v50, 4, v51
	s_waitcnt vmcnt(20)
	v_dot8_i32_i4 v49, v54, v73, 0
	v_dot8_i32_i4 v50, v54, v75, 0
	buffer_load_dwordx2 v[32:33], v192, s[52:55], s0 offen
	v_readlane_b32 s0, v10, 13
	s_lshl_b32 s0, s0, 9
	v_dot8_i32_i4 v49, v55, v77, v49
	v_dot8_i32_i4 v50, v55, v108, v50
	s_waitcnt vmcnt(20)
	v_dot8_i32_i4 v51, v42, v75, 0
	buffer_load_dwordx2 v[24:25], v192, s[52:55], s0 offen
	v_readlane_b32 s0, v10, 14
	s_lshl_b32 s0, s0, 9
	v_lshl_add_u32 v49, v49, 4, v50
	v_dot8_i32_i4 v50, v42, v73, 0
	v_dot8_i32_i4 v50, v43, v77, v50
	buffer_load_dwordx2 v[14:15], v192, s[52:55], s0 offen
	v_readlane_b32 s0, v10, 15
	s_lshl_b32 s0, s0, 9
	v_dot8_i32_i4 v51, v43, v108, v51
	s_waitcnt vmcnt(21)
	v_dot8_i32_i4 v43, v34, v73, 0
	v_dot8_i32_i4 v43, v35, v77, v43
	buffer_load_dwordx2 v[28:29], v192, s[52:55], s0 offen
	v_lshl_add_u32 v42, v50, 4, v51
	v_dot8_i32_i4 v50, v34, v75, 0
	v_dot8_i32_i4 v50, v35, v108, v50
	s_waitcnt vmcnt(21)
	v_dot8_i32_i4 v35, v30, v73, 0
	v_dot8_i32_i4 v35, v31, v77, v35
	v_lshl_add_u32 v34, v43, 4, v50
	v_dot8_i32_i4 v43, v30, v75, 0
	v_dot8_i32_i4 v43, v31, v108, v43
	s_waitcnt vmcnt(20)
	v_dot8_i32_i4 v31, v38, v73, 0
	v_dot8_i32_i4 v31, v39, v77, v31
	v_lshl_add_u32 v30, v35, 4, v43
	v_dot8_i32_i4 v35, v38, v75, 0
	v_dot8_i32_i4 v35, v39, v108, v35
	s_waitcnt vmcnt(19)
	v_dot8_i32_i4 v38, v26, v75, 0
	v_dot8_i32_i4 v38, v27, v108, v38
	v_lshl_add_u32 v31, v31, 4, v35
	v_dot8_i32_i4 v35, v26, v73, 0
	v_dot8_i32_i4 v35, v27, v77, v35
	s_waitcnt vmcnt(18)
	v_dot8_i32_i4 v27, v20, v73, 0
	v_dot8_i32_i4 v27, v21, v77, v27
	v_lshl_add_u32 v26, v35, 4, v38
	v_dot8_i32_i4 v35, v20, v75, 0
	v_dot8_i32_i4 v35, v21, v108, v35
	s_waitcnt vmcnt(17)
	v_dot8_i32_i4 v21, v16, v73, 0
	s_nop 0
	v_lshl_add_u32 v20, v27, 4, v35
	v_dot8_i32_i4 v27, v16, v75, 0
	v_dot8_i32_i4 v21, v17, v77, v21
	v_dot8_i32_i4 v27, v17, v108, v27
	s_waitcnt vmcnt(16)
	v_dot8_i32_i4 v17, v22, v73, 0
	v_dot8_i32_i4 v17, v23, v77, v17
	v_lshl_add_u32 v16, v21, 4, v27
	v_dot8_i32_i4 v21, v22, v75, 0
	v_dot8_i32_i4 v21, v23, v108, v21
	v_lshl_add_u32 v19, v19, 4, v78
	s_nop 0
	s_nop 0
	v_lshl_add_u32 v17, v17, 4, v21
	s_nop 0
	v_cndmask_b32_e64 v21, v9, v5, s[40:41]
	v_cndmask_b32_e64 v5, v5, v9, s[40:41]
	v_cndmask_b32_e64 v9, v13, v11, s[40:41]
	v_cndmask_b32_e64 v11, v11, v13, s[40:41]
	s_nop 1
	v_mov_b32_dpp v11, v11 quad_perm:[1,0,3,2] row_mask:0xf bank_mask:0xf
	s_nop 1
	v_mov_b32_dpp v5, v5 quad_perm:[1,0,3,2] row_mask:0xf bank_mask:0xf
	v_cndmask_b32_e64 v13, v18, v19, s[40:41]
	s_waitcnt lgkmcnt(0)
	v_add_u32_e32 v9, v9, v11
	v_cndmask_b32_e64 v11, v19, v18, s[40:41]
	s_nop 1
	v_mov_b32_dpp v13, v13 quad_perm:[1,0,3,2] row_mask:0xf bank_mask:0xf
	v_cndmask_b32_e64 v18, v48, v49, s[40:41]
	s_nop 1
	v_mov_b32_dpp v18, v18 quad_perm:[1,0,3,2] row_mask:0xf bank_mask:0xf
	v_cndmask_b32_e64 v19, v42, v34, s[40:41]
	s_waitcnt lgkmcnt(0)
	v_add_u32_e32 v5, v21, v5
	s_nop 1
	v_mov_b32_dpp v19, v19 quad_perm:[1,0,3,2] row_mask:0xf bank_mask:0xf
	v_cndmask_b32_e64 v21, v30, v31, s[40:41]
	s_nop 1
	v_mov_b32_dpp v21, v21 quad_perm:[1,0,3,2] row_mask:0xf bank_mask:0xf
	s_waitcnt lgkmcnt(0)
	v_add_u32_e32 v11, v11, v13
	v_cndmask_b32_e64 v13, v49, v48, s[40:41]
	s_waitcnt lgkmcnt(0)
	v_add_u32_e32 v13, v13, v18
	v_cndmask_b32_e64 v18, v34, v42, s[40:41]
	s_waitcnt lgkmcnt(0)
	v_add_u32_e32 v18, v18, v19
	v_cndmask_b32_e64 v19, v31, v30, s[40:41]
	s_waitcnt lgkmcnt(0)
	v_add_u32_e32 v19, v19, v21
	v_cndmask_b32_e64 v21, v20, v26, s[40:41]
	v_cndmask_b32_e64 v20, v26, v20, s[40:41]
	s_nop 1
	v_mov_b32_dpp v20, v20 quad_perm:[1,0,3,2] row_mask:0xf bank_mask:0xf
	s_waitcnt lgkmcnt(0)
	v_add_u32_e32 v20, v21, v20
	v_cndmask_b32_e64 v21, v17, v16, s[40:41]
	v_cndmask_b32_e64 v16, v16, v17, s[40:41]
	v_cndmask_b32_e64 v17, v9, v5, s[42:43]
	v_cndmask_b32_e64 v5, v5, v9, s[42:43]
	v_cndmask_b32_e64 v9, v13, v11, s[42:43]
	v_cndmask_b32_e64 v11, v11, v13, s[42:43]
	s_nop 1
	v_mov_b32_dpp v16, v16 quad_perm:[1,0,3,2] row_mask:0xf bank_mask:0xf
	s_nop 1
	v_mov_b32_dpp v11, v11 quad_perm:[2,3,0,1] row_mask:0xf bank_mask:0xf
	v_cndmask_b32_e64 v13, v18, v19, s[42:43]
	s_nop 1
	v_mov_b32_dpp v13, v13 quad_perm:[2,3,0,1] row_mask:0xf bank_mask:0xf
	s_nop 1
	v_mov_b32_dpp v5, v5 quad_perm:[2,3,0,1] row_mask:0xf bank_mask:0xf
	s_waitcnt lgkmcnt(0)
	v_add_u32_e32 v16, v21, v16
	s_waitcnt lgkmcnt(0)
	v_add_u32_e32 v9, v9, v11
	v_cndmask_b32_e64 v11, v19, v18, s[42:43]
	s_waitcnt lgkmcnt(0)
	v_add_u32_e32 v11, v11, v13
	v_cndmask_b32_e64 v13, v16, v20, s[42:43]
	v_cndmask_b32_e64 v16, v20, v16, s[42:43]
	s_nop 1
	v_mov_b32_dpp v16, v16 quad_perm:[2,3,0,1] row_mask:0xf bank_mask:0xf
	s_waitcnt lgkmcnt(0)
	v_add_u32_e32 v5, v17, v5
	s_waitcnt lgkmcnt(0)
	v_add_u32_e32 v13, v13, v16
	v_cndmask_b32_e64 v16, v9, v5, s[44:45]
	v_cndmask_b32_e64 v5, v5, v9, s[44:45]
	v_cndmask_b32_e64 v9, v13, v11, s[44:45]
	v_cndmask_b32_e64 v11, v11, v13, s[44:45]
	s_nop 1
	v_mov_b32_dpp v5, v5 row_half_mirror row_mask:0xf bank_mask:0xf
	s_nop 1
	v_mov_b32_dpp v5, v5 quad_perm:[3,2,1,0] row_mask:0xf bank_mask:0xf
	s_nop 1
	v_mov_b32_dpp v11, v11 row_half_mirror row_mask:0xf bank_mask:0xf
	s_nop 1
	v_mov_b32_dpp v11, v11 quad_perm:[3,2,1,0] row_mask:0xf bank_mask:0xf
	s_waitcnt lgkmcnt(0)
	v_add_u32_e32 v5, v16, v5
	s_waitcnt lgkmcnt(0)
	v_add_u32_e32 v9, v9, v11
	v_cndmask_b32_e64 v11, v9, v5, s[46:47]
	v_cndmask_b32_e64 v5, v5, v9, s[46:47]
	s_nop 1
	v_mov_b32_dpp v5, v5 row_ror:8 row_mask:0xf bank_mask:0xf
	s_waitcnt lgkmcnt(0)
	v_add_u32_e32 v5, v11, v5
	ds_swizzle_b32 v9, v5 offset:swizzle(SWAP,16)
	s_waitcnt lgkmcnt(0)
	v_add_u32_e32 v5, v5, v9
	ds_bpermute_b32 v9, v0, v5
	s_and_saveexec_b64 s[0:1], s[48:49]
	s_cbranch_execz .LBB0_549
	v_ashrrev_i32_e32 v13, 31, v12
	v_lshlrev_b64 v[12:13], 2, v[12:13]
	v_lshl_add_u64 v[16:17], s[8:9], 0, v[12:13]
	v_mov_b32_e32 v11, v132
	v_lshl_add_u64 v[12:13], s[10:11], 0, v[12:13]
	v_mov_b32_e32 v16, v148
	s_nop 0
	v_mov_b32_e32 v12, v140
	s_waitcnt lgkmcnt(0)
	v_add_u32_e32 v5, v5, v9
	v_cvt_f32_i32_e32 v5, v5
	v_mul_f32_e32 v5, v5, v11
	v_mul_f32_e32 v5, v3, v5
	v_mul_f32_e32 v11, 0x3d372713, v5
	v_mul_f32_e32 v11, v5, v11
	v_mul_f32_e32 v9, 0.5, v5
	v_fmac_f32_e32 v5, v5, v11
	v_mul_f32_e32 v5, 0x3f4c422a, v5
	v_add_f32_e32 v5, v5, v5
	v_mul_f32_e32 v5, 0x3fb8aa3b, v5
	v_exp_f32_e32 v5, v5
	s_nop 0
	v_add_f32_e32 v5, 1.0, v5
	v_rcp_f32_e32 v5, v5
	s_nop 0
	v_fma_f32 v5, v5, -2.0, 1.0
	v_add_f32_e32 v5, 1.0, v5
	v_mul_f32_e32 v5, v9, v5
	v_mul_f32_e32 v5, v16, v5
	v_mul_f32_e32 v5, v12, v5
	ds_write_b32 v109, v5 offset:256
.LBB0_549:
	s_or_b64 exec, exec, s[0:1]
	v_readlane_b32 s0, v8, 0
	s_lshl_b32 s0, s0, 9
	s_waitcnt lgkmcnt(0)
	s_waitcnt vmcnt(15)
	v_dot8_i32_i4 v5, v92, v73, 0
	v_dot8_i32_i4 v9, v92, v75, 0
	buffer_load_dwordx2 v[86:87], v192, s[52:55], s0 offen
	v_readlane_b32 s0, v8, 1
	s_lshl_b32 s0, s0, 9
	v_dot8_i32_i4 v5, v93, v77, v5
	v_dot8_i32_i4 v9, v93, v108, v9
	s_waitcnt vmcnt(15)
	v_dot8_i32_i4 v11, v96, v75, 0
	buffer_load_dwordx2 v[78:79], v192, s[52:55], s0 offen
	v_readlane_b32 s0, v8, 2
	s_lshl_b32 s0, s0, 9
	v_lshl_add_u32 v5, v5, 4, v9
	v_dot8_i32_i4 v9, v96, v73, 0
	v_dot8_i32_i4 v9, v97, v77, v9
	buffer_load_dwordx2 v[54:55], v192, s[52:55], s0 offen
	v_readlane_b32 s0, v8, 3
	s_lshl_b32 s0, s0, 9
	v_dot8_i32_i4 v11, v97, v108, v11
	s_waitcnt vmcnt(16)
	v_dot8_i32_i4 v90, v88, v75, 0
	v_dot8_i32_i4 v90, v89, v108, v90
	buffer_load_dwordx2 v[84:85], v192, s[52:55], s0 offen
	v_readlane_b32 s0, v8, 4
	s_lshl_b32 s0, s0, 9
	v_lshl_add_u32 v9, v9, 4, v11
	v_dot8_i32_i4 v11, v88, v73, 0
	v_dot8_i32_i4 v11, v89, v77, v11
	buffer_load_dwordx2 v[50:51], v192, s[52:55], s0 offen
	v_readlane_b32 s0, v8, 5
	s_lshl_b32 s0, s0, 9
	s_waitcnt vmcnt(17)
	v_dot8_i32_i4 v88, v98, v73, 0
	v_dot8_i32_i4 v89, v98, v75, 0
	buffer_load_dwordx2 v[42:43], v192, s[52:55], s0 offen
	v_readlane_b32 s0, v8, 6
	s_lshl_b32 s0, s0, 9
	v_dot8_i32_i4 v88, v99, v77, v88
	v_dot8_i32_i4 v89, v99, v108, v89
	v_lshl_add_u32 v11, v11, 4, v90
	buffer_load_dwordx2 v[38:39], v192, s[52:55], s0 offen
	v_readlane_b32 s0, v8, 7
	s_lshl_b32 s0, s0, 9
	v_lshl_add_u32 v88, v88, 4, v89
	s_waitcnt vmcnt(18)
	v_dot8_i32_i4 v89, v82, v73, 0
	v_dot8_i32_i4 v90, v82, v75, 0
	buffer_load_dwordx2 v[48:49], v192, s[52:55], s0 offen
	v_readlane_b32 s0, v8, 8
	s_lshl_b32 s0, s0, 9
	v_dot8_i32_i4 v89, v83, v77, v89
	v_dot8_i32_i4 v90, v83, v108, v90
	s_waitcnt vmcnt(18)
	v_dot8_i32_i4 v83, v56, v73, 0
	buffer_load_dwordx2 v[34:35], v192, s[52:55], s0 offen
	v_readlane_b32 s0, v8, 9
	s_lshl_b32 s0, s0, 9
	v_lshl_add_u32 v82, v89, 4, v90
	v_dot8_i32_i4 v89, v56, v75, 0
	v_dot8_i32_i4 v83, v57, v77, v83
	buffer_load_dwordx2 v[26:27], v192, s[52:55], s0 offen
	v_readlane_b32 s0, v8, 10
	s_lshl_b32 s0, s0, 9
	v_dot8_i32_i4 v89, v57, v108, v89
	s_waitcnt vmcnt(19)
	v_dot8_i32_i4 v57, v52, v73, 0
	v_dot8_i32_i4 v57, v53, v77, v57
	buffer_load_dwordx2 v[22:23], v192, s[52:55], s0 offen
	v_readlane_b32 s0, v8, 11
	s_lshl_b32 s0, s0, 9
	v_lshl_add_u32 v56, v83, 4, v89
	v_dot8_i32_i4 v83, v52, v75, 0
	v_dot8_i32_i4 v83, v53, v108, v83
	buffer_load_dwordx2 v[30:31], v192, s[52:55], s0 offen
	v_readlane_b32 s0, v8, 12
	s_lshl_b32 s0, s0, 9
	v_lshl_add_u32 v52, v57, 4, v83
	s_waitcnt vmcnt(20)
	v_dot8_i32_i4 v53, v80, v73, 0
	buffer_load_dwordx2 v[20:21], v192, s[52:55], s0 offen
	v_readlane_b32 s0, v8, 13
	s_lshl_b32 s0, s0, 9
	v_dot8_i32_i4 v57, v80, v75, 0
	v_dot8_i32_i4 v53, v81, v77, v53
	v_dot8_i32_i4 v57, v81, v108, v57
	buffer_load_dwordx2 v[16:17], v192, s[52:55], s0 offen
	v_readlane_b32 s0, v8, 14
	s_lshl_b32 s0, s0, 9
	v_lshl_add_u32 v53, v53, 4, v57
	s_waitcnt vmcnt(21)
	v_dot8_i32_i4 v57, v46, v73, 0
	v_dot8_i32_i4 v80, v46, v75, 0
	buffer_load_dwordx2 v[12:13], v192, s[52:55], s0 offen
	v_readlane_b32 s0, v8, 15
	s_lshl_b32 s0, s0, 9
	v_dot8_i32_i4 v57, v47, v77, v57
	v_dot8_i32_i4 v80, v47, v108, v80
	s_waitcnt vmcnt(21)
	v_dot8_i32_i4 v47, v40, v73, 0
	buffer_load_dwordx2 v[18:19], v192, s[52:55], s0 offen
	v_lshl_add_u32 v46, v57, 4, v80
	v_dot8_i32_i4 v57, v40, v75, 0
	v_dot8_i32_i4 v47, v41, v77, v47
	v_dot8_i32_i4 v57, v41, v108, v57
	s_waitcnt vmcnt(21)
	v_dot8_i32_i4 v41, v36, v73, 0
	v_dot8_i32_i4 v41, v37, v77, v41
	v_lshl_add_u32 v40, v47, 4, v57
	v_dot8_i32_i4 v47, v36, v75, 0
	v_dot8_i32_i4 v47, v37, v108, v47
	s_waitcnt vmcnt(20)
	v_dot8_i32_i4 v37, v44, v73, 0
	v_dot8_i32_i4 v37, v45, v77, v37
	v_lshl_add_u32 v36, v41, 4, v47
	v_dot8_i32_i4 v41, v44, v75, 0
	v_dot8_i32_i4 v41, v45, v108, v41
	s_waitcnt vmcnt(19)
	v_dot8_i32_i4 v44, v32, v75, 0
	v_dot8_i32_i4 v44, v33, v108, v44
	v_lshl_add_u32 v37, v37, 4, v41
	v_dot8_i32_i4 v41, v32, v73, 0
	v_dot8_i32_i4 v41, v33, v77, v41
	s_waitcnt vmcnt(18)
	v_dot8_i32_i4 v33, v24, v73, 0
	v_dot8_i32_i4 v33, v25, v77, v33
	v_lshl_add_u32 v32, v41, 4, v44
	v_dot8_i32_i4 v41, v24, v75, 0
	v_dot8_i32_i4 v41, v25, v108, v41
	s_waitcnt vmcnt(17)
	v_dot8_i32_i4 v25, v14, v73, 0
	s_nop 0
	v_lshl_add_u32 v24, v33, 4, v41
	v_dot8_i32_i4 v33, v14, v75, 0
	v_dot8_i32_i4 v25, v15, v77, v25
	v_dot8_i32_i4 v33, v15, v108, v33
	s_waitcnt vmcnt(16)
	v_dot8_i32_i4 v15, v28, v73, 0
	v_dot8_i32_i4 v15, v29, v77, v15
	v_lshl_add_u32 v14, v25, 4, v33
	v_dot8_i32_i4 v25, v28, v75, 0
	v_dot8_i32_i4 v25, v29, v108, v25
	s_nop 1
	s_nop 0
	v_lshl_add_u32 v15, v15, 4, v25
	s_nop 0
	v_cndmask_b32_e64 v25, v9, v5, s[40:41]
	v_cndmask_b32_e64 v5, v5, v9, s[40:41]
	s_nop 1
	v_mov_b32_dpp v5, v5 quad_perm:[1,0,3,2] row_mask:0xf bank_mask:0xf
	v_cndmask_b32_e64 v9, v88, v11, s[40:41]
	v_cndmask_b32_e64 v11, v11, v88, s[40:41]
	s_waitcnt lgkmcnt(0)
	v_add_u32_e32 v5, v25, v5
	s_nop 1
	v_mov_b32_dpp v11, v11 quad_perm:[1,0,3,2] row_mask:0xf bank_mask:0xf
	v_cndmask_b32_e64 v25, v82, v56, s[40:41]
	s_nop 1
	v_mov_b32_dpp v25, v25 quad_perm:[1,0,3,2] row_mask:0xf bank_mask:0xf
	v_cndmask_b32_e64 v28, v52, v53, s[40:41]
	s_nop 1
	v_mov_b32_dpp v28, v28 quad_perm:[1,0,3,2] row_mask:0xf bank_mask:0xf
	v_cndmask_b32_e64 v29, v46, v40, s[40:41]
	s_nop 1
	v_mov_b32_dpp v29, v29 quad_perm:[1,0,3,2] row_mask:0xf bank_mask:0xf
	v_cndmask_b32_e64 v33, v36, v37, s[40:41]
	s_nop 1
	v_mov_b32_dpp v33, v33 quad_perm:[1,0,3,2] row_mask:0xf bank_mask:0xf
	s_waitcnt lgkmcnt(0)
	v_add_u32_e32 v9, v9, v11
	v_cndmask_b32_e64 v11, v56, v82, s[40:41]
	s_waitcnt lgkmcnt(0)
	v_add_u32_e32 v11, v11, v25
	v_cndmask_b32_e64 v25, v53, v52, s[40:41]
	s_waitcnt lgkmcnt(0)
	v_add_u32_e32 v25, v25, v28
	v_cndmask_b32_e64 v28, v40, v46, s[40:41]
	s_waitcnt lgkmcnt(0)
	v_add_u32_e32 v28, v28, v29
	v_cndmask_b32_e64 v29, v37, v36, s[40:41]
	s_waitcnt lgkmcnt(0)
	v_add_u32_e32 v29, v29, v33
	v_cndmask_b32_e64 v33, v24, v32, s[40:41]
	v_cndmask_b32_e64 v24, v32, v24, s[40:41]
	v_cndmask_b32_e64 v32, v15, v14, s[40:41]
	v_cndmask_b32_e64 v14, v14, v15, s[40:41]
	v_cndmask_b32_e64 v15, v9, v5, s[42:43]
	v_cndmask_b32_e64 v5, v5, v9, s[42:43]
	s_nop 1
	v_mov_b32_dpp v5, v5 quad_perm:[2,3,0,1] row_mask:0xf bank_mask:0xf
	v_cndmask_b32_e64 v9, v25, v11, s[42:43]
	v_cndmask_b32_e64 v11, v11, v25, s[42:43]
	s_nop 1
	v_mov_b32_dpp v24, v24 quad_perm:[1,0,3,2] row_mask:0xf bank_mask:0xf
	s_nop 1
	v_mov_b32_dpp v14, v14 quad_perm:[1,0,3,2] row_mask:0xf bank_mask:0xf
	s_waitcnt lgkmcnt(0)
	v_add_u32_e32 v5, v15, v5
	s_nop 1
	v_mov_b32_dpp v11, v11 quad_perm:[2,3,0,1] row_mask:0xf bank_mask:0xf
	v_cndmask_b32_e64 v15, v28, v29, s[42:43]
	s_nop 1
	v_mov_b32_dpp v15, v15 quad_perm:[2,3,0,1] row_mask:0xf bank_mask:0xf
	s_waitcnt lgkmcnt(0)
	v_add_u32_e32 v24, v33, v24
	s_waitcnt lgkmcnt(0)
	v_add_u32_e32 v14, v32, v14
	s_waitcnt lgkmcnt(0)
	v_add_u32_e32 v9, v9, v11
	v_cndmask_b32_e64 v11, v29, v28, s[42:43]
	s_waitcnt lgkmcnt(0)
	v_add_u32_e32 v11, v11, v15
	v_cndmask_b32_e64 v15, v14, v24, s[42:43]
	v_cndmask_b32_e64 v14, v24, v14, s[42:43]
	s_nop 1
	v_mov_b32_dpp v14, v14 quad_perm:[2,3,0,1] row_mask:0xf bank_mask:0xf
	s_waitcnt lgkmcnt(0)
	v_add_u32_e32 v14, v15, v14
	v_cndmask_b32_e64 v15, v9, v5, s[44:45]
	v_cndmask_b32_e64 v5, v5, v9, s[44:45]
	v_cndmask_b32_e64 v9, v14, v11, s[44:45]
	v_cndmask_b32_e64 v11, v11, v14, s[44:45]
	s_nop 1
	v_mov_b32_dpp v5, v5 row_half_mirror row_mask:0xf bank_mask:0xf
	s_nop 1
	v_mov_b32_dpp v5, v5 quad_perm:[3,2,1,0] row_mask:0xf bank_mask:0xf
	s_nop 1
	v_mov_b32_dpp v11, v11 row_half_mirror row_mask:0xf bank_mask:0xf
	s_nop 1
	v_mov_b32_dpp v11, v11 quad_perm:[3,2,1,0] row_mask:0xf bank_mask:0xf
	s_waitcnt lgkmcnt(0)
	v_add_u32_e32 v5, v15, v5
	s_waitcnt lgkmcnt(0)
	v_add_u32_e32 v9, v9, v11
	v_cndmask_b32_e64 v11, v9, v5, s[46:47]
	v_cndmask_b32_e64 v5, v5, v9, s[46:47]
	s_nop 1
	v_mov_b32_dpp v5, v5 row_ror:8 row_mask:0xf bank_mask:0xf
	s_waitcnt lgkmcnt(0)
	v_add_u32_e32 v5, v11, v5
	ds_swizzle_b32 v9, v5 offset:swizzle(SWAP,16)
	s_waitcnt lgkmcnt(0)
	v_add_u32_e32 v5, v5, v9
	ds_bpermute_b32 v9, v0, v5
	s_and_saveexec_b64 s[0:1], s[48:49]
	s_cbranch_execz .LBB0_551
	v_ashrrev_i32_e32 v11, 31, v10
	v_lshlrev_b64 v[10:11], 2, v[10:11]
	v_lshl_add_u64 v[14:15], s[8:9], 0, v[10:11]
	v_mov_b32_e32 v14, v133
	v_lshl_add_u64 v[10:11], s[10:11], 0, v[10:11]
	v_mov_b32_e32 v15, v149
	s_nop 0
	v_mov_b32_e32 v10, v141
	s_waitcnt lgkmcnt(0)
	v_add_u32_e32 v5, v5, v9
	v_cvt_f32_i32_e32 v5, v5
	v_mul_f32_e32 v5, v5, v14
	v_mul_f32_e32 v5, v3, v5
	v_mul_f32_e32 v11, 0x3d372713, v5
	v_mul_f32_e32 v11, v5, v11
	v_mul_f32_e32 v9, 0.5, v5
	v_fmac_f32_e32 v5, v5, v11
	v_mul_f32_e32 v5, 0x3f4c422a, v5
	v_add_f32_e32 v5, v5, v5
	v_mul_f32_e32 v5, 0x3fb8aa3b, v5
	v_exp_f32_e32 v5, v5
	s_nop 0
	v_add_f32_e32 v5, 1.0, v5
	v_rcp_f32_e32 v5, v5
	s_nop 0
	v_fma_f32 v5, v5, -2.0, 1.0
	v_add_f32_e32 v5, 1.0, v5
	v_mul_f32_e32 v5, v9, v5
	v_mul_f32_e32 v5, v15, v5
	v_mul_f32_e32 v5, v10, v5
	ds_write_b32 v109, v5 offset:320
.LBB0_551:
	s_or_b64 exec, exec, s[0:1]
	s_waitcnt lgkmcnt(0)
	v_readlane_b32 s0, v4, 0
	s_waitcnt vmcnt(15)
	v_dot8_i32_i4 v5, v86, v73, 0
	v_dot8_i32_i4 v9, v86, v75, 0
	s_lshl_b32 s0, s0, 9
	v_dot8_i32_i4 v5, v87, v77, v5
	v_dot8_i32_i4 v9, v87, v108, v9
	buffer_load_dwordx2 v[88:89], v192, s[52:55], s0 offen
	v_readlane_b32 s0, v4, 1
	s_nop 0
	v_lshl_add_u32 v5, v5, 4, v9
	s_lshl_b32 s0, s0, 9
	s_waitcnt vmcnt(15)
	v_dot8_i32_i4 v9, v78, v73, 0
	v_dot8_i32_i4 v86, v78, v75, 0
	buffer_load_dwordx2 v[90:91], v192, s[52:55], s0 offen
	v_readlane_b32 s0, v4, 2
	v_dot8_i32_i4 v9, v79, v77, v9
	v_dot8_i32_i4 v86, v79, v108, v86
	s_lshl_b32 s0, s0, 9
	s_waitcnt vmcnt(15)
	v_dot8_i32_i4 v78, v54, v73, 0
	v_dot8_i32_i4 v79, v54, v75, 0
	buffer_load_dwordx2 v[82:83], v192, s[52:55], s0 offen
	v_readlane_b32 s0, v4, 3
	v_dot8_i32_i4 v78, v55, v77, v78
	v_dot8_i32_i4 v79, v55, v108, v79
	s_lshl_b32 s0, s0, 9
	s_waitcnt vmcnt(15)
	v_dot8_i32_i4 v55, v84, v73, 0
	v_lshl_add_u32 v54, v78, 4, v79
	buffer_load_dwordx2 v[92:93], v192, s[52:55], s0 offen
	v_readlane_b32 s0, v4, 4
	v_dot8_i32_i4 v78, v84, v75, 0
	s_lshl_b32 s0, s0, 9
	v_dot8_i32_i4 v55, v85, v77, v55
	v_dot8_i32_i4 v78, v85, v108, v78
	buffer_load_dwordx2 v[80:81], v192, s[52:55], s0 offen
	v_readlane_b32 s0, v4, 5
	s_nop 0
	v_lshl_add_u32 v55, v55, 4, v78
	s_lshl_b32 s0, s0, 9
	s_waitcnt vmcnt(16)
	v_dot8_i32_i4 v78, v50, v73, 0
	v_dot8_i32_i4 v79, v50, v75, 0
	buffer_load_dwordx2 v[52:53], v192, s[52:55], s0 offen
	v_readlane_b32 s0, v4, 6
	v_dot8_i32_i4 v78, v51, v77, v78
	v_dot8_i32_i4 v79, v51, v108, v79
	s_lshl_b32 s0, s0, 9
	s_waitcnt vmcnt(16)
	v_dot8_i32_i4 v51, v42, v73, 0
	v_lshl_add_u32 v50, v78, 4, v79
	buffer_load_dwordx2 v[46:47], v192, s[52:55], s0 offen
	v_readlane_b32 s0, v4, 7
	v_dot8_i32_i4 v78, v42, v75, 0
	s_lshl_b32 s0, s0, 9
	v_dot8_i32_i4 v51, v43, v77, v51
	v_dot8_i32_i4 v78, v43, v108, v78
	buffer_load_dwordx2 v[56:57], v192, s[52:55], s0 offen
	v_readlane_b32 s0, v4, 8
	s_nop 0
	v_lshl_add_u32 v42, v51, 4, v78
	s_lshl_b32 s0, s0, 9
	s_waitcnt vmcnt(17)
	v_dot8_i32_i4 v43, v38, v73, 0
	v_dot8_i32_i4 v51, v38, v75, 0
	buffer_load_dwordx2 v[44:45], v192, s[52:55], s0 offen
	v_readlane_b32 s0, v4, 9
	v_dot8_i32_i4 v43, v39, v77, v43
	v_dot8_i32_i4 v51, v39, v108, v51
	s_lshl_b32 s0, s0, 9
	s_waitcnt vmcnt(17)
	v_dot8_i32_i4 v39, v48, v73, 0
	v_lshl_add_u32 v38, v43, 4, v51
	buffer_load_dwordx2 v[36:37], v192, s[52:55], s0 offen
	v_readlane_b32 s0, v4, 10
	v_dot8_i32_i4 v43, v48, v75, 0
	s_lshl_b32 s0, s0, 9
	v_dot8_i32_i4 v39, v49, v77, v39
	v_dot8_i32_i4 v43, v49, v108, v43
	buffer_load_dwordx2 v[32:33], v192, s[52:55], s0 offen
	v_readlane_b32 s0, v4, 11
	s_nop 0
	v_lshl_add_u32 v39, v39, 4, v43
	s_lshl_b32 s0, s0, 9
	s_waitcnt vmcnt(18)
	v_dot8_i32_i4 v43, v34, v73, 0
	v_dot8_i32_i4 v48, v34, v75, 0
	buffer_load_dwordx2 v[40:41], v192, s[52:55], s0 offen
	v_readlane_b32 s0, v4, 12
	v_dot8_i32_i4 v43, v35, v77, v43
	v_dot8_i32_i4 v48, v35, v108, v48
	s_lshl_b32 s0, s0, 9
	s_waitcnt vmcnt(18)
	v_dot8_i32_i4 v35, v26, v73, 0
	v_lshl_add_u32 v34, v43, 4, v48
	buffer_load_dwordx2 v[28:29], v192, s[52:55], s0 offen
	v_readlane_b32 s0, v4, 13
	v_dot8_i32_i4 v43, v26, v75, 0
	s_lshl_b32 s0, s0, 9
	v_dot8_i32_i4 v35, v27, v77, v35
	v_dot8_i32_i4 v43, v27, v108, v43
	buffer_load_dwordx2 v[14:15], v192, s[52:55], s0 offen
	v_readlane_b32 s0, v4, 14
	s_nop 0
	v_lshl_add_u32 v26, v35, 4, v43
	s_lshl_b32 s0, s0, 9
	s_waitcnt vmcnt(19)
	v_dot8_i32_i4 v27, v22, v73, 0
	v_dot8_i32_i4 v35, v22, v75, 0
	buffer_load_dwordx2 v[10:11], v192, s[52:55], s0 offen
	v_readlane_b32 s0, v4, 15
	v_dot8_i32_i4 v27, v23, v77, v27
	v_dot8_i32_i4 v35, v23, v108, v35
	s_lshl_b32 s0, s0, 9
	s_waitcnt vmcnt(19)
	v_dot8_i32_i4 v23, v30, v73, 0
	v_lshl_add_u32 v22, v27, 4, v35
	buffer_load_dwordx2 v[24:25], v192, s[52:55], s0 offen
	v_dot8_i32_i4 v27, v30, v75, 0
	v_dot8_i32_i4 v23, v31, v77, v23
	v_dot8_i32_i4 v27, v31, v108, v27
	s_waitcnt vmcnt(19)
	v_dot8_i32_i4 v30, v20, v75, 0
	v_dot8_i32_i4 v30, v21, v108, v30
	v_lshl_add_u32 v23, v23, 4, v27
	v_dot8_i32_i4 v27, v20, v73, 0
	v_dot8_i32_i4 v27, v21, v77, v27
	s_waitcnt vmcnt(18)
	v_dot8_i32_i4 v21, v16, v73, 0
	v_dot8_i32_i4 v21, v17, v77, v21
	v_lshl_add_u32 v20, v27, 4, v30
	v_dot8_i32_i4 v27, v16, v75, 0
	v_dot8_i32_i4 v27, v17, v108, v27
	v_lshl_add_u32 v9, v9, 4, v86
	s_waitcnt vmcnt(17)
	v_dot8_i32_i4 v17, v12, v73, 0
	v_lshl_add_u32 v16, v21, 4, v27
	v_dot8_i32_i4 v21, v12, v75, 0
	v_dot8_i32_i4 v17, v13, v77, v17
	v_dot8_i32_i4 v21, v13, v108, v21
	s_waitcnt vmcnt(16)
	v_dot8_i32_i4 v13, v18, v73, 0
	v_dot8_i32_i4 v13, v19, v77, v13
	v_lshl_add_u32 v12, v17, 4, v21
	v_dot8_i32_i4 v17, v18, v75, 0
	v_dot8_i32_i4 v17, v19, v108, v17
	s_nop 1
	s_nop 0
	v_lshl_add_u32 v13, v13, 4, v17
	s_nop 0
	v_cndmask_b32_e64 v17, v9, v5, s[40:41]
	v_cndmask_b32_e64 v5, v5, v9, s[40:41]
	s_nop 1
	v_mov_b32_dpp v5, v5 quad_perm:[1,0,3,2] row_mask:0xf bank_mask:0xf
	s_waitcnt lgkmcnt(0)
	v_add_u32_e32 v5, v17, v5
	v_cndmask_b32_e64 v17, v54, v55, s[40:41]
	s_nop 1
	v_mov_b32_dpp v17, v17 quad_perm:[1,0,3,2] row_mask:0xf bank_mask:0xf
	v_cndmask_b32_e64 v18, v50, v42, s[40:41]
	s_nop 1
	v_mov_b32_dpp v18, v18 quad_perm:[1,0,3,2] row_mask:0xf bank_mask:0xf
	v_cndmask_b32_e64 v19, v38, v39, s[40:41]
	s_nop 1
	v_mov_b32_dpp v19, v19 quad_perm:[1,0,3,2] row_mask:0xf bank_mask:0xf
	v_cndmask_b32_e64 v21, v34, v26, s[40:41]
	s_nop 1
	v_mov_b32_dpp v21, v21 quad_perm:[1,0,3,2] row_mask:0xf bank_mask:0xf
	v_cndmask_b32_e64 v9, v55, v54, s[40:41]
	s_waitcnt lgkmcnt(0)
	v_add_u32_e32 v9, v9, v17
	v_cndmask_b32_e64 v17, v42, v50, s[40:41]
	s_waitcnt lgkmcnt(0)
	v_add_u32_e32 v17, v17, v18
	v_cndmask_b32_e64 v18, v39, v38, s[40:41]
	s_waitcnt lgkmcnt(0)
	v_add_u32_e32 v18, v18, v19
	v_cndmask_b32_e64 v19, v26, v34, s[40:41]
	s_waitcnt lgkmcnt(0)
	v_add_u32_e32 v19, v19, v21
	v_cndmask_b32_e64 v21, v23, v22, s[40:41]
	v_cndmask_b32_e64 v22, v22, v23, s[40:41]
	s_nop 1
	v_mov_b32_dpp v22, v22 quad_perm:[1,0,3,2] row_mask:0xf bank_mask:0xf
	s_waitcnt lgkmcnt(0)
	v_add_u32_e32 v21, v21, v22
	v_cndmask_b32_e64 v22, v16, v20, s[40:41]
	v_cndmask_b32_e64 v16, v20, v16, s[40:41]
	v_cndmask_b32_e64 v20, v13, v12, s[40:41]
	v_cndmask_b32_e64 v12, v12, v13, s[40:41]
	v_cndmask_b32_e64 v13, v9, v5, s[42:43]
	v_cndmask_b32_e64 v5, v5, v9, s[42:43]
	s_nop 1
	v_mov_b32_dpp v5, v5 quad_perm:[2,3,0,1] row_mask:0xf bank_mask:0xf
	s_nop 1
	v_mov_b32_dpp v16, v16 quad_perm:[1,0,3,2] row_mask:0xf bank_mask:0xf
	s_nop 1
	v_mov_b32_dpp v12, v12 quad_perm:[1,0,3,2] row_mask:0xf bank_mask:0xf
	v_cndmask_b32_e64 v9, v18, v17, s[42:43]
	s_waitcnt lgkmcnt(0)
	v_add_u32_e32 v5, v13, v5
	v_cndmask_b32_e64 v13, v17, v18, s[42:43]
	s_nop 1
	v_mov_b32_dpp v13, v13 quad_perm:[2,3,0,1] row_mask:0xf bank_mask:0xf
	v_cndmask_b32_e64 v17, v19, v21, s[42:43]
	s_nop 1
	v_mov_b32_dpp v17, v17 quad_perm:[2,3,0,1] row_mask:0xf bank_mask:0xf
	s_waitcnt lgkmcnt(0)
	v_add_u32_e32 v16, v22, v16
	s_waitcnt lgkmcnt(0)
	v_add_u32_e32 v12, v20, v12
	s_waitcnt lgkmcnt(0)
	v_add_u32_e32 v9, v9, v13
	v_cndmask_b32_e64 v13, v21, v19, s[42:43]
	s_waitcnt lgkmcnt(0)
	v_add_u32_e32 v13, v13, v17
	v_cndmask_b32_e64 v17, v12, v16, s[42:43]
	v_cndmask_b32_e64 v12, v16, v12, s[42:43]
	s_nop 1
	v_mov_b32_dpp v12, v12 quad_perm:[2,3,0,1] row_mask:0xf bank_mask:0xf
	v_cndmask_b32_e64 v16, v9, v5, s[44:45]
	v_cndmask_b32_e64 v5, v5, v9, s[44:45]
	s_nop 1
	v_mov_b32_dpp v5, v5 row_half_mirror row_mask:0xf bank_mask:0xf
	s_nop 1
	v_mov_b32_dpp v5, v5 quad_perm:[3,2,1,0] row_mask:0xf bank_mask:0xf
	s_waitcnt lgkmcnt(0)
	v_add_u32_e32 v12, v17, v12
	v_cndmask_b32_e64 v9, v12, v13, s[44:45]
	v_cndmask_b32_e64 v12, v13, v12, s[44:45]
	s_nop 1
	v_mov_b32_dpp v12, v12 row_half_mirror row_mask:0xf bank_mask:0xf
	s_nop 1
	v_mov_b32_dpp v12, v12 quad_perm:[3,2,1,0] row_mask:0xf bank_mask:0xf
	s_waitcnt lgkmcnt(0)
	v_add_u32_e32 v5, v16, v5
	s_waitcnt lgkmcnt(0)
	v_add_u32_e32 v9, v9, v12
	v_cndmask_b32_e64 v12, v9, v5, s[46:47]
	v_cndmask_b32_e64 v5, v5, v9, s[46:47]
	s_nop 1
	v_mov_b32_dpp v5, v5 row_ror:8 row_mask:0xf bank_mask:0xf
	s_waitcnt lgkmcnt(0)
	v_add_u32_e32 v5, v12, v5
	ds_swizzle_b32 v9, v5 offset:swizzle(SWAP,16)
	s_waitcnt lgkmcnt(0)
	v_add_u32_e32 v5, v5, v9
	ds_bpermute_b32 v12, v0, v5
	s_and_saveexec_b64 s[0:1], s[48:49]
	s_cbranch_execz .LBB0_553
	v_ashrrev_i32_e32 v9, 31, v8
	v_lshlrev_b64 v[8:9], 2, v[8:9]
	v_lshl_add_u64 v[16:17], s[8:9], 0, v[8:9]
	v_mov_b32_e32 v13, v134
	v_lshl_add_u64 v[8:9], s[10:11], 0, v[8:9]
	v_mov_b32_e32 v16, v150
	s_nop 0
	v_mov_b32_e32 v8, v142
	s_waitcnt lgkmcnt(0)
	v_add_u32_e32 v5, v5, v12
	v_cvt_f32_i32_e32 v5, v5
	v_mul_f32_e32 v5, v5, v13
	v_mul_f32_e32 v5, v3, v5
	v_mul_f32_e32 v12, 0x3d372713, v5
	v_mul_f32_e32 v12, v5, v12
	v_mul_f32_e32 v9, 0.5, v5
	v_fmac_f32_e32 v5, v5, v12
	v_mul_f32_e32 v5, 0x3f4c422a, v5
	v_add_f32_e32 v5, v5, v5
	v_mul_f32_e32 v5, 0x3fb8aa3b, v5
	v_exp_f32_e32 v5, v5
	s_nop 0
	v_add_f32_e32 v5, 1.0, v5
	v_rcp_f32_e32 v5, v5
	s_nop 0
	v_fma_f32 v5, v5, -2.0, 1.0
	v_add_f32_e32 v5, 1.0, v5
	v_mul_f32_e32 v5, v9, v5
	v_mul_f32_e32 v5, v16, v5
	v_mul_f32_e32 v5, v8, v5
	ds_write_b32 v109, v5 offset:384
.LBB0_553:
	s_or_b64 exec, exec, s[0:1]
	s_waitcnt vmcnt(15)
	v_dot8_i32_i4 v5, v88, v73, 0
	v_dot8_i32_i4 v8, v88, v75, 0
	v_dot8_i32_i4 v5, v89, v77, v5
	v_dot8_i32_i4 v8, v89, v108, v8
	s_waitcnt vmcnt(14)
	v_dot8_i32_i4 v9, v90, v75, 0
	v_dot8_i32_i4 v9, v91, v108, v9
	v_lshl_add_u32 v5, v5, 4, v8
	v_dot8_i32_i4 v8, v90, v73, 0
	v_dot8_i32_i4 v8, v91, v77, v8
	s_waitcnt lgkmcnt(0)
	s_waitcnt vmcnt(13)
	v_dot8_i32_i4 v12, v82, v75, 0
	v_dot8_i32_i4 v12, v83, v108, v12
	v_lshl_add_u32 v8, v8, 4, v9
	v_dot8_i32_i4 v9, v82, v73, 0
	v_dot8_i32_i4 v9, v83, v77, v9
	s_waitcnt vmcnt(12)
	v_dot8_i32_i4 v13, v92, v75, 0
	v_dot8_i32_i4 v13, v93, v108, v13
	v_lshl_add_u32 v9, v9, 4, v12
	v_dot8_i32_i4 v12, v92, v73, 0
	v_dot8_i32_i4 v12, v93, v77, v12
	s_waitcnt vmcnt(11)
	v_dot8_i32_i4 v16, v80, v75, 0
	v_dot8_i32_i4 v16, v81, v108, v16
	v_lshl_add_u32 v12, v12, 4, v13
	v_dot8_i32_i4 v13, v80, v73, 0
	v_dot8_i32_i4 v13, v81, v77, v13
	s_waitcnt vmcnt(10)
	v_dot8_i32_i4 v17, v52, v75, 0
	v_dot8_i32_i4 v17, v53, v108, v17
	v_lshl_add_u32 v13, v13, 4, v16
	v_dot8_i32_i4 v16, v52, v73, 0
	v_dot8_i32_i4 v16, v53, v77, v16
	s_waitcnt vmcnt(9)
	v_dot8_i32_i4 v18, v46, v75, 0
	v_dot8_i32_i4 v18, v47, v108, v18
	v_lshl_add_u32 v16, v16, 4, v17
	v_dot8_i32_i4 v17, v46, v73, 0
	v_dot8_i32_i4 v17, v47, v77, v17
	s_waitcnt vmcnt(8)
	v_dot8_i32_i4 v19, v56, v75, 0
	v_dot8_i32_i4 v19, v57, v108, v19
	v_lshl_add_u32 v17, v17, 4, v18
	v_dot8_i32_i4 v18, v56, v73, 0
	v_dot8_i32_i4 v18, v57, v77, v18
	s_waitcnt vmcnt(7)
	v_dot8_i32_i4 v20, v44, v75, 0
	v_dot8_i32_i4 v20, v45, v108, v20
	v_lshl_add_u32 v18, v18, 4, v19
	v_dot8_i32_i4 v19, v44, v73, 0
	v_dot8_i32_i4 v19, v45, v77, v19
	s_waitcnt vmcnt(6)
	v_dot8_i32_i4 v21, v36, v75, 0
	v_dot8_i32_i4 v21, v37, v108, v21
	v_lshl_add_u32 v19, v19, 4, v20
	v_dot8_i32_i4 v20, v36, v73, 0
	v_dot8_i32_i4 v20, v37, v77, v20
	s_waitcnt vmcnt(5)
	v_dot8_i32_i4 v22, v32, v75, 0
	v_dot8_i32_i4 v22, v33, v108, v22
	v_lshl_add_u32 v20, v20, 4, v21
	v_dot8_i32_i4 v21, v32, v73, 0
	v_dot8_i32_i4 v21, v33, v77, v21
	s_waitcnt vmcnt(4)
	v_dot8_i32_i4 v23, v40, v75, 0
	v_dot8_i32_i4 v23, v41, v108, v23
	v_lshl_add_u32 v21, v21, 4, v22
	v_dot8_i32_i4 v22, v40, v73, 0
	v_dot8_i32_i4 v22, v41, v77, v22
	s_waitcnt vmcnt(3)
	v_dot8_i32_i4 v26, v28, v75, 0
	v_dot8_i32_i4 v26, v29, v108, v26
	v_lshl_add_u32 v22, v22, 4, v23
	v_dot8_i32_i4 v23, v28, v73, 0
	v_dot8_i32_i4 v23, v29, v77, v23
	s_waitcnt vmcnt(2)
	v_dot8_i32_i4 v27, v14, v75, 0
	v_dot8_i32_i4 v27, v15, v108, v27
	v_lshl_add_u32 v23, v23, 4, v26
	v_dot8_i32_i4 v26, v14, v73, 0
	v_dot8_i32_i4 v26, v15, v77, v26
	s_waitcnt vmcnt(1)
	v_dot8_i32_i4 v15, v10, v73, 0
	s_nop 0
	v_lshl_add_u32 v14, v26, 4, v27
	v_dot8_i32_i4 v26, v10, v75, 0
	v_dot8_i32_i4 v15, v11, v77, v15
	v_dot8_i32_i4 v26, v11, v108, v26
	s_waitcnt vmcnt(0)
	v_dot8_i32_i4 v11, v24, v73, 0
	v_dot8_i32_i4 v11, v25, v77, v11
	v_lshl_add_u32 v10, v15, 4, v26
	v_dot8_i32_i4 v15, v24, v75, 0
	v_dot8_i32_i4 v15, v25, v108, v15
	s_nop 1
	s_nop 0
	v_lshl_add_u32 v11, v11, 4, v15
	s_nop 0
	v_cndmask_b32_e64 v15, v8, v5, s[40:41]
	v_cndmask_b32_e64 v5, v5, v8, s[40:41]
	v_cndmask_b32_e64 v8, v9, v12, s[40:41]
	s_nop 1
	v_mov_b32_dpp v8, v8 quad_perm:[1,0,3,2] row_mask:0xf bank_mask:0xf
	s_nop 1
	v_mov_b32_dpp v5, v5 quad_perm:[1,0,3,2] row_mask:0xf bank_mask:0xf
	v_cndmask_b32_e64 v9, v12, v9, s[40:41]
	v_cndmask_b32_e64 v24, v13, v16, s[40:41]
	s_waitcnt lgkmcnt(0)
	v_add_u32_e32 v8, v9, v8
	v_cndmask_b32_e64 v9, v16, v13, s[40:41]
	v_cndmask_b32_e64 v13, v17, v18, s[40:41]
	s_waitcnt lgkmcnt(0)
	v_add_u32_e32 v5, v15, v5
	s_nop 1
	v_mov_b32_dpp v13, v13 quad_perm:[1,0,3,2] row_mask:0xf bank_mask:0xf
	v_cndmask_b32_e64 v15, v19, v20, s[40:41]
	s_nop 1
	v_mov_b32_dpp v15, v15 quad_perm:[1,0,3,2] row_mask:0xf bank_mask:0xf
	v_cndmask_b32_e64 v16, v21, v22, s[40:41]
	s_nop 1
	v_mov_b32_dpp v16, v16 quad_perm:[1,0,3,2] row_mask:0xf bank_mask:0xf
	v_cndmask_b32_e64 v12, v18, v17, s[40:41]
	s_waitcnt lgkmcnt(0)
	v_add_u32_e32 v12, v12, v13
	v_cndmask_b32_e64 v13, v20, v19, s[40:41]
	s_waitcnt lgkmcnt(0)
	v_add_u32_e32 v13, v13, v15
	v_cndmask_b32_e64 v15, v22, v21, s[40:41]
	s_nop 1
	v_mov_b32_dpp v24, v24 quad_perm:[1,0,3,2] row_mask:0xf bank_mask:0xf
	s_waitcnt lgkmcnt(0)
	v_add_u32_e32 v15, v15, v16
	v_cndmask_b32_e64 v16, v14, v23, s[40:41]
	v_cndmask_b32_e64 v14, v23, v14, s[40:41]
	v_cndmask_b32_e64 v17, v10, v11, s[40:41]
	s_nop 1
	v_mov_b32_dpp v14, v14 quad_perm:[1,0,3,2] row_mask:0xf bank_mask:0xf
	s_nop 1
	v_mov_b32_dpp v17, v17 quad_perm:[1,0,3,2] row_mask:0xf bank_mask:0xf
	s_waitcnt lgkmcnt(0)
	v_add_u32_e32 v9, v9, v24
	v_cndmask_b32_e64 v10, v11, v10, s[40:41]
	v_cndmask_b32_e64 v18, v5, v8, s[42:43]
	s_waitcnt lgkmcnt(0)
	v_add_u32_e32 v14, v16, v14
	s_waitcnt lgkmcnt(0)
	v_add_u32_e32 v10, v10, v17
	v_cndmask_b32_e64 v5, v8, v5, s[42:43]
	v_cndmask_b32_e64 v8, v12, v9, s[42:43]
	v_cndmask_b32_e64 v9, v9, v12, s[42:43]
	s_nop 1
	v_mov_b32_dpp v9, v9 quad_perm:[2,3,0,1] row_mask:0xf bank_mask:0xf
	v_cndmask_b32_e64 v11, v13, v15, s[42:43]
	v_cndmask_b32_e64 v12, v14, v10, s[42:43]
	s_nop 1
	v_mov_b32_dpp v18, v18 quad_perm:[2,3,0,1] row_mask:0xf bank_mask:0xf
	s_nop 1
	v_mov_b32_dpp v11, v11 quad_perm:[2,3,0,1] row_mask:0xf bank_mask:0xf
	s_nop 1
	v_mov_b32_dpp v12, v12 quad_perm:[2,3,0,1] row_mask:0xf bank_mask:0xf
	s_waitcnt lgkmcnt(0)
	v_add_u32_e32 v8, v8, v9
	v_cndmask_b32_e64 v9, v15, v13, s[42:43]
	v_cndmask_b32_e64 v10, v10, v14, s[42:43]
	s_waitcnt lgkmcnt(0)
	v_add_u32_e32 v5, v5, v18
	s_waitcnt lgkmcnt(0)
	v_add_u32_e32 v9, v9, v11
	s_waitcnt lgkmcnt(0)
	v_add_u32_e32 v10, v10, v12
	v_cndmask_b32_e64 v11, v5, v8, s[44:45]
	v_cndmask_b32_e64 v12, v9, v10, s[44:45]
	s_nop 1
	v_mov_b32_dpp v11, v11 row_half_mirror row_mask:0xf bank_mask:0xf
	s_nop 1
	v_mov_b32_dpp v11, v11 quad_perm:[3,2,1,0] row_mask:0xf bank_mask:0xf
	s_nop 1
	v_mov_b32_dpp v12, v12 row_half_mirror row_mask:0xf bank_mask:0xf
	s_nop 1
	v_mov_b32_dpp v12, v12 quad_perm:[3,2,1,0] row_mask:0xf bank_mask:0xf
	v_cndmask_b32_e64 v5, v8, v5, s[44:45]
	v_cndmask_b32_e64 v8, v10, v9, s[44:45]
	s_waitcnt lgkmcnt(0)
	v_add_u32_e32 v5, v5, v11
	s_waitcnt lgkmcnt(0)
	v_add_u32_e32 v8, v8, v12
	v_cndmask_b32_e64 v9, v5, v8, s[46:47]
	s_nop 1
	v_mov_b32_dpp v9, v9 row_ror:8 row_mask:0xf bank_mask:0xf
	v_cndmask_b32_e64 v5, v8, v5, s[46:47]
	s_waitcnt lgkmcnt(0)
	v_add_u32_e32 v5, v5, v9
	ds_swizzle_b32 v8, v5 offset:swizzle(SWAP,16)
	s_waitcnt lgkmcnt(0)
	v_add_u32_e32 v8, v5, v8
	ds_bpermute_b32 v0, v0, v8
	s_and_saveexec_b64 s[0:1], s[48:49]
	s_cbranch_execz .LBB0_536
	v_ashrrev_i32_e32 v5, 31, v4
	v_lshlrev_b64 v[4:5], 2, v[4:5]
	v_lshl_add_u64 v[10:11], s[8:9], 0, v[4:5]
	v_mov_b32_e32 v9, v135
	v_lshl_add_u64 v[4:5], s[10:11], 0, v[4:5]
	v_mov_b32_e32 v6, v151
	s_nop 0
	v_mov_b32_e32 v4, v143
	s_waitcnt lgkmcnt(0)
	v_add_u32_e32 v0, v8, v0
	v_cvt_f32_i32_e32 v0, v0
	v_mul_f32_e32 v0, v0, v9
	v_mul_f32_e32 v0, v3, v0
	v_mul_f32_e32 v5, 0x3d372713, v0
	v_mul_f32_e32 v5, v0, v5
	v_mul_f32_e32 v3, 0.5, v0
	v_fmac_f32_e32 v0, v0, v5
	v_mul_f32_e32 v0, 0x3f4c422a, v0
	v_add_f32_e32 v0, v0, v0
	v_mul_f32_e32 v0, 0x3fb8aa3b, v0
	v_exp_f32_e32 v0, v0
	s_nop 0
	v_add_f32_e32 v0, 1.0, v0
	v_rcp_f32_e32 v0, v0
	s_nop 0
	v_fma_f32 v0, v0, -2.0, 1.0
	v_add_f32_e32 v0, 1.0, v0
	v_mul_f32_e32 v0, v3, v0
	v_mul_f32_e32 v0, v6, v0
	v_mul_f32_e32 v0, v4, v0
	ds_write_b32 v109, v0 offset:448
	s_branch .LBB0_536

.LBB0_668:
	v_cmp_gt_i32_e32 vcc, s33, v2
	s_or_b64 s[16:17], s[16:17], exec
	s_and_saveexec_b64 s[18:19], vcc
	s_cbranch_execz .LBB0_667
	v_ashrrev_i32_e32 v3, 31, v2
	v_lshlrev_b64 v[4:5], 11, v[2:3]
	v_lshl_add_u64 v[8:9], v[60:61], 0, v[4:5]
	global_load_dwordx4 v[4:7], v[8:9], off offset:16
	s_nop 0
	global_load_dwordx4 v[8:11], v[8:9], off
	v_lshlrev_b64 v[110:111], 9, v[2:3]
	v_lshl_add_u64 v[110:111], v[62:63], 0, v[110:111]
	global_load_dword v112, v[110:111], off
	global_load_dword v113, v[110:111], off offset:64
	global_load_dword v114, v[110:111], off offset:128
	global_load_dword v115, v[110:111], off offset:192
	global_load_dword v116, v[110:111], off offset:256
	global_load_dword v117, v[110:111], off offset:320
	global_load_dword v118, v[110:111], off offset:384
	global_load_dword v119, v[110:111], off offset:448
	v_add_u32_e32 v109, s20, v193
	s_waitcnt vmcnt(9)
	v_lshlrev_b32_e32 v13, 16, v4
	s_waitcnt vmcnt(8)
	v_lshlrev_b32_e32 v12, 16, v8
	v_and_b32_e32 v8, 0xffff0000, v8
	v_lshlrev_b32_e32 v14, 16, v9
	v_and_b32_e32 v15, 0xffff0000, v9
	s_waitcnt lgkmcnt(0)
	v_max3_f32 v0, |v12|, 0, |v8|
	v_lshlrev_b32_e32 v17, 16, v10
	v_and_b32_e32 v10, 0xffff0000, v10
	v_max3_f32 v0, v0, |v14|, |v15|
	v_lshlrev_b32_e32 v19, 16, v11
	v_and_b32_e32 v11, 0xffff0000, v11
	v_max3_f32 v0, v0, |v17|, |v10|
	v_and_b32_e32 v4, 0xffff0000, v4
	v_max3_f32 v0, v0, |v19|, |v11|
	v_lshlrev_b32_e32 v16, 16, v5
	v_and_b32_e32 v5, 0xffff0000, v5
	v_max3_f32 v0, v0, |v13|, |v4|
	v_lshlrev_b32_e32 v18, 16, v6
	v_and_b32_e32 v6, 0xffff0000, v6
	v_max3_f32 v0, v0, |v16|, |v5|
	v_lshlrev_b32_e32 v20, 16, v7
	v_and_b32_e32 v7, 0xffff0000, v7
	v_max3_f32 v0, v0, |v18|, |v6|
	v_max3_f32 v9, v0, |v20|, |v7|
	v_and_b32_e32 v0, 64, v219
	v_add_u32_e32 v21, 64, v0
	v_xor_b32_e32 v0, 32, v219
	v_cmp_lt_i32_e32 vcc, v0, v21
	s_nop 1
	v_cndmask_b32_e32 v0, v219, v0, vcc
	v_lshlrev_b32_e32 v0, 2, v0
	ds_bpermute_b32 v22, v0, v9
	s_waitcnt lgkmcnt(0)
	v_max_f32_e32 v22, v22, v22
	v_max_f32_e32 v9, v9, v22
	v_xor_b32_e32 v22, 16, v219
	v_cmp_lt_i32_e32 vcc, v22, v21
	s_nop 1
	v_cndmask_b32_e32 v22, v219, v22, vcc
	v_lshlrev_b32_e32 v22, 2, v22
	ds_bpermute_b32 v22, v22, v9
	s_waitcnt lgkmcnt(0)
	v_max_f32_e32 v22, v22, v22
	v_max_f32_e32 v9, v9, v22
	v_xor_b32_e32 v22, 8, v219
	v_cmp_lt_i32_e32 vcc, v22, v21
	s_nop 1
	v_cndmask_b32_e32 v22, v219, v22, vcc
	v_lshlrev_b32_e32 v22, 2, v22
	ds_bpermute_b32 v22, v22, v9
	s_waitcnt lgkmcnt(0)
	v_max_f32_e32 v22, v22, v22
	v_max_f32_e32 v9, v9, v22
	v_xor_b32_e32 v22, 4, v219
	v_cmp_lt_i32_e32 vcc, v22, v21
	s_nop 1
	v_cndmask_b32_e32 v22, v219, v22, vcc
	v_lshlrev_b32_e32 v22, 2, v22
	ds_bpermute_b32 v22, v22, v9
	s_waitcnt lgkmcnt(0)
	v_max_f32_e32 v22, v22, v22
	v_max_f32_e32 v9, v9, v22
	v_xor_b32_e32 v22, 2, v219
	v_cmp_lt_i32_e32 vcc, v22, v21
	s_nop 1
	v_cndmask_b32_e32 v22, v219, v22, vcc
	v_lshlrev_b32_e32 v22, 2, v22
	ds_bpermute_b32 v22, v22, v9
	s_waitcnt lgkmcnt(0)
	v_max_f32_e32 v22, v22, v22
	v_max_f32_e32 v9, v9, v22
	v_xor_b32_e32 v22, 1, v219
	v_cmp_lt_i32_e32 vcc, v22, v21
	s_nop 1
	v_cndmask_b32_e32 v21, v219, v22, vcc
	v_lshlrev_b32_e32 v21, 2, v21
	ds_bpermute_b32 v21, v21, v9
	s_waitcnt lgkmcnt(0)
	v_max_f32_e32 v21, v21, v21
	v_max_f32_e32 v9, v9, v21
	v_div_scale_f32 v21, s[22:23], v9, v9, s69
	v_rcp_f32_e32 v22, v21
	v_cmp_lt_f32_e64 s[0:1], 0, v9
	v_fma_f32 v23, -v21, v22, 1.0
	v_fmac_f32_e32 v22, v23, v22
	v_div_scale_f32 v23, vcc, s69, v9, s69
	v_mul_f32_e32 v24, v23, v22
	v_fma_f32 v25, -v21, v24, v23
	v_fmac_f32_e32 v24, v25, v22
	v_fma_f32 v21, -v21, v24, v23
	v_div_fmas_f32 v21, v21, v22, v24
	v_div_fixup_f32 v21, v21, v9, s69
	v_cndmask_b32_e64 v21, 0, v21, s[0:1]
	v_mul_f32_e32 v12, v21, v12
	v_mul_f32_e32 v8, v21, v8
	v_rndne_f32_e32 v12, v12
	v_rndne_f32_e32 v8, v8
	v_cvt_i32_f32_e32 v12, v12
	v_cvt_i32_f32_e32 v8, v8
	v_mul_f32_e32 v14, v21, v14
	v_mul_f32_e32 v15, v21, v15
	v_rndne_f32_e32 v14, v14
	v_rndne_f32_e32 v15, v15
	v_cvt_i32_f32_e32 v14, v14
	v_cvt_i32_f32_e32 v15, v15
	v_mul_f32_e32 v17, v21, v17
	v_mul_f32_e32 v10, v21, v10
	v_rndne_f32_e32 v17, v17
	v_rndne_f32_e32 v10, v10
	v_add_u32_e32 v22, 8, v12
	v_add_u32_e32 v23, 8, v8
	v_cvt_i32_f32_e32 v17, v17
	v_cvt_i32_f32_e32 v10, v10
	v_mul_f32_e32 v11, v21, v11
	v_lshrrev_b32_e32 v22, 4, v22
	v_and_b32_e32 v23, 0xf0, v23
	v_mul_f32_e32 v19, v21, v19
	v_rndne_f32_e32 v11, v11
	v_and_or_b32 v22, v22, 15, v23
	v_lshl_add_u32 v23, v14, 4, v222
	v_lshl_add_u32 v24, v15, 8, v223
	v_rndne_f32_e32 v19, v19
	v_cvt_i32_f32_e32 v11, v11
	v_and_b32_e32 v23, 0xf00, v23
	v_and_b32_e32 v24, 0xf000, v24
	v_cvt_i32_f32_e32 v19, v19
	v_or3_b32 v22, v22, v23, v24
	v_lshl_add_u32 v23, v17, 12, v224
	v_lshl_add_u32 v24, v10, 16, v225
	v_and_b32_e32 v12, 15, v12
	v_lshlrev_b32_e32 v8, 4, v8
	v_lshlrev_b32_e32 v14, 8, v14
	v_and_b32_e32 v23, 0xf0000, v23
	v_and_b32_e32 v24, 0xf00000, v24
	v_and_b32_e32 v8, 0xf0, v8
	v_and_b32_e32 v14, 0xf00, v14
	v_lshlrev_b32_e32 v15, 12, v15
	v_lshlrev_b32_e32 v17, 16, v17
	v_or3_b32 v22, v22, v23, v24
	v_lshl_add_u32 v24, v11, 24, v227
	v_lshl_or_b32 v11, v11, 28, v12
	v_and_b32_e32 v15, 0xf000, v15
	v_and_b32_e32 v17, 0xf0000, v17
	v_lshlrev_b32_e32 v10, 20, v10
	v_lshl_add_u32 v23, v19, 20, v226
	v_lshlrev_b32_e32 v19, 24, v19
	v_or3_b32 v8, v11, v8, v14
	v_and_b32_e32 v10, 0xf00000, v10
	v_and_b32_e32 v19, 0xf000000, v19
	v_or3_b32 v8, v8, v15, v17
	v_or3_b32 v75, v8, v10, v19
	v_mul_f32_e32 v8, v21, v13
	v_mul_f32_e32 v4, v21, v4
	v_rndne_f32_e32 v8, v8
	v_rndne_f32_e32 v4, v4
	v_cvt_i32_f32_e32 v8, v8
	v_cvt_i32_f32_e32 v4, v4
	v_mul_f32_e32 v5, v21, v5
	v_rndne_f32_e32 v5, v5
	v_add_u32_e32 v10, 8, v8
	v_add_u32_e32 v11, 8, v4
	v_lshrrev_b32_e32 v10, 4, v10
	v_and_b32_e32 v11, 0xf0, v11
	v_and_or_b32 v10, v10, 15, v11
	v_mul_f32_e32 v11, v21, v16
	v_rndne_f32_e32 v11, v11
	v_cvt_i32_f32_e32 v11, v11
	v_cvt_i32_f32_e32 v5, v5
	v_mul_f32_e32 v6, v21, v6
	v_rndne_f32_e32 v6, v6
	v_lshl_add_u32 v12, v11, 4, v222
	v_lshl_add_u32 v13, v5, 8, v223
	v_and_b32_e32 v12, 0xf00, v12
	v_and_b32_e32 v13, 0xf000, v13
	v_or3_b32 v10, v10, v12, v13
	v_mul_f32_e32 v12, v21, v18
	v_rndne_f32_e32 v12, v12
	v_cvt_i32_f32_e32 v12, v12
	v_cvt_i32_f32_e32 v6, v6
	v_mul_f32_e32 v7, v21, v7
	v_rndne_f32_e32 v7, v7
	v_lshl_add_u32 v13, v12, 12, v224
	v_lshl_add_u32 v14, v6, 16, v225
	v_and_b32_e32 v13, 0xf0000, v13
	v_and_b32_e32 v14, 0xf00000, v14
	v_or3_b32 v10, v10, v13, v14
	v_mul_f32_e32 v13, v21, v20
	v_rndne_f32_e32 v13, v13
	v_cvt_i32_f32_e32 v7, v7
	v_cvt_i32_f32_e32 v13, v13
	v_and_b32_e32 v8, 15, v8
	v_lshlrev_b32_e32 v4, 4, v4
	v_lshlrev_b32_e32 v11, 8, v11
	v_and_b32_e32 v4, 0xf0, v4
	v_and_b32_e32 v11, 0xf00, v11
	v_lshlrev_b32_e32 v5, 12, v5
	v_lshlrev_b32_e32 v12, 16, v12
	v_lshl_add_u32 v15, v7, 24, v227
	v_lshl_or_b32 v7, v7, 28, v8
	v_and_b32_e32 v5, 0xf000, v5
	v_and_b32_e32 v12, 0xf0000, v12
	v_lshlrev_b32_e32 v6, 20, v6
	v_lshl_add_u32 v14, v13, 20, v226
	v_lshlrev_b32_e32 v13, 24, v13
	v_or3_b32 v4, v7, v4, v11
	v_and_b32_e32 v6, 0xf00000, v6
	v_and_b32_e32 v13, 0xf000000, v13
	v_or3_b32 v4, v4, v5, v12
	v_or3_b32 v108, v4, v6, v13
	v_lshlrev_b64 v[6:7], 9, v[2:3]
	v_and_b32_e32 v14, 0xf000000, v14
	v_and_b32_e32 v15, 0xf0000000, v15
	v_lshl_add_u64 v[4:5], v[62:63], 0, v[6:7]
	v_or3_b32 v77, v10, v14, v15
	s_waitcnt vmcnt(7)
	v_mov_b32_e32 v20, v112
	s_waitcnt vmcnt(6)
	v_mov_b32_e32 v18, v113
	s_waitcnt vmcnt(5)
	v_mov_b32_e32 v16, v114
	s_waitcnt vmcnt(4)
	v_mov_b32_e32 v14, v115
	s_waitcnt vmcnt(3)
	v_mov_b32_e32 v12, v116
	s_waitcnt vmcnt(2)
	v_mov_b32_e32 v10, v117
	s_waitcnt vmcnt(1)
	v_mov_b32_e32 v8, v118
	s_nop 0
	s_waitcnt vmcnt(0)
	v_mov_b32_e32 v4, v119
	v_and_b32_e32 v23, 0xf000000, v23
	v_and_b32_e32 v24, 0xf0000000, v24
	v_or3_b32 v73, v22, v23, v24
	v_mul_f32_e32 v3, 0x3c09ae41, v9
	v_lshl_add_u64 v[6:7], v[64:65], 0, v[6:7]
	v_lshlrev_b32_e32 v120, 2, v20
	v_lshlrev_b32_e32 v121, 2, v18
	v_lshlrev_b32_e32 v122, 2, v16
	v_lshlrev_b32_e32 v123, 2, v14
	v_lshlrev_b32_e32 v124, 2, v12
	v_lshlrev_b32_e32 v125, 2, v10
	v_lshlrev_b32_e32 v126, 2, v8
	v_lshlrev_b32_e32 v127, 2, v4
	v_lshlrev_b32_e32 v20, 9, v20
	v_lshlrev_b32_e32 v18, 9, v18
	v_lshlrev_b32_e32 v16, 9, v16
	v_lshlrev_b32_e32 v14, 9, v14
	v_lshlrev_b32_e32 v12, 9, v12
	v_lshlrev_b32_e32 v10, 9, v10
	v_lshlrev_b32_e32 v8, 9, v8
	v_lshlrev_b32_e32 v4, 9, v4
	s_nop 0
	v_readlane_b32 s0, v20, 0
	s_nop 4
	buffer_load_dwordx2 v[100:101], v192, s[52:55], s0 offen
	v_readlane_b32 s0, v20, 1
	s_nop 4
	buffer_load_dwordx2 v[102:103], v192, s[52:55], s0 offen
	v_readlane_b32 s0, v20, 2
	s_nop 4
	buffer_load_dwordx2 v[98:99], v192, s[52:55], s0 offen
	v_readlane_b32 s0, v20, 3
	s_nop 4
	buffer_load_dwordx2 v[104:105], v192, s[52:55], s0 offen
	v_readlane_b32 s0, v20, 4
	s_nop 4
	buffer_load_dwordx2 v[94:95], v192, s[52:55], s0 offen
	v_readlane_b32 s0, v20, 5
	s_nop 4
	buffer_load_dwordx2 v[86:87], v192, s[52:55], s0 offen
	v_readlane_b32 s0, v20, 6
	s_nop 4
	buffer_load_dwordx2 v[84:85], v192, s[52:55], s0 offen
	v_readlane_b32 s0, v20, 7
	s_nop 4
	buffer_load_dwordx2 v[90:91], v192, s[52:55], s0 offen
	v_readlane_b32 s0, v20, 8
	s_nop 4
	buffer_load_dwordx2 v[78:79], v192, s[52:55], s0 offen
	v_readlane_b32 s0, v20, 9
	s_nop 4
	buffer_load_dwordx2 v[50:51], v192, s[52:55], s0 offen
	v_readlane_b32 s0, v20, 10
	s_nop 4
	buffer_load_dwordx2 v[48:49], v192, s[52:55], s0 offen
	v_readlane_b32 s0, v20, 11
	s_nop 4
	buffer_load_dwordx2 v[54:55], v192, s[52:55], s0 offen
	v_readlane_b32 s0, v20, 12
	s_nop 4
	buffer_load_dwordx2 v[42:43], v192, s[52:55], s0 offen
	v_readlane_b32 s0, v20, 13
	s_nop 4
	buffer_load_dwordx2 v[34:35], v192, s[52:55], s0 offen
	v_readlane_b32 s0, v20, 14
	s_nop 4
	buffer_load_dwordx2 v[32:33], v192, s[52:55], s0 offen
	v_readlane_b32 s0, v20, 15
	s_nop 4
	buffer_load_dwordx2 v[38:39], v192, s[52:55], s0 offen
	global_load_dword v128, v120, s[8:9]
	global_load_dword v136, v120, s[10:11]
	global_load_dword v144, v[6:7], off
	global_load_dword v129, v121, s[8:9]
	global_load_dword v137, v121, s[10:11]
	global_load_dword v145, v[6:7], off offset:64
	global_load_dword v130, v122, s[8:9]
	global_load_dword v138, v122, s[10:11]
	global_load_dword v146, v[6:7], off offset:128
	global_load_dword v131, v123, s[8:9]
	global_load_dword v139, v123, s[10:11]
	global_load_dword v147, v[6:7], off offset:192
	global_load_dword v132, v124, s[8:9]
	global_load_dword v140, v124, s[10:11]
	global_load_dword v148, v[6:7], off offset:256
	global_load_dword v133, v125, s[8:9]
	global_load_dword v141, v125, s[10:11]
	global_load_dword v149, v[6:7], off offset:320
	global_load_dword v134, v126, s[8:9]
	global_load_dword v142, v126, s[10:11]
	global_load_dword v150, v[6:7], off offset:384
	global_load_dword v135, v127, s[8:9]
	global_load_dword v143, v127, s[10:11]
	global_load_dword v151, v[6:7], off offset:448
	s_nop 3
	s_waitcnt vmcnt(39)
	v_dot8_i32_i4 v5, v100, v73, 0
	s_nop 1
	v_dot8_i32_i4 v9, v100, v75, 0
	v_dot8_i32_i4 v5, v101, v77, v5
	v_dot8_i32_i4 v9, v101, v108, v9
	s_waitcnt vmcnt(38)
	v_dot8_i32_i4 v11, v102, v75, 0
	s_nop 0
	v_lshl_add_u32 v5, v5, 4, v9
	v_dot8_i32_i4 v9, v102, v73, 0
	v_dot8_i32_i4 v9, v103, v77, v9
	v_dot8_i32_i4 v11, v103, v108, v11
	s_waitcnt vmcnt(37)
	v_dot8_i32_i4 v13, v98, v75, 0
	s_nop 0
	v_lshl_add_u32 v9, v9, 4, v11
	v_dot8_i32_i4 v11, v98, v73, 0
	v_dot8_i32_i4 v11, v99, v77, v11
	v_dot8_i32_i4 v13, v99, v108, v13
	s_waitcnt vmcnt(36)
	v_dot8_i32_i4 v15, v104, v75, 0
	v_dot8_i32_i4 v15, v105, v108, v15
	v_lshl_add_u32 v11, v11, 4, v13
	v_dot8_i32_i4 v13, v104, v73, 0
	v_dot8_i32_i4 v13, v105, v77, v13
	s_nop 1
	s_nop 0
	v_lshl_add_u32 v13, v13, 4, v15
	s_nop 0
	s_waitcnt vmcnt(35)
	v_dot8_i32_i4 v15, v94, v73, 0
	s_nop 1
	v_dot8_i32_i4 v17, v94, v75, 0
	v_dot8_i32_i4 v15, v95, v77, v15
	v_dot8_i32_i4 v17, v95, v108, v17
	s_waitcnt vmcnt(34)
	v_dot8_i32_i4 v19, v86, v75, 0
	s_nop 0
	v_lshl_add_u32 v15, v15, 4, v17
	v_dot8_i32_i4 v17, v86, v73, 0
	v_dot8_i32_i4 v17, v87, v77, v17
	v_dot8_i32_i4 v19, v87, v108, v19
	s_waitcnt vmcnt(33)
	v_dot8_i32_i4 v21, v84, v75, 0
	v_dot8_i32_i4 v21, v85, v108, v21
	v_lshl_add_u32 v17, v17, 4, v19
	v_dot8_i32_i4 v19, v84, v73, 0
	v_dot8_i32_i4 v19, v85, v77, v19
	s_nop 1
	s_nop 0
	v_lshl_add_u32 v19, v19, 4, v21
	s_waitcnt vmcnt(32)
	v_dot8_i32_i4 v21, v90, v73, 0
	v_dot8_i32_i4 v84, v90, v75, 0
	v_dot8_i32_i4 v21, v91, v77, v21
	v_dot8_i32_i4 v84, v91, v108, v84
	v_readlane_b32 s0, v18, 0
	s_nop 0
	s_nop 0
	v_lshl_add_u32 v21, v21, 4, v84
	s_waitcnt vmcnt(31)
	v_dot8_i32_i4 v84, v78, v73, 0
	v_dot8_i32_i4 v85, v78, v75, 0
	s_nop 0
	buffer_load_dwordx2 v[96:97], v192, s[52:55], s0 offen
	v_readlane_b32 s0, v18, 1
	v_dot8_i32_i4 v84, v79, v77, v84
	v_dot8_i32_i4 v85, v79, v108, v85
	s_nop 1
	s_nop 0
	buffer_load_dwordx2 v[88:89], v192, s[52:55], s0 offen
	v_readlane_b32 s0, v18, 2
	v_lshl_add_u32 v78, v84, 4, v85
	s_nop 1
	s_nop 1
	buffer_load_dwordx2 v[82:83], v192, s[52:55], s0 offen
	v_readlane_b32 s0, v18, 3
	s_waitcnt vmcnt(33)
	v_dot8_i32_i4 v79, v50, v73, 0
	s_nop 0
	s_nop 0
	s_nop 0
	buffer_load_dwordx2 v[92:93], v192, s[52:55], s0 offen
	v_readlane_b32 s0, v18, 4
	v_dot8_i32_i4 v84, v50, v75, 0
	v_dot8_i32_i4 v79, v51, v77, v79
	v_dot8_i32_i4 v84, v51, v108, v84
	s_nop 1
	buffer_load_dwordx2 v[80:81], v192, s[52:55], s0 offen
	v_readlane_b32 s0, v18, 5
	s_nop 0
	v_lshl_add_u32 v50, v79, 4, v84
	s_waitcnt vmcnt(34)
	v_dot8_i32_i4 v51, v48, v73, 0
	v_dot8_i32_i4 v79, v48, v75, 0
	s_nop 0
	buffer_load_dwordx2 v[52:53], v192, s[52:55], s0 offen
	v_readlane_b32 s0, v18, 6
	v_dot8_i32_i4 v51, v49, v77, v51
	v_dot8_i32_i4 v79, v49, v108, v79
	s_waitcnt vmcnt(34)
	v_dot8_i32_i4 v49, v54, v73, 0
	s_nop 0
	buffer_load_dwordx2 v[46:47], v192, s[52:55], s0 offen
	v_readlane_b32 s0, v18, 7
	v_lshl_add_u32 v48, v51, 4, v79
	v_dot8_i32_i4 v51, v54, v75, 0
	v_dot8_i32_i4 v49, v55, v77, v49
	s_nop 1
	buffer_load_dwordx2 v[56:57], v192, s[52:55], s0 offen
	v_readlane_b32 s0, v18, 8
	v_dot8_i32_i4 v51, v55, v108, v51
	s_waitcnt vmcnt(35)
	v_dot8_i32_i4 v54, v42, v75, 0
	v_dot8_i32_i4 v54, v43, v108, v54
	s_nop 0
	buffer_load_dwordx2 v[44:45], v192, s[52:55], s0 offen
	v_readlane_b32 s0, v18, 9
	v_lshl_add_u32 v49, v49, 4, v51
	v_dot8_i32_i4 v51, v42, v73, 0
	v_dot8_i32_i4 v51, v43, v77, v51
	s_nop 1
	buffer_load_dwordx2 v[36:37], v192, s[52:55], s0 offen
	v_readlane_b32 s0, v18, 10
	s_nop 0
	v_lshl_add_u32 v42, v51, 4, v54
	s_waitcnt vmcnt(36)
	v_dot8_i32_i4 v43, v34, v73, 0
	s_nop 1
	buffer_load_dwordx2 v[30:31], v192, s[52:55], s0 offen
	v_readlane_b32 s0, v18, 11
	v_dot8_i32_i4 v51, v34, v75, 0
	v_dot8_i32_i4 v43, v35, v77, v43
	v_dot8_i32_i4 v51, v35, v108, v51
	s_nop 1
	buffer_load_dwordx2 v[40:41], v192, s[52:55], s0 offen
	v_readlane_b32 s0, v18, 12
	s_nop 0
	v_lshl_add_u32 v34, v43, 4, v51
	s_waitcnt vmcnt(37)
	v_dot8_i32_i4 v35, v32, v73, 0
	v_dot8_i32_i4 v43, v32, v75, 0
	s_nop 0
	buffer_load_dwordx2 v[28:29], v192, s[52:55], s0 offen
	v_readlane_b32 s0, v18, 13
	v_dot8_i32_i4 v35, v33, v77, v35
	v_dot8_i32_i4 v43, v33, v108, v43
	s_waitcnt vmcnt(37)
	v_dot8_i32_i4 v33, v38, v73, 0
	s_nop 0
	buffer_load_dwordx2 v[24:25], v192, s[52:55], s0 offen
	v_readlane_b32 s0, v18, 14
	v_lshl_add_u32 v32, v35, 4, v43
	v_dot8_i32_i4 v35, v38, v75, 0
	v_dot8_i32_i4 v33, v39, v77, v33
	s_nop 1
	buffer_load_dwordx2 v[22:23], v192, s[52:55], s0 offen
	v_readlane_b32 s0, v18, 15
	v_dot8_i32_i4 v35, v39, v108, v35
	s_nop 0
	s_nop 2
	buffer_load_dwordx2 v[26:27], v192, s[52:55], s0 offen
	s_nop 0
	v_lshl_add_u32 v33, v33, 4, v35
	v_cndmask_b32_e64 v35, v9, v5, s[40:41]
	v_cndmask_b32_e64 v5, v5, v9, s[40:41]
	v_cndmask_b32_e64 v9, v13, v11, s[40:41]
	v_cndmask_b32_e64 v11, v11, v13, s[40:41]
	s_nop 1
	v_mov_b32_dpp v11, v11 quad_perm:[1,0,3,2] row_mask:0xf bank_mask:0xf
	v_cndmask_b32_e64 v13, v15, v17, s[40:41]
	s_nop 1
	v_mov_b32_dpp v13, v13 quad_perm:[1,0,3,2] row_mask:0xf bank_mask:0xf
	s_waitcnt lgkmcnt(0)
	v_add_u32_e32 v9, v9, v11
	v_cndmask_b32_e64 v11, v17, v15, s[40:41]
	v_cndmask_b32_e64 v15, v19, v21, s[40:41]
	s_nop 1
	v_mov_b32_dpp v15, v15 quad_perm:[1,0,3,2] row_mask:0xf bank_mask:0xf
	v_cndmask_b32_e64 v17, v78, v50, s[40:41]
	s_waitcnt lgkmcnt(0)
	v_add_u32_e32 v11, v11, v13
	v_cndmask_b32_e64 v13, v21, v19, s[40:41]
	s_nop 1
	v_mov_b32_dpp v17, v17 quad_perm:[1,0,3,2] row_mask:0xf bank_mask:0xf
	v_cndmask_b32_e64 v19, v48, v49, s[40:41]
	s_nop 1
	v_mov_b32_dpp v19, v19 quad_perm:[1,0,3,2] row_mask:0xf bank_mask:0xf
	v_cndmask_b32_e64 v21, v42, v34, s[40:41]
	s_nop 1
	v_mov_b32_dpp v21, v21 quad_perm:[1,0,3,2] row_mask:0xf bank_mask:0xf
	s_waitcnt lgkmcnt(0)
	v_add_u32_e32 v13, v13, v15
	v_cndmask_b32_e64 v15, v50, v78, s[40:41]
	s_waitcnt lgkmcnt(0)
	v_add_u32_e32 v15, v15, v17
	v_cndmask_b32_e64 v17, v49, v48, s[40:41]
	s_waitcnt lgkmcnt(0)
	v_add_u32_e32 v17, v17, v19
	v_cndmask_b32_e64 v19, v34, v42, s[40:41]
	s_nop 1
	v_mov_b32_dpp v5, v5 quad_perm:[1,0,3,2] row_mask:0xf bank_mask:0xf
	s_waitcnt lgkmcnt(0)
	v_add_u32_e32 v19, v19, v21
	v_cndmask_b32_e64 v21, v33, v32, s[40:41]
	v_cndmask_b32_e64 v32, v32, v33, s[40:41]
	s_nop 1
	v_mov_b32_dpp v32, v32 quad_perm:[1,0,3,2] row_mask:0xf bank_mask:0xf
	s_waitcnt lgkmcnt(0)
	v_add_u32_e32 v5, v35, v5
	s_waitcnt lgkmcnt(0)
	v_add_u32_e32 v21, v21, v32
	v_cndmask_b32_e64 v32, v9, v5, s[42:43]
	v_cndmask_b32_e64 v5, v5, v9, s[42:43]
	v_cndmask_b32_e64 v9, v13, v11, s[42:43]
	v_cndmask_b32_e64 v11, v11, v13, s[42:43]
	s_nop 1
	v_mov_b32_dpp v11, v11 quad_perm:[2,3,0,1] row_mask:0xf bank_mask:0xf
	v_cndmask_b32_e64 v13, v15, v17, s[42:43]
	s_nop 1
	v_mov_b32_dpp v13, v13 quad_perm:[2,3,0,1] row_mask:0xf bank_mask:0xf
	s_nop 1
	v_mov_b32_dpp v5, v5 quad_perm:[2,3,0,1] row_mask:0xf bank_mask:0xf
	s_waitcnt lgkmcnt(0)
	v_add_u32_e32 v9, v9, v11
	v_cndmask_b32_e64 v11, v17, v15, s[42:43]
	v_cndmask_b32_e64 v15, v19, v21, s[42:43]
	s_nop 1
	v_mov_b32_dpp v15, v15 quad_perm:[2,3,0,1] row_mask:0xf bank_mask:0xf
	s_waitcnt lgkmcnt(0)
	v_add_u32_e32 v11, v11, v13
	v_cndmask_b32_e64 v13, v21, v19, s[42:43]
	s_waitcnt lgkmcnt(0)
	v_add_u32_e32 v5, v32, v5
	s_waitcnt lgkmcnt(0)
	v_add_u32_e32 v13, v13, v15
	v_cndmask_b32_e64 v15, v9, v5, s[44:45]
	v_cndmask_b32_e64 v5, v5, v9, s[44:45]
	v_cndmask_b32_e64 v9, v13, v11, s[44:45]
	v_cndmask_b32_e64 v11, v11, v13, s[44:45]
	s_nop 1
	v_mov_b32_dpp v5, v5 row_half_mirror row_mask:0xf bank_mask:0xf
	s_nop 1
	v_mov_b32_dpp v5, v5 quad_perm:[3,2,1,0] row_mask:0xf bank_mask:0xf
	s_nop 1
	v_mov_b32_dpp v11, v11 row_half_mirror row_mask:0xf bank_mask:0xf
	s_nop 1
	v_mov_b32_dpp v11, v11 quad_perm:[3,2,1,0] row_mask:0xf bank_mask:0xf
	s_waitcnt lgkmcnt(0)
	v_add_u32_e32 v5, v15, v5
	s_waitcnt lgkmcnt(0)
	v_add_u32_e32 v9, v9, v11
	v_cndmask_b32_e64 v11, v9, v5, s[46:47]
	v_cndmask_b32_e64 v5, v5, v9, s[46:47]
	s_nop 1
	v_mov_b32_dpp v5, v5 row_ror:8 row_mask:0xf bank_mask:0xf
	s_waitcnt lgkmcnt(0)
	v_add_u32_e32 v5, v11, v5
	ds_swizzle_b32 v9, v5 offset:swizzle(SWAP,16)
	s_waitcnt lgkmcnt(0)
	v_add_u32_e32 v5, v5, v9
	ds_bpermute_b32 v9, v0, v5
	s_and_saveexec_b64 s[0:1], s[48:49]
	s_cbranch_execz .LBB0_671
	v_ashrrev_i32_e32 v21, 31, v20
	v_lshlrev_b64 v[20:21], 2, v[20:21]
	v_lshl_add_u64 v[32:33], s[8:9], 0, v[20:21]
	s_waitcnt vmcnt(39)
	v_mov_b32_e32 v11, v128
	v_lshl_add_u64 v[20:21], s[10:11], 0, v[20:21]
	s_waitcnt vmcnt(37)
	v_mov_b32_e32 v13, v144
	v_mov_b32_e32 v15, v136
	s_waitcnt lgkmcnt(0)
	v_add_u32_e32 v5, v5, v9
	v_cvt_f32_i32_e32 v5, v5
	v_mul_f32_e32 v5, v5, v11
	v_mul_f32_e32 v5, v3, v5
	v_mul_f32_e32 v11, 0x3d372713, v5
	v_mul_f32_e32 v11, v5, v11
	v_mul_f32_e32 v9, 0.5, v5
	v_fmac_f32_e32 v5, v5, v11
	v_mul_f32_e32 v5, 0x3f4c422a, v5
	v_add_f32_e32 v5, v5, v5
	v_mul_f32_e32 v5, 0x3fb8aa3b, v5
	v_exp_f32_e32 v5, v5
	s_nop 0
	v_add_f32_e32 v5, 1.0, v5
	v_rcp_f32_e32 v5, v5
	s_nop 0
	v_fma_f32 v5, v5, -2.0, 1.0
	v_add_f32_e32 v5, 1.0, v5
	v_mul_f32_e32 v5, v9, v5
	v_mul_f32_e32 v5, v13, v5
	v_mul_f32_e32 v5, v15, v5
	ds_write_b32 v109, v5
.LBB0_671:
	s_or_b64 exec, exec, s[0:1]
	v_readlane_b32 s0, v16, 0
	s_waitcnt lgkmcnt(0)
	s_waitcnt vmcnt(15)
	v_dot8_i32_i4 v5, v96, v73, 0
	v_dot8_i32_i4 v9, v96, v75, 0
	s_nop 0
	buffer_load_dwordx2 v[102:103], v192, s[52:55], s0 offen
	v_readlane_b32 s0, v16, 1
	v_dot8_i32_i4 v5, v97, v77, v5
	v_dot8_i32_i4 v9, v97, v108, v9
	s_waitcnt vmcnt(15)
	v_dot8_i32_i4 v11, v88, v75, 0
	s_nop 0
	buffer_load_dwordx2 v[98:99], v192, s[52:55], s0 offen
	v_readlane_b32 s0, v16, 2
	v_lshl_add_u32 v5, v5, 4, v9
	v_dot8_i32_i4 v9, v88, v73, 0
	v_dot8_i32_i4 v9, v89, v77, v9
	s_nop 1
	buffer_load_dwordx2 v[94:95], v192, s[52:55], s0 offen
	v_readlane_b32 s0, v16, 3
	v_dot8_i32_i4 v11, v89, v108, v11
	s_waitcnt vmcnt(16)
	v_dot8_i32_i4 v13, v82, v75, 0
	v_dot8_i32_i4 v13, v83, v108, v13
	s_nop 0
	buffer_load_dwordx2 v[100:101], v192, s[52:55], s0 offen
	v_readlane_b32 s0, v16, 4
	v_lshl_add_u32 v9, v9, 4, v11
	v_dot8_i32_i4 v11, v82, v73, 0
	v_dot8_i32_i4 v11, v83, v77, v11
	s_nop 1
	buffer_load_dwordx2 v[90:91], v192, s[52:55], s0 offen
	v_readlane_b32 s0, v16, 5
	s_nop 0
	v_lshl_add_u32 v11, v11, 4, v13
	s_waitcnt vmcnt(17)
	v_dot8_i32_i4 v13, v92, v73, 0
	s_nop 1
	buffer_load_dwordx2 v[84:85], v192, s[52:55], s0 offen
	v_readlane_b32 s0, v16, 6
	v_dot8_i32_i4 v15, v92, v75, 0
	v_dot8_i32_i4 v13, v93, v77, v13
	v_dot8_i32_i4 v15, v93, v108, v15
	s_nop 1
	buffer_load_dwordx2 v[78:79], v192, s[52:55], s0 offen
	v_readlane_b32 s0, v16, 7
	s_nop 0
	v_lshl_add_u32 v13, v13, 4, v15
	s_waitcnt vmcnt(18)
	v_dot8_i32_i4 v15, v80, v73, 0
	v_dot8_i32_i4 v17, v80, v75, 0
	s_nop 0
	buffer_load_dwordx2 v[86:87], v192, s[52:55], s0 offen
	v_readlane_b32 s0, v16, 8
	v_dot8_i32_i4 v15, v81, v77, v15
	v_dot8_i32_i4 v17, v81, v108, v17
	s_waitcnt vmcnt(18)
	v_dot8_i32_i4 v19, v52, v75, 0
	s_nop 0
	buffer_load_dwordx2 v[54:55], v192, s[52:55], s0 offen
	v_readlane_b32 s0, v16, 9
	v_lshl_add_u32 v15, v15, 4, v17
	v_dot8_i32_i4 v17, v52, v73, 0
	v_dot8_i32_i4 v17, v53, v77, v17
	s_nop 1
	buffer_load_dwordx2 v[48:49], v192, s[52:55], s0 offen
	v_readlane_b32 s0, v16, 10
	v_dot8_i32_i4 v19, v53, v108, v19
	s_waitcnt vmcnt(19)
	v_dot8_i32_i4 v52, v46, v75, 0
	v_dot8_i32_i4 v52, v47, v108, v52
	s_nop 0
	buffer_load_dwordx2 v[42:43], v192, s[52:55], s0 offen
	v_readlane_b32 s0, v16, 11
	v_lshl_add_u32 v17, v17, 4, v19
	v_dot8_i32_i4 v19, v46, v73, 0
	v_dot8_i32_i4 v19, v47, v77, v19
	s_nop 1
	buffer_load_dwordx2 v[50:51], v192, s[52:55], s0 offen
	v_readlane_b32 s0, v16, 12
	s_waitcnt vmcnt(20)
	v_dot8_i32_i4 v46, v56, v73, 0
	v_dot8_i32_i4 v47, v56, v75, 0
	s_nop 1
	buffer_load_dwordx2 v[38:39], v192, s[52:55], s0 offen
	v_readlane_b32 s0, v16, 13
	v_dot8_i32_i4 v46, v57, v77, v46
	v_dot8_i32_i4 v47, v57, v108, v47
	v_lshl_add_u32 v19, v19, 4, v52
	s_nop 1
	buffer_load_dwordx2 v[32:33], v192, s[52:55], s0 offen
	v_readlane_b32 s0, v16, 14
	v_lshl_add_u32 v46, v46, 4, v47
	s_waitcnt vmcnt(21)
	v_dot8_i32_i4 v47, v44, v73, 0
	v_dot8_i32_i4 v52, v44, v75, 0
	s_nop 0
	buffer_load_dwordx2 v[20:21], v192, s[52:55], s0 offen
	v_readlane_b32 s0, v16, 15
	v_dot8_i32_i4 v47, v45, v77, v47
	v_dot8_i32_i4 v52, v45, v108, v52
	s_waitcnt vmcnt(21)
	v_dot8_i32_i4 v45, v36, v73, 0
	s_nop 0
	buffer_load_dwordx2 v[34:35], v192, s[52:55], s0 offen
	v_lshl_add_u32 v44, v47, 4, v52
	v_dot8_i32_i4 v47, v36, v75, 0
	v_dot8_i32_i4 v45, v37, v77, v45
	v_dot8_i32_i4 v47, v37, v108, v47
	s_waitcnt vmcnt(21)
	v_dot8_i32_i4 v37, v30, v73, 0
	v_dot8_i32_i4 v37, v31, v77, v37
	v_lshl_add_u32 v36, v45, 4, v47
	v_dot8_i32_i4 v45, v30, v75, 0
	v_dot8_i32_i4 v45, v31, v108, v45
	s_waitcnt vmcnt(20)
	v_dot8_i32_i4 v31, v40, v73, 0
	v_dot8_i32_i4 v31, v41, v77, v31
	v_lshl_add_u32 v30, v37, 4, v45
	v_dot8_i32_i4 v37, v40, v75, 0
	v_dot8_i32_i4 v37, v41, v108, v37
	s_waitcnt vmcnt(19)
	v_dot8_i32_i4 v40, v28, v75, 0
	v_dot8_i32_i4 v40, v29, v108, v40
	v_lshl_add_u32 v31, v31, 4, v37
	v_dot8_i32_i4 v37, v28, v73, 0
	v_dot8_i32_i4 v37, v29, v77, v37
	s_waitcnt vmcnt(18)
	v_dot8_i32_i4 v29, v24, v73, 0
	v_dot8_i32_i4 v29, v25, v77, v29
	v_lshl_add_u32 v28, v37, 4, v40
	v_dot8_i32_i4 v37, v24, v75, 0
	v_dot8_i32_i4 v37, v25, v108, v37
	s_waitcnt vmcnt(17)
	v_dot8_i32_i4 v25, v22, v73, 0
	s_nop 0
	v_lshl_add_u32 v24, v29, 4, v37
	v_dot8_i32_i4 v29, v22, v75, 0
	v_dot8_i32_i4 v25, v23, v77, v25
	v_dot8_i32_i4 v29, v23, v108, v29
	s_nop 0
	s_nop 0
	s_nop 0
	v_lshl_add_u32 v22, v25, 4, v29
	s_waitcnt vmcnt(16)
	v_dot8_i32_i4 v23, v26, v73, 0
	v_dot8_i32_i4 v25, v26, v75, 0
	v_dot8_i32_i4 v23, v27, v77, v23
	v_dot8_i32_i4 v25, v27, v108, v25
	s_nop 0
	s_nop 0
	s_nop 0
	v_lshl_add_u32 v23, v23, 4, v25
	s_nop 1
	v_cndmask_b32_e64 v25, v9, v5, s[40:41]
	v_cndmask_b32_e64 v5, v5, v9, s[40:41]
	v_cndmask_b32_e64 v9, v13, v11, s[40:41]
	v_cndmask_b32_e64 v11, v11, v13, s[40:41]
	s_nop 1
	v_mov_b32_dpp v11, v11 quad_perm:[1,0,3,2] row_mask:0xf bank_mask:0xf
	v_cndmask_b32_e64 v13, v15, v17, s[40:41]
	s_nop 1
	v_mov_b32_dpp v13, v13 quad_perm:[1,0,3,2] row_mask:0xf bank_mask:0xf
	s_waitcnt lgkmcnt(0)
	v_add_u32_e32 v9, v9, v11
	v_cndmask_b32_e64 v11, v17, v15, s[40:41]
	v_cndmask_b32_e64 v15, v19, v46, s[40:41]
	s_nop 1
	v_mov_b32_dpp v15, v15 quad_perm:[1,0,3,2] row_mask:0xf bank_mask:0xf
	v_cndmask_b32_e64 v17, v44, v36, s[40:41]
	s_waitcnt lgkmcnt(0)
	v_add_u32_e32 v11, v11, v13
	v_cndmask_b32_e64 v13, v46, v19, s[40:41]
	s_nop 1
	v_mov_b32_dpp v17, v17 quad_perm:[1,0,3,2] row_mask:0xf bank_mask:0xf
	v_cndmask_b32_e64 v19, v30, v31, s[40:41]
	s_nop 1
	v_mov_b32_dpp v19, v19 quad_perm:[1,0,3,2] row_mask:0xf bank_mask:0xf
	s_waitcnt lgkmcnt(0)
	v_add_u32_e32 v13, v13, v15
	v_cndmask_b32_e64 v15, v36, v44, s[40:41]
	s_waitcnt lgkmcnt(0)
	v_add_u32_e32 v15, v15, v17
	v_cndmask_b32_e64 v17, v31, v30, s[40:41]
	s_waitcnt lgkmcnt(0)
	v_add_u32_e32 v17, v17, v19
	v_cndmask_b32_e64 v19, v24, v28, s[40:41]
	v_cndmask_b32_e64 v24, v28, v24, s[40:41]
	s_nop 1
	v_mov_b32_dpp v5, v5 quad_perm:[1,0,3,2] row_mask:0xf bank_mask:0xf
	s_nop 1
	v_mov_b32_dpp v24, v24 quad_perm:[1,0,3,2] row_mask:0xf bank_mask:0xf
	s_waitcnt lgkmcnt(0)
	v_add_u32_e32 v5, v25, v5
	s_waitcnt lgkmcnt(0)
	v_add_u32_e32 v19, v19, v24
	v_cndmask_b32_e64 v24, v23, v22, s[40:41]
	v_cndmask_b32_e64 v22, v22, v23, s[40:41]
	s_nop 1
	v_mov_b32_dpp v22, v22 quad_perm:[1,0,3,2] row_mask:0xf bank_mask:0xf
	v_cndmask_b32_e64 v23, v9, v5, s[42:43]
	v_cndmask_b32_e64 v5, v5, v9, s[42:43]
	v_cndmask_b32_e64 v9, v13, v11, s[42:43]
	v_cndmask_b32_e64 v11, v11, v13, s[42:43]
	s_nop 1
	v_mov_b32_dpp v11, v11 quad_perm:[2,3,0,1] row_mask:0xf bank_mask:0xf
	s_waitcnt lgkmcnt(0)
	v_add_u32_e32 v22, v24, v22
	v_cndmask_b32_e64 v13, v15, v17, s[42:43]
	s_nop 1
	v_mov_b32_dpp v13, v13 quad_perm:[2,3,0,1] row_mask:0xf bank_mask:0xf
	s_nop 1
	v_mov_b32_dpp v5, v5 quad_perm:[2,3,0,1] row_mask:0xf bank_mask:0xf
	s_waitcnt lgkmcnt(0)
	v_add_u32_e32 v9, v9, v11
	v_cndmask_b32_e64 v11, v17, v15, s[42:43]
	v_cndmask_b32_e64 v15, v19, v22, s[42:43]
	s_nop 1
	v_mov_b32_dpp v15, v15 quad_perm:[2,3,0,1] row_mask:0xf bank_mask:0xf
	s_waitcnt lgkmcnt(0)
	v_add_u32_e32 v11, v11, v13
	v_cndmask_b32_e64 v13, v22, v19, s[42:43]
	s_waitcnt lgkmcnt(0)
	v_add_u32_e32 v5, v23, v5
	s_waitcnt lgkmcnt(0)
	v_add_u32_e32 v13, v13, v15
	v_cndmask_b32_e64 v15, v9, v5, s[44:45]
	v_cndmask_b32_e64 v5, v5, v9, s[44:45]
	v_cndmask_b32_e64 v9, v13, v11, s[44:45]
	v_cndmask_b32_e64 v11, v11, v13, s[44:45]
	s_nop 1
	v_mov_b32_dpp v5, v5 row_half_mirror row_mask:0xf bank_mask:0xf
	s_nop 1
	v_mov_b32_dpp v5, v5 quad_perm:[3,2,1,0] row_mask:0xf bank_mask:0xf
	s_nop 1
	v_mov_b32_dpp v11, v11 row_half_mirror row_mask:0xf bank_mask:0xf
	s_nop 1
	v_mov_b32_dpp v11, v11 quad_perm:[3,2,1,0] row_mask:0xf bank_mask:0xf
	s_waitcnt lgkmcnt(0)
	v_add_u32_e32 v5, v15, v5
	s_waitcnt lgkmcnt(0)
	v_add_u32_e32 v9, v9, v11
	v_cndmask_b32_e64 v11, v9, v5, s[46:47]
	v_cndmask_b32_e64 v5, v5, v9, s[46:47]
	s_nop 1
	v_mov_b32_dpp v5, v5 row_ror:8 row_mask:0xf bank_mask:0xf
	s_waitcnt lgkmcnt(0)
	v_add_u32_e32 v5, v11, v5
	ds_swizzle_b32 v9, v5 offset:swizzle(SWAP,16)
	s_waitcnt lgkmcnt(0)
	v_add_u32_e32 v5, v5, v9
	ds_bpermute_b32 v9, v0, v5
	s_and_saveexec_b64 s[0:1], s[48:49]
	s_cbranch_execz .LBB0_673
	v_ashrrev_i32_e32 v19, 31, v18
	v_lshlrev_b64 v[18:19], 2, v[18:19]
	v_lshl_add_u64 v[22:23], s[8:9], 0, v[18:19]
	v_mov_b32_e32 v11, v129
	v_lshl_add_u64 v[18:19], s[10:11], 0, v[18:19]
	v_mov_b32_e32 v13, v145
	v_mov_b32_e32 v15, v137
	s_waitcnt lgkmcnt(0)
	v_add_u32_e32 v5, v5, v9
	v_cvt_f32_i32_e32 v5, v5
	v_mul_f32_e32 v5, v5, v11
	v_mul_f32_e32 v5, v3, v5
	v_mul_f32_e32 v11, 0x3d372713, v5
	v_mul_f32_e32 v11, v5, v11
	v_mul_f32_e32 v9, 0.5, v5
	v_fmac_f32_e32 v5, v5, v11
	v_mul_f32_e32 v5, 0x3f4c422a, v5
	v_add_f32_e32 v5, v5, v5
	v_mul_f32_e32 v5, 0x3fb8aa3b, v5
	v_exp_f32_e32 v5, v5
	s_nop 0
	v_add_f32_e32 v5, 1.0, v5
	v_rcp_f32_e32 v5, v5
	s_nop 0
	v_fma_f32 v5, v5, -2.0, 1.0
	v_add_f32_e32 v5, 1.0, v5
	v_mul_f32_e32 v5, v9, v5
	v_mul_f32_e32 v5, v13, v5
	v_mul_f32_e32 v5, v15, v5
	ds_write_b32 v109, v5 offset:64
.LBB0_673:
	s_or_b64 exec, exec, s[0:1]
	v_readlane_b32 s0, v14, 0
	s_waitcnt lgkmcnt(0)
	s_waitcnt vmcnt(15)
	v_dot8_i32_i4 v5, v102, v73, 0
	v_dot8_i32_i4 v9, v102, v75, 0
	s_nop 0
	buffer_load_dwordx2 v[96:97], v192, s[52:55], s0 offen
	v_readlane_b32 s0, v14, 1
	v_dot8_i32_i4 v5, v103, v77, v5
	v_dot8_i32_i4 v9, v103, v108, v9
	s_waitcnt vmcnt(15)
	v_dot8_i32_i4 v11, v98, v75, 0
	s_nop 0
	buffer_load_dwordx2 v[104:105], v192, s[52:55], s0 offen
	v_readlane_b32 s0, v14, 2
	v_lshl_add_u32 v5, v5, 4, v9
	v_dot8_i32_i4 v9, v98, v73, 0
	v_dot8_i32_i4 v9, v99, v77, v9
	s_nop 1
	buffer_load_dwordx2 v[92:93], v192, s[52:55], s0 offen
	v_readlane_b32 s0, v14, 3
	v_dot8_i32_i4 v11, v99, v108, v11
	s_waitcnt vmcnt(16)
	v_dot8_i32_i4 v13, v94, v75, 0
	v_dot8_i32_i4 v13, v95, v108, v13
	s_nop 0
	buffer_load_dwordx2 v[106:107], v192, s[52:55], s0 offen
	v_readlane_b32 s0, v14, 4
	v_lshl_add_u32 v9, v9, 4, v11
	v_dot8_i32_i4 v11, v94, v73, 0
	v_dot8_i32_i4 v11, v95, v77, v11
	s_nop 1
	buffer_load_dwordx2 v[88:89], v192, s[52:55], s0 offen
	v_readlane_b32 s0, v14, 5
	s_nop 0
	v_lshl_add_u32 v11, v11, 4, v13
	s_waitcnt vmcnt(17)
	v_dot8_i32_i4 v13, v100, v73, 0
	s_nop 1
	buffer_load_dwordx2 v[80:81], v192, s[52:55], s0 offen
	v_readlane_b32 s0, v14, 6
	v_dot8_i32_i4 v15, v100, v75, 0
	v_dot8_i32_i4 v13, v101, v77, v13
	v_dot8_i32_i4 v15, v101, v108, v15
	s_nop 1
	buffer_load_dwordx2 v[56:57], v192, s[52:55], s0 offen
	v_readlane_b32 s0, v14, 7
	s_nop 0
	v_lshl_add_u32 v13, v13, 4, v15
	s_waitcnt vmcnt(18)
	v_dot8_i32_i4 v15, v90, v73, 0
	v_dot8_i32_i4 v17, v90, v75, 0
	s_nop 0
	buffer_load_dwordx2 v[82:83], v192, s[52:55], s0 offen
	v_readlane_b32 s0, v14, 8
	v_dot8_i32_i4 v15, v91, v77, v15
	v_dot8_i32_i4 v17, v91, v108, v17
	s_waitcnt vmcnt(18)
	v_dot8_i32_i4 v22, v84, v75, 0
	s_nop 0
	buffer_load_dwordx2 v[52:53], v192, s[52:55], s0 offen
	v_readlane_b32 s0, v14, 9
	v_lshl_add_u32 v15, v15, 4, v17
	v_dot8_i32_i4 v17, v84, v73, 0
	v_dot8_i32_i4 v17, v85, v77, v17
	s_nop 1
	buffer_load_dwordx2 v[44:45], v192, s[52:55], s0 offen
	v_readlane_b32 s0, v14, 10
	v_dot8_i32_i4 v22, v85, v108, v22
	s_waitcnt vmcnt(19)
	v_dot8_i32_i4 v23, v78, v75, 0
	v_dot8_i32_i4 v23, v79, v108, v23
	s_nop 0
	buffer_load_dwordx2 v[40:41], v192, s[52:55], s0 offen
	v_readlane_b32 s0, v14, 11
	v_lshl_add_u32 v17, v17, 4, v22
	v_dot8_i32_i4 v22, v78, v73, 0
	v_dot8_i32_i4 v22, v79, v77, v22
	s_nop 1
	buffer_load_dwordx2 v[46:47], v192, s[52:55], s0 offen
	v_readlane_b32 s0, v14, 12
	s_nop 0
	v_lshl_add_u32 v22, v22, 4, v23
	s_waitcnt vmcnt(20)
	v_dot8_i32_i4 v23, v86, v73, 0
	s_nop 1
	buffer_load_dwordx2 v[36:37], v192, s[52:55], s0 offen
	v_readlane_b32 s0, v14, 13
	v_dot8_i32_i4 v26, v86, v75, 0
	v_dot8_i32_i4 v23, v87, v77, v23
	v_dot8_i32_i4 v26, v87, v108, v26
	s_nop 1
	buffer_load_dwordx2 v[24:25], v192, s[52:55], s0 offen
	v_readlane_b32 s0, v14, 14
	s_nop 0
	v_lshl_add_u32 v23, v23, 4, v26
	s_waitcnt vmcnt(21)
	v_dot8_i32_i4 v26, v54, v73, 0
	v_dot8_i32_i4 v27, v54, v75, 0
	s_nop 0
	buffer_load_dwordx2 v[18:19], v192, s[52:55], s0 offen
	v_readlane_b32 s0, v14, 15
	v_dot8_i32_i4 v26, v55, v77, v26
	v_dot8_i32_i4 v27, v55, v108, v27
	s_waitcnt vmcnt(21)
	v_dot8_i32_i4 v30, v48, v75, 0
	s_nop 0
	buffer_load_dwordx2 v[28:29], v192, s[52:55], s0 offen
	v_lshl_add_u32 v26, v26, 4, v27
	v_dot8_i32_i4 v27, v48, v73, 0
	v_dot8_i32_i4 v27, v49, v77, v27
	v_dot8_i32_i4 v30, v49, v108, v30
	s_waitcnt vmcnt(21)
	v_dot8_i32_i4 v31, v42, v75, 0
	v_dot8_i32_i4 v31, v43, v108, v31
	v_lshl_add_u32 v27, v27, 4, v30
	v_dot8_i32_i4 v30, v42, v73, 0
	v_dot8_i32_i4 v30, v43, v77, v30
	s_waitcnt vmcnt(20)
	v_dot8_i32_i4 v42, v50, v75, 0
	v_dot8_i32_i4 v42, v51, v108, v42
	v_lshl_add_u32 v30, v30, 4, v31
	v_dot8_i32_i4 v31, v50, v73, 0
	v_dot8_i32_i4 v31, v51, v77, v31
	s_waitcnt vmcnt(19)
	v_dot8_i32_i4 v43, v38, v75, 0
	v_dot8_i32_i4 v43, v39, v108, v43
	v_lshl_add_u32 v31, v31, 4, v42
	v_dot8_i32_i4 v42, v38, v73, 0
	v_dot8_i32_i4 v42, v39, v77, v42
	s_waitcnt vmcnt(18)
	v_dot8_i32_i4 v39, v32, v73, 0
	v_dot8_i32_i4 v39, v33, v77, v39
	v_lshl_add_u32 v38, v42, 4, v43
	v_dot8_i32_i4 v42, v32, v75, 0
	v_dot8_i32_i4 v42, v33, v108, v42
	s_waitcnt vmcnt(17)
	v_dot8_i32_i4 v33, v20, v73, 0
	s_nop 0
	v_lshl_add_u32 v32, v39, 4, v42
	v_dot8_i32_i4 v39, v20, v75, 0
	v_dot8_i32_i4 v33, v21, v77, v33
	v_dot8_i32_i4 v39, v21, v108, v39
	s_nop 0
	s_nop 0
	s_nop 0
	v_lshl_add_u32 v20, v33, 4, v39
	s_waitcnt vmcnt(16)
	v_dot8_i32_i4 v21, v34, v73, 0
	v_dot8_i32_i4 v33, v34, v75, 0
	v_dot8_i32_i4 v21, v35, v77, v21
	v_dot8_i32_i4 v33, v35, v108, v33
	s_nop 0
	s_nop 0
	s_nop 0
	v_lshl_add_u32 v21, v21, 4, v33
	s_nop 1
	v_cndmask_b32_e64 v33, v9, v5, s[40:41]
	v_cndmask_b32_e64 v5, v5, v9, s[40:41]
	v_cndmask_b32_e64 v9, v13, v11, s[40:41]
	v_cndmask_b32_e64 v11, v11, v13, s[40:41]
	s_nop 1
	v_mov_b32_dpp v11, v11 quad_perm:[1,0,3,2] row_mask:0xf bank_mask:0xf
	v_cndmask_b32_e64 v13, v15, v17, s[40:41]
	s_nop 1
	v_mov_b32_dpp v13, v13 quad_perm:[1,0,3,2] row_mask:0xf bank_mask:0xf
	s_waitcnt lgkmcnt(0)
	v_add_u32_e32 v9, v9, v11
	v_cndmask_b32_e64 v11, v17, v15, s[40:41]
	v_cndmask_b32_e64 v15, v22, v23, s[40:41]
	s_nop 1
	v_mov_b32_dpp v15, v15 quad_perm:[1,0,3,2] row_mask:0xf bank_mask:0xf
	v_cndmask_b32_e64 v17, v26, v27, s[40:41]
	s_waitcnt lgkmcnt(0)
	v_add_u32_e32 v11, v11, v13
	v_cndmask_b32_e64 v13, v23, v22, s[40:41]
	s_nop 1
	v_mov_b32_dpp v17, v17 quad_perm:[1,0,3,2] row_mask:0xf bank_mask:0xf
	v_cndmask_b32_e64 v22, v30, v31, s[40:41]
	s_nop 1
	v_mov_b32_dpp v22, v22 quad_perm:[1,0,3,2] row_mask:0xf bank_mask:0xf
	v_cndmask_b32_e64 v23, v38, v32, s[40:41]
	s_nop 1
	v_mov_b32_dpp v5, v5 quad_perm:[1,0,3,2] row_mask:0xf bank_mask:0xf
	s_nop 1
	v_mov_b32_dpp v23, v23 quad_perm:[1,0,3,2] row_mask:0xf bank_mask:0xf
	s_waitcnt lgkmcnt(0)
	v_add_u32_e32 v13, v13, v15
	v_cndmask_b32_e64 v15, v27, v26, s[40:41]
	s_waitcnt lgkmcnt(0)
	v_add_u32_e32 v15, v15, v17
	v_cndmask_b32_e64 v17, v31, v30, s[40:41]
	s_waitcnt lgkmcnt(0)
	v_add_u32_e32 v17, v17, v22
	v_cndmask_b32_e64 v22, v32, v38, s[40:41]
	s_waitcnt lgkmcnt(0)
	v_add_u32_e32 v5, v33, v5
	s_waitcnt lgkmcnt(0)
	v_add_u32_e32 v22, v22, v23
	v_cndmask_b32_e64 v23, v21, v20, s[40:41]
	v_cndmask_b32_e64 v20, v20, v21, s[40:41]
	s_nop 1
	v_mov_b32_dpp v20, v20 quad_perm:[1,0,3,2] row_mask:0xf bank_mask:0xf
	v_cndmask_b32_e64 v21, v9, v5, s[42:43]
	v_cndmask_b32_e64 v5, v5, v9, s[42:43]
	v_cndmask_b32_e64 v9, v13, v11, s[42:43]
	v_cndmask_b32_e64 v11, v11, v13, s[42:43]
	s_nop 1
	v_mov_b32_dpp v11, v11 quad_perm:[2,3,0,1] row_mask:0xf bank_mask:0xf
	s_waitcnt lgkmcnt(0)
	v_add_u32_e32 v20, v23, v20
	v_cndmask_b32_e64 v13, v15, v17, s[42:43]
	s_nop 1
	v_mov_b32_dpp v13, v13 quad_perm:[2,3,0,1] row_mask:0xf bank_mask:0xf
	s_nop 1
	v_mov_b32_dpp v5, v5 quad_perm:[2,3,0,1] row_mask:0xf bank_mask:0xf
	s_waitcnt lgkmcnt(0)
	v_add_u32_e32 v9, v9, v11
	v_cndmask_b32_e64 v11, v17, v15, s[42:43]
	v_cndmask_b32_e64 v15, v22, v20, s[42:43]
	s_nop 1
	v_mov_b32_dpp v15, v15 quad_perm:[2,3,0,1] row_mask:0xf bank_mask:0xf
	s_waitcnt lgkmcnt(0)
	v_add_u32_e32 v11, v11, v13
	v_cndmask_b32_e64 v13, v20, v22, s[42:43]
	s_waitcnt lgkmcnt(0)
	v_add_u32_e32 v5, v21, v5
	s_waitcnt lgkmcnt(0)
	v_add_u32_e32 v13, v13, v15
	v_cndmask_b32_e64 v15, v9, v5, s[44:45]
	v_cndmask_b32_e64 v5, v5, v9, s[44:45]
	v_cndmask_b32_e64 v9, v13, v11, s[44:45]
	v_cndmask_b32_e64 v11, v11, v13, s[44:45]
	s_nop 1
	v_mov_b32_dpp v5, v5 row_half_mirror row_mask:0xf bank_mask:0xf
	s_nop 1
	v_mov_b32_dpp v5, v5 quad_perm:[3,2,1,0] row_mask:0xf bank_mask:0xf
	s_nop 1
	v_mov_b32_dpp v11, v11 row_half_mirror row_mask:0xf bank_mask:0xf
	s_nop 1
	v_mov_b32_dpp v11, v11 quad_perm:[3,2,1,0] row_mask:0xf bank_mask:0xf
	s_waitcnt lgkmcnt(0)
	v_add_u32_e32 v5, v15, v5
	s_waitcnt lgkmcnt(0)
	v_add_u32_e32 v9, v9, v11
	v_cndmask_b32_e64 v11, v9, v5, s[46:47]
	v_cndmask_b32_e64 v5, v5, v9, s[46:47]
	s_nop 1
	v_mov_b32_dpp v5, v5 row_ror:8 row_mask:0xf bank_mask:0xf
	s_waitcnt lgkmcnt(0)
	v_add_u32_e32 v5, v11, v5
	ds_swizzle_b32 v9, v5 offset:swizzle(SWAP,16)
	s_waitcnt lgkmcnt(0)
	v_add_u32_e32 v5, v5, v9
	ds_bpermute_b32 v9, v0, v5
	s_and_saveexec_b64 s[0:1], s[48:49]
	s_cbranch_execz .LBB0_675
	v_ashrrev_i32_e32 v17, 31, v16
	v_lshlrev_b64 v[16:17], 2, v[16:17]
	v_lshl_add_u64 v[20:21], s[8:9], 0, v[16:17]
	v_mov_b32_e32 v11, v130
	v_lshl_add_u64 v[16:17], s[10:11], 0, v[16:17]
	v_mov_b32_e32 v13, v146
	v_mov_b32_e32 v15, v138
	s_waitcnt lgkmcnt(0)
	v_add_u32_e32 v5, v5, v9
	v_cvt_f32_i32_e32 v5, v5
	v_mul_f32_e32 v5, v5, v11
	v_mul_f32_e32 v5, v3, v5
	v_mul_f32_e32 v11, 0x3d372713, v5
	v_mul_f32_e32 v11, v5, v11
	v_mul_f32_e32 v9, 0.5, v5
	v_fmac_f32_e32 v5, v5, v11
	v_mul_f32_e32 v5, 0x3f4c422a, v5
	v_add_f32_e32 v5, v5, v5
	v_mul_f32_e32 v5, 0x3fb8aa3b, v5
	v_exp_f32_e32 v5, v5
	s_nop 0
	v_add_f32_e32 v5, 1.0, v5
	v_rcp_f32_e32 v5, v5
	s_nop 0
	v_fma_f32 v5, v5, -2.0, 1.0
	v_add_f32_e32 v5, 1.0, v5
	v_mul_f32_e32 v5, v9, v5
	v_mul_f32_e32 v5, v13, v5
	v_mul_f32_e32 v5, v15, v5
	ds_write_b32 v109, v5 offset:128
.LBB0_675:
	s_or_b64 exec, exec, s[0:1]
	v_readlane_b32 s0, v12, 0
	s_waitcnt lgkmcnt(0)
	s_waitcnt vmcnt(15)
	v_dot8_i32_i4 v5, v96, v73, 0
	v_dot8_i32_i4 v9, v96, v75, 0
	s_nop 0
	buffer_load_dwordx2 v[94:95], v192, s[52:55], s0 offen
	v_readlane_b32 s0, v12, 1
	v_dot8_i32_i4 v5, v97, v77, v5
	v_dot8_i32_i4 v9, v97, v108, v9
	s_waitcnt vmcnt(15)
	v_dot8_i32_i4 v11, v104, v75, 0
	s_nop 0
	buffer_load_dwordx2 v[86:87], v192, s[52:55], s0 offen
	v_readlane_b32 s0, v12, 2
	v_lshl_add_u32 v5, v5, 4, v9
	v_dot8_i32_i4 v9, v104, v73, 0
	v_dot8_i32_i4 v9, v105, v77, v9
	s_nop 1
	buffer_load_dwordx2 v[84:85], v192, s[52:55], s0 offen
	v_readlane_b32 s0, v12, 3
	v_dot8_i32_i4 v11, v105, v108, v11
	s_waitcnt vmcnt(16)
	v_dot8_i32_i4 v13, v92, v75, 0
	v_dot8_i32_i4 v13, v93, v108, v13
	s_nop 0
	buffer_load_dwordx2 v[90:91], v192, s[52:55], s0 offen
	v_readlane_b32 s0, v12, 4
	v_lshl_add_u32 v9, v9, 4, v11
	v_dot8_i32_i4 v11, v92, v73, 0
	v_dot8_i32_i4 v11, v93, v77, v11
	s_nop 1
	buffer_load_dwordx2 v[78:79], v192, s[52:55], s0 offen
	v_readlane_b32 s0, v12, 5
	s_nop 0
	v_lshl_add_u32 v11, v11, 4, v13
	s_waitcnt vmcnt(17)
	v_dot8_i32_i4 v13, v106, v73, 0
	s_nop 1
	buffer_load_dwordx2 v[50:51], v192, s[52:55], s0 offen
	v_readlane_b32 s0, v12, 6
	v_dot8_i32_i4 v15, v106, v75, 0
	v_dot8_i32_i4 v13, v107, v77, v13
	v_dot8_i32_i4 v15, v107, v108, v15
	s_nop 1
	buffer_load_dwordx2 v[48:49], v192, s[52:55], s0 offen
	v_readlane_b32 s0, v12, 7
	s_nop 0
	v_lshl_add_u32 v13, v13, 4, v15
	s_waitcnt vmcnt(18)
	v_dot8_i32_i4 v15, v88, v73, 0
	v_dot8_i32_i4 v32, v88, v75, 0
	s_nop 0
	buffer_load_dwordx2 v[54:55], v192, s[52:55], s0 offen
	v_readlane_b32 s0, v12, 8
	v_dot8_i32_i4 v15, v89, v77, v15
	v_dot8_i32_i4 v32, v89, v108, v32
	s_waitcnt vmcnt(18)
	v_dot8_i32_i4 v33, v80, v75, 0
	s_nop 0
	buffer_load_dwordx2 v[42:43], v192, s[52:55], s0 offen
	v_readlane_b32 s0, v12, 9
	v_lshl_add_u32 v15, v15, 4, v32
	v_dot8_i32_i4 v32, v80, v73, 0
	v_dot8_i32_i4 v32, v81, v77, v32
	s_nop 1
	buffer_load_dwordx2 v[34:35], v192, s[52:55], s0 offen
	v_readlane_b32 s0, v12, 10
	v_dot8_i32_i4 v33, v81, v108, v33
	s_waitcnt vmcnt(19)
	v_dot8_i32_i4 v80, v56, v75, 0
	v_dot8_i32_i4 v80, v57, v108, v80
	s_nop 0
	buffer_load_dwordx2 v[30:31], v192, s[52:55], s0 offen
	v_readlane_b32 s0, v12, 11
	v_lshl_add_u32 v32, v32, 4, v33
	v_dot8_i32_i4 v33, v56, v73, 0
	v_dot8_i32_i4 v33, v57, v77, v33
	s_nop 1
	buffer_load_dwordx2 v[38:39], v192, s[52:55], s0 offen
	v_readlane_b32 s0, v12, 12
	s_waitcnt vmcnt(20)
	v_dot8_i32_i4 v56, v82, v73, 0
	v_dot8_i32_i4 v57, v82, v75, 0
	s_nop 1
	buffer_load_dwordx2 v[26:27], v192, s[52:55], s0 offen
	v_readlane_b32 s0, v12, 13
	v_dot8_i32_i4 v56, v83, v77, v56
	v_dot8_i32_i4 v57, v83, v108, v57
	v_lshl_add_u32 v33, v33, 4, v80
	s_nop 1
	buffer_load_dwordx2 v[20:21], v192, s[52:55], s0 offen
	v_readlane_b32 s0, v12, 14
	v_lshl_add_u32 v56, v56, 4, v57
	s_waitcnt vmcnt(21)
	v_dot8_i32_i4 v57, v52, v73, 0
	v_dot8_i32_i4 v80, v52, v75, 0
	s_nop 0
	buffer_load_dwordx2 v[16:17], v192, s[52:55], s0 offen
	v_readlane_b32 s0, v12, 15
	v_dot8_i32_i4 v57, v53, v77, v57
	v_dot8_i32_i4 v80, v53, v108, v80
	s_waitcnt vmcnt(21)
	v_dot8_i32_i4 v53, v44, v73, 0
	s_nop 0
	buffer_load_dwordx2 v[22:23], v192, s[52:55], s0 offen
	v_lshl_add_u32 v52, v57, 4, v80
	v_dot8_i32_i4 v57, v44, v75, 0
	v_dot8_i32_i4 v53, v45, v77, v53
	v_dot8_i32_i4 v57, v45, v108, v57
	s_waitcnt vmcnt(21)
	v_dot8_i32_i4 v45, v40, v73, 0
	v_dot8_i32_i4 v45, v41, v77, v45
	v_lshl_add_u32 v44, v53, 4, v57
	v_dot8_i32_i4 v53, v40, v75, 0
	v_dot8_i32_i4 v53, v41, v108, v53
	s_waitcnt vmcnt(20)
	v_dot8_i32_i4 v41, v46, v73, 0
	v_dot8_i32_i4 v41, v47, v77, v41
	v_lshl_add_u32 v40, v45, 4, v53
	v_dot8_i32_i4 v45, v46, v75, 0
	v_dot8_i32_i4 v45, v47, v108, v45
	s_waitcnt vmcnt(19)
	v_dot8_i32_i4 v46, v36, v75, 0
	v_dot8_i32_i4 v46, v37, v108, v46
	v_lshl_add_u32 v41, v41, 4, v45
	v_dot8_i32_i4 v45, v36, v73, 0
	v_dot8_i32_i4 v45, v37, v77, v45
	s_waitcnt vmcnt(18)
	v_dot8_i32_i4 v37, v24, v73, 0
	v_dot8_i32_i4 v37, v25, v77, v37
	v_lshl_add_u32 v36, v45, 4, v46
	v_dot8_i32_i4 v45, v24, v75, 0
	v_dot8_i32_i4 v45, v25, v108, v45
	s_waitcnt vmcnt(17)
	v_dot8_i32_i4 v25, v18, v73, 0
	s_nop 0
	v_lshl_add_u32 v24, v37, 4, v45
	v_dot8_i32_i4 v37, v18, v75, 0
	v_dot8_i32_i4 v25, v19, v77, v25
	v_dot8_i32_i4 v37, v19, v108, v37
	s_waitcnt vmcnt(16)
	v_dot8_i32_i4 v19, v28, v73, 0
	v_dot8_i32_i4 v19, v29, v77, v19
	v_lshl_add_u32 v18, v25, 4, v37
	v_dot8_i32_i4 v25, v28, v75, 0
	v_dot8_i32_i4 v25, v29, v108, v25
	s_nop 1
	s_nop 0
	v_lshl_add_u32 v19, v19, 4, v25
	s_nop 0
	v_cndmask_b32_e64 v25, v9, v5, s[40:41]
	v_cndmask_b32_e64 v5, v5, v9, s[40:41]
	v_cndmask_b32_e64 v9, v13, v11, s[40:41]
	v_cndmask_b32_e64 v11, v11, v13, s[40:41]
	s_nop 1
	v_mov_b32_dpp v11, v11 quad_perm:[1,0,3,2] row_mask:0xf bank_mask:0xf
	s_nop 1
	v_mov_b32_dpp v5, v5 quad_perm:[1,0,3,2] row_mask:0xf bank_mask:0xf
	v_cndmask_b32_e64 v13, v15, v32, s[40:41]
	s_waitcnt lgkmcnt(0)
	v_add_u32_e32 v9, v9, v11
	v_cndmask_b32_e64 v11, v32, v15, s[40:41]
	s_nop 1
	v_mov_b32_dpp v13, v13 quad_perm:[1,0,3,2] row_mask:0xf bank_mask:0xf
	v_cndmask_b32_e64 v15, v33, v56, s[40:41]
	s_waitcnt lgkmcnt(0)
	v_add_u32_e32 v5, v25, v5
	s_nop 1
	v_mov_b32_dpp v15, v15 quad_perm:[1,0,3,2] row_mask:0xf bank_mask:0xf
	v_cndmask_b32_e64 v25, v52, v44, s[40:41]
	s_nop 1
	v_mov_b32_dpp v25, v25 quad_perm:[1,0,3,2] row_mask:0xf bank_mask:0xf
	v_cndmask_b32_e64 v28, v40, v41, s[40:41]
	s_nop 1
	v_mov_b32_dpp v28, v28 quad_perm:[1,0,3,2] row_mask:0xf bank_mask:0xf
	s_waitcnt lgkmcnt(0)
	v_add_u32_e32 v11, v11, v13
	v_cndmask_b32_e64 v13, v56, v33, s[40:41]
	s_waitcnt lgkmcnt(0)
	v_add_u32_e32 v13, v13, v15
	v_cndmask_b32_e64 v15, v44, v52, s[40:41]
	s_waitcnt lgkmcnt(0)
	v_add_u32_e32 v15, v15, v25
	v_cndmask_b32_e64 v25, v41, v40, s[40:41]
	s_waitcnt lgkmcnt(0)
	v_add_u32_e32 v25, v25, v28
	v_cndmask_b32_e64 v28, v24, v36, s[40:41]
	v_cndmask_b32_e64 v24, v36, v24, s[40:41]
	s_nop 1
	v_mov_b32_dpp v24, v24 quad_perm:[1,0,3,2] row_mask:0xf bank_mask:0xf
	s_waitcnt lgkmcnt(0)
	v_add_u32_e32 v24, v28, v24
	v_cndmask_b32_e64 v28, v19, v18, s[40:41]
	v_cndmask_b32_e64 v18, v18, v19, s[40:41]
	s_nop 1
	v_mov_b32_dpp v18, v18 quad_perm:[1,0,3,2] row_mask:0xf bank_mask:0xf
	v_cndmask_b32_e64 v19, v9, v5, s[42:43]
	v_cndmask_b32_e64 v5, v5, v9, s[42:43]
	v_cndmask_b32_e64 v9, v13, v11, s[42:43]
	v_cndmask_b32_e64 v11, v11, v13, s[42:43]
	s_nop 1
	v_mov_b32_dpp v11, v11 quad_perm:[2,3,0,1] row_mask:0xf bank_mask:0xf
	s_waitcnt lgkmcnt(0)
	v_add_u32_e32 v18, v28, v18
	v_cndmask_b32_e64 v13, v15, v25, s[42:43]
	s_nop 1
	v_mov_b32_dpp v13, v13 quad_perm:[2,3,0,1] row_mask:0xf bank_mask:0xf
	s_nop 1
	v_mov_b32_dpp v5, v5 quad_perm:[2,3,0,1] row_mask:0xf bank_mask:0xf
	s_waitcnt lgkmcnt(0)
	v_add_u32_e32 v9, v9, v11
	v_cndmask_b32_e64 v11, v25, v15, s[42:43]
	v_cndmask_b32_e64 v15, v24, v18, s[42:43]
	s_nop 1
	v_mov_b32_dpp v15, v15 quad_perm:[2,3,0,1] row_mask:0xf bank_mask:0xf
	s_waitcnt lgkmcnt(0)
	v_add_u32_e32 v11, v11, v13
	v_cndmask_b32_e64 v13, v18, v24, s[42:43]
	s_waitcnt lgkmcnt(0)
	v_add_u32_e32 v5, v19, v5
	s_waitcnt lgkmcnt(0)
	v_add_u32_e32 v13, v13, v15
	v_cndmask_b32_e64 v15, v9, v5, s[44:45]
	v_cndmask_b32_e64 v5, v5, v9, s[44:45]
	v_cndmask_b32_e64 v9, v13, v11, s[44:45]
	v_cndmask_b32_e64 v11, v11, v13, s[44:45]
	s_nop 1
	v_mov_b32_dpp v5, v5 row_half_mirror row_mask:0xf bank_mask:0xf
	s_nop 1
	v_mov_b32_dpp v5, v5 quad_perm:[3,2,1,0] row_mask:0xf bank_mask:0xf
	s_nop 1
	v_mov_b32_dpp v11, v11 row_half_mirror row_mask:0xf bank_mask:0xf
	s_nop 1
	v_mov_b32_dpp v11, v11 quad_perm:[3,2,1,0] row_mask:0xf bank_mask:0xf
	s_waitcnt lgkmcnt(0)
	v_add_u32_e32 v5, v15, v5
	s_waitcnt lgkmcnt(0)
	v_add_u32_e32 v9, v9, v11
	v_cndmask_b32_e64 v11, v9, v5, s[46:47]
	v_cndmask_b32_e64 v5, v5, v9, s[46:47]
	s_nop 1
	v_mov_b32_dpp v5, v5 row_ror:8 row_mask:0xf bank_mask:0xf
	s_waitcnt lgkmcnt(0)
	v_add_u32_e32 v5, v11, v5
	ds_swizzle_b32 v9, v5 offset:swizzle(SWAP,16)
	s_waitcnt lgkmcnt(0)
	v_add_u32_e32 v5, v5, v9
	ds_bpermute_b32 v9, v0, v5
	s_and_saveexec_b64 s[0:1], s[48:49]
	s_cbranch_execz .LBB0_677
	v_ashrrev_i32_e32 v15, 31, v14
	v_lshlrev_b64 v[14:15], 2, v[14:15]
	v_lshl_add_u64 v[18:19], s[8:9], 0, v[14:15]
	v_mov_b32_e32 v11, v131
	v_lshl_add_u64 v[14:15], s[10:11], 0, v[14:15]
	v_mov_b32_e32 v13, v147
	s_nop 0
	v_mov_b32_e32 v14, v139
	s_waitcnt lgkmcnt(0)
	v_add_u32_e32 v5, v5, v9
	v_cvt_f32_i32_e32 v5, v5
	v_mul_f32_e32 v5, v5, v11
	v_mul_f32_e32 v5, v3, v5
	v_mul_f32_e32 v11, 0x3d372713, v5
	v_mul_f32_e32 v11, v5, v11
	v_mul_f32_e32 v9, 0.5, v5
	v_fmac_f32_e32 v5, v5, v11
	v_mul_f32_e32 v5, 0x3f4c422a, v5
	v_add_f32_e32 v5, v5, v5
	v_mul_f32_e32 v5, 0x3fb8aa3b, v5
	v_exp_f32_e32 v5, v5
	s_nop 0
	v_add_f32_e32 v5, 1.0, v5
	v_rcp_f32_e32 v5, v5
	s_nop 0
	v_fma_f32 v5, v5, -2.0, 1.0
	v_add_f32_e32 v5, 1.0, v5
	v_mul_f32_e32 v5, v9, v5
	v_mul_f32_e32 v5, v13, v5
	v_mul_f32_e32 v5, v14, v5
	ds_write_b32 v109, v5 offset:192
.LBB0_677:
	s_or_b64 exec, exec, s[0:1]
	v_readlane_b32 s0, v10, 0
	s_waitcnt lgkmcnt(0)
	s_waitcnt vmcnt(15)
	v_dot8_i32_i4 v5, v94, v73, 0
	v_dot8_i32_i4 v9, v94, v75, 0
	s_nop 0
	buffer_load_dwordx2 v[92:93], v192, s[52:55], s0 offen
	v_readlane_b32 s0, v10, 1
	v_dot8_i32_i4 v5, v95, v77, v5
	v_dot8_i32_i4 v9, v95, v108, v9
	s_waitcnt vmcnt(15)
	v_dot8_i32_i4 v11, v86, v75, 0
	s_nop 0
	buffer_load_dwordx2 v[96:97], v192, s[52:55], s0 offen
	v_readlane_b32 s0, v10, 2
	v_lshl_add_u32 v5, v5, 4, v9
	v_dot8_i32_i4 v9, v86, v73, 0
	v_dot8_i32_i4 v9, v87, v77, v9
	s_nop 1
	buffer_load_dwordx2 v[88:89], v192, s[52:55], s0 offen
	v_readlane_b32 s0, v10, 3
	v_dot8_i32_i4 v11, v87, v108, v11
	s_waitcnt vmcnt(16)
	v_dot8_i32_i4 v13, v84, v75, 0
	v_dot8_i32_i4 v13, v85, v108, v13
	s_nop 0
	buffer_load_dwordx2 v[98:99], v192, s[52:55], s0 offen
	v_readlane_b32 s0, v10, 4
	v_lshl_add_u32 v9, v9, 4, v11
	v_dot8_i32_i4 v11, v84, v73, 0
	v_dot8_i32_i4 v11, v85, v77, v11
	s_nop 1
	buffer_load_dwordx2 v[82:83], v192, s[52:55], s0 offen
	v_readlane_b32 s0, v10, 5
	s_nop 0
	v_lshl_add_u32 v11, v11, 4, v13
	s_waitcnt vmcnt(17)
	v_dot8_i32_i4 v13, v90, v73, 0
	s_nop 1
	buffer_load_dwordx2 v[56:57], v192, s[52:55], s0 offen
	v_readlane_b32 s0, v10, 6
	v_dot8_i32_i4 v18, v90, v75, 0
	v_dot8_i32_i4 v13, v91, v77, v13
	v_dot8_i32_i4 v18, v91, v108, v18
	s_nop 1
	buffer_load_dwordx2 v[52:53], v192, s[52:55], s0 offen
	v_readlane_b32 s0, v10, 7
	s_nop 0
	v_lshl_add_u32 v13, v13, 4, v18
	s_waitcnt vmcnt(18)
	v_dot8_i32_i4 v18, v78, v73, 0
	v_dot8_i32_i4 v19, v78, v75, 0
	s_nop 0
	buffer_load_dwordx2 v[80:81], v192, s[52:55], s0 offen
	v_readlane_b32 s0, v10, 8
	v_dot8_i32_i4 v18, v79, v77, v18
	v_dot8_i32_i4 v19, v79, v108, v19
	s_waitcnt vmcnt(18)
	v_dot8_i32_i4 v78, v50, v75, 0
	s_nop 0
	buffer_load_dwordx2 v[46:47], v192, s[52:55], s0 offen
	v_readlane_b32 s0, v10, 9
	v_lshl_add_u32 v18, v18, 4, v19
	v_dot8_i32_i4 v19, v50, v73, 0
	v_dot8_i32_i4 v19, v51, v77, v19
	s_nop 1
	buffer_load_dwordx2 v[40:41], v192, s[52:55], s0 offen
	v_readlane_b32 s0, v10, 10
	v_dot8_i32_i4 v78, v51, v108, v78
	s_waitcnt vmcnt(19)
	v_dot8_i32_i4 v50, v48, v73, 0
	s_nop 1
	buffer_load_dwordx2 v[36:37], v192, s[52:55], s0 offen
	v_readlane_b32 s0, v10, 11
	v_dot8_i32_i4 v51, v48, v75, 0
	v_dot8_i32_i4 v50, v49, v77, v50
	v_dot8_i32_i4 v51, v49, v108, v51
	s_nop 1
	buffer_load_dwordx2 v[44:45], v192, s[52:55], s0 offen
	v_readlane_b32 s0, v10, 12
	s_nop 0
	v_lshl_add_u32 v48, v50, 4, v51
	s_waitcnt vmcnt(20)
	v_dot8_i32_i4 v49, v54, v73, 0
	v_dot8_i32_i4 v50, v54, v75, 0
	s_nop 0
	buffer_load_dwordx2 v[32:33], v192, s[52:55], s0 offen
	v_readlane_b32 s0, v10, 13
	v_dot8_i32_i4 v49, v55, v77, v49
	v_dot8_i32_i4 v50, v55, v108, v50
	s_waitcnt vmcnt(20)
	v_dot8_i32_i4 v51, v42, v75, 0
	s_nop 0
	buffer_load_dwordx2 v[24:25], v192, s[52:55], s0 offen
	v_readlane_b32 s0, v10, 14
	v_lshl_add_u32 v49, v49, 4, v50
	v_dot8_i32_i4 v50, v42, v73, 0
	v_dot8_i32_i4 v50, v43, v77, v50
	s_nop 1
	buffer_load_dwordx2 v[14:15], v192, s[52:55], s0 offen
	v_readlane_b32 s0, v10, 15
	v_dot8_i32_i4 v51, v43, v108, v51
	s_waitcnt vmcnt(21)
	v_dot8_i32_i4 v43, v34, v73, 0
	v_dot8_i32_i4 v43, v35, v77, v43
	s_nop 0
	buffer_load_dwordx2 v[28:29], v192, s[52:55], s0 offen
	v_lshl_add_u32 v42, v50, 4, v51
	v_dot8_i32_i4 v50, v34, v75, 0
	v_dot8_i32_i4 v50, v35, v108, v50
	s_waitcnt vmcnt(21)
	v_dot8_i32_i4 v35, v30, v73, 0
	v_dot8_i32_i4 v35, v31, v77, v35
	v_lshl_add_u32 v34, v43, 4, v50
	v_dot8_i32_i4 v43, v30, v75, 0
	v_dot8_i32_i4 v43, v31, v108, v43
	s_waitcnt vmcnt(20)
	v_dot8_i32_i4 v31, v38, v73, 0
	v_dot8_i32_i4 v31, v39, v77, v31
	v_lshl_add_u32 v30, v35, 4, v43
	v_dot8_i32_i4 v35, v38, v75, 0
	v_dot8_i32_i4 v35, v39, v108, v35
	s_waitcnt vmcnt(19)
	v_dot8_i32_i4 v38, v26, v75, 0
	v_dot8_i32_i4 v38, v27, v108, v38
	v_lshl_add_u32 v31, v31, 4, v35
	v_dot8_i32_i4 v35, v26, v73, 0
	v_dot8_i32_i4 v35, v27, v77, v35
	s_waitcnt vmcnt(18)
	v_dot8_i32_i4 v27, v20, v73, 0
	v_dot8_i32_i4 v27, v21, v77, v27
	v_lshl_add_u32 v26, v35, 4, v38
	v_dot8_i32_i4 v35, v20, v75, 0
	v_dot8_i32_i4 v35, v21, v108, v35
	s_waitcnt vmcnt(17)
	v_dot8_i32_i4 v21, v16, v73, 0
	s_nop 0
	v_lshl_add_u32 v20, v27, 4, v35
	v_dot8_i32_i4 v27, v16, v75, 0
	v_dot8_i32_i4 v21, v17, v77, v21
	v_dot8_i32_i4 v27, v17, v108, v27
	s_waitcnt vmcnt(16)
	v_dot8_i32_i4 v17, v22, v73, 0
	v_dot8_i32_i4 v17, v23, v77, v17
	v_lshl_add_u32 v16, v21, 4, v27
	v_dot8_i32_i4 v21, v22, v75, 0
	v_dot8_i32_i4 v21, v23, v108, v21
	v_lshl_add_u32 v19, v19, 4, v78
	s_nop 0
	s_nop 0
	v_lshl_add_u32 v17, v17, 4, v21
	s_nop 0
	v_cndmask_b32_e64 v21, v9, v5, s[40:41]
	v_cndmask_b32_e64 v5, v5, v9, s[40:41]
	v_cndmask_b32_e64 v9, v13, v11, s[40:41]
	v_cndmask_b32_e64 v11, v11, v13, s[40:41]
	s_nop 1
	v_mov_b32_dpp v11, v11 quad_perm:[1,0,3,2] row_mask:0xf bank_mask:0xf
	s_nop 1
	v_mov_b32_dpp v5, v5 quad_perm:[1,0,3,2] row_mask:0xf bank_mask:0xf
	v_cndmask_b32_e64 v13, v18, v19, s[40:41]
	s_waitcnt lgkmcnt(0)
	v_add_u32_e32 v9, v9, v11
	v_cndmask_b32_e64 v11, v19, v18, s[40:41]
	s_nop 1
	v_mov_b32_dpp v13, v13 quad_perm:[1,0,3,2] row_mask:0xf bank_mask:0xf
	v_cndmask_b32_e64 v18, v48, v49, s[40:41]
	s_nop 1
	v_mov_b32_dpp v18, v18 quad_perm:[1,0,3,2] row_mask:0xf bank_mask:0xf
	v_cndmask_b32_e64 v19, v42, v34, s[40:41]
	s_waitcnt lgkmcnt(0)
	v_add_u32_e32 v5, v21, v5
	s_nop 1
	v_mov_b32_dpp v19, v19 quad_perm:[1,0,3,2] row_mask:0xf bank_mask:0xf
	v_cndmask_b32_e64 v21, v30, v31, s[40:41]
	s_nop 1
	v_mov_b32_dpp v21, v21 quad_perm:[1,0,3,2] row_mask:0xf bank_mask:0xf
	s_waitcnt lgkmcnt(0)
	v_add_u32_e32 v11, v11, v13
	v_cndmask_b32_e64 v13, v49, v48, s[40:41]
	s_waitcnt lgkmcnt(0)
	v_add_u32_e32 v13, v13, v18
	v_cndmask_b32_e64 v18, v34, v42, s[40:41]
	s_waitcnt lgkmcnt(0)
	v_add_u32_e32 v18, v18, v19
	v_cndmask_b32_e64 v19, v31, v30, s[40:41]
	s_waitcnt lgkmcnt(0)
	v_add_u32_e32 v19, v19, v21
	v_cndmask_b32_e64 v21, v20, v26, s[40:41]
	v_cndmask_b32_e64 v20, v26, v20, s[40:41]
	s_nop 1
	v_mov_b32_dpp v20, v20 quad_perm:[1,0,3,2] row_mask:0xf bank_mask:0xf
	s_waitcnt lgkmcnt(0)
	v_add_u32_e32 v20, v21, v20
	v_cndmask_b32_e64 v21, v17, v16, s[40:41]
	v_cndmask_b32_e64 v16, v16, v17, s[40:41]
	v_cndmask_b32_e64 v17, v9, v5, s[42:43]
	v_cndmask_b32_e64 v5, v5, v9, s[42:43]
	v_cndmask_b32_e64 v9, v13, v11, s[42:43]
	v_cndmask_b32_e64 v11, v11, v13, s[42:43]
	s_nop 1
	v_mov_b32_dpp v16, v16 quad_perm:[1,0,3,2] row_mask:0xf bank_mask:0xf
	s_nop 1
	v_mov_b32_dpp v11, v11 quad_perm:[2,3,0,1] row_mask:0xf bank_mask:0xf
	v_cndmask_b32_e64 v13, v18, v19, s[42:43]
	s_nop 1
	v_mov_b32_dpp v13, v13 quad_perm:[2,3,0,1] row_mask:0xf bank_mask:0xf
	s_nop 1
	v_mov_b32_dpp v5, v5 quad_perm:[2,3,0,1] row_mask:0xf bank_mask:0xf
	s_waitcnt lgkmcnt(0)
	v_add_u32_e32 v16, v21, v16
	s_waitcnt lgkmcnt(0)
	v_add_u32_e32 v9, v9, v11
	v_cndmask_b32_e64 v11, v19, v18, s[42:43]
	s_waitcnt lgkmcnt(0)
	v_add_u32_e32 v11, v11, v13
	v_cndmask_b32_e64 v13, v16, v20, s[42:43]
	v_cndmask_b32_e64 v16, v20, v16, s[42:43]
	s_nop 1
	v_mov_b32_dpp v16, v16 quad_perm:[2,3,0,1] row_mask:0xf bank_mask:0xf
	s_waitcnt lgkmcnt(0)
	v_add_u32_e32 v5, v17, v5
	s_waitcnt lgkmcnt(0)
	v_add_u32_e32 v13, v13, v16
	v_cndmask_b32_e64 v16, v9, v5, s[44:45]
	v_cndmask_b32_e64 v5, v5, v9, s[44:45]
	v_cndmask_b32_e64 v9, v13, v11, s[44:45]
	v_cndmask_b32_e64 v11, v11, v13, s[44:45]
	s_nop 1
	v_mov_b32_dpp v5, v5 row_half_mirror row_mask:0xf bank_mask:0xf
	s_nop 1
	v_mov_b32_dpp v5, v5 quad_perm:[3,2,1,0] row_mask:0xf bank_mask:0xf
	s_nop 1
	v_mov_b32_dpp v11, v11 row_half_mirror row_mask:0xf bank_mask:0xf
	s_nop 1
	v_mov_b32_dpp v11, v11 quad_perm:[3,2,1,0] row_mask:0xf bank_mask:0xf
	s_waitcnt lgkmcnt(0)
	v_add_u32_e32 v5, v16, v5
	s_waitcnt lgkmcnt(0)
	v_add_u32_e32 v9, v9, v11
	v_cndmask_b32_e64 v11, v9, v5, s[46:47]
	v_cndmask_b32_e64 v5, v5, v9, s[46:47]
	s_nop 1
	v_mov_b32_dpp v5, v5 row_ror:8 row_mask:0xf bank_mask:0xf
	s_waitcnt lgkmcnt(0)
	v_add_u32_e32 v5, v11, v5
	ds_swizzle_b32 v9, v5 offset:swizzle(SWAP,16)
	s_waitcnt lgkmcnt(0)
	v_add_u32_e32 v5, v5, v9
	ds_bpermute_b32 v9, v0, v5
	s_and_saveexec_b64 s[0:1], s[48:49]
	s_cbranch_execz .LBB0_679
	v_ashrrev_i32_e32 v13, 31, v12
	v_lshlrev_b64 v[12:13], 2, v[12:13]
	v_lshl_add_u64 v[16:17], s[8:9], 0, v[12:13]
	v_mov_b32_e32 v11, v132
	v_lshl_add_u64 v[12:13], s[10:11], 0, v[12:13]
	v_mov_b32_e32 v16, v148
	s_nop 0
	v_mov_b32_e32 v12, v140
	s_waitcnt lgkmcnt(0)
	v_add_u32_e32 v5, v5, v9
	v_cvt_f32_i32_e32 v5, v5
	v_mul_f32_e32 v5, v5, v11
	v_mul_f32_e32 v5, v3, v5
	v_mul_f32_e32 v11, 0x3d372713, v5
	v_mul_f32_e32 v11, v5, v11
	v_mul_f32_e32 v9, 0.5, v5
	v_fmac_f32_e32 v5, v5, v11
	v_mul_f32_e32 v5, 0x3f4c422a, v5
	v_add_f32_e32 v5, v5, v5
	v_mul_f32_e32 v5, 0x3fb8aa3b, v5
	v_exp_f32_e32 v5, v5
	s_nop 0
	v_add_f32_e32 v5, 1.0, v5
	v_rcp_f32_e32 v5, v5
	s_nop 0
	v_fma_f32 v5, v5, -2.0, 1.0
	v_add_f32_e32 v5, 1.0, v5
	v_mul_f32_e32 v5, v9, v5
	v_mul_f32_e32 v5, v16, v5
	v_mul_f32_e32 v5, v12, v5
	ds_write_b32 v109, v5 offset:256
.LBB0_679:
	s_or_b64 exec, exec, s[0:1]
	v_readlane_b32 s0, v8, 0
	s_waitcnt lgkmcnt(0)
	s_waitcnt vmcnt(15)
	v_dot8_i32_i4 v5, v92, v73, 0
	v_dot8_i32_i4 v9, v92, v75, 0
	s_nop 0
	buffer_load_dwordx2 v[86:87], v192, s[52:55], s0 offen
	v_readlane_b32 s0, v8, 1
	v_dot8_i32_i4 v5, v93, v77, v5
	v_dot8_i32_i4 v9, v93, v108, v9
	s_waitcnt vmcnt(15)
	v_dot8_i32_i4 v11, v96, v75, 0
	s_nop 0
	buffer_load_dwordx2 v[78:79], v192, s[52:55], s0 offen
	v_readlane_b32 s0, v8, 2
	v_lshl_add_u32 v5, v5, 4, v9
	v_dot8_i32_i4 v9, v96, v73, 0
	v_dot8_i32_i4 v9, v97, v77, v9
	s_nop 1
	buffer_load_dwordx2 v[54:55], v192, s[52:55], s0 offen
	v_readlane_b32 s0, v8, 3
	v_dot8_i32_i4 v11, v97, v108, v11
	s_waitcnt vmcnt(16)
	v_dot8_i32_i4 v90, v88, v75, 0
	v_dot8_i32_i4 v90, v89, v108, v90
	s_nop 0
	buffer_load_dwordx2 v[84:85], v192, s[52:55], s0 offen
	v_readlane_b32 s0, v8, 4
	v_lshl_add_u32 v9, v9, 4, v11
	v_dot8_i32_i4 v11, v88, v73, 0
	v_dot8_i32_i4 v11, v89, v77, v11
	s_nop 1
	buffer_load_dwordx2 v[50:51], v192, s[52:55], s0 offen
	v_readlane_b32 s0, v8, 5
	s_waitcnt vmcnt(17)
	v_dot8_i32_i4 v88, v98, v73, 0
	v_dot8_i32_i4 v89, v98, v75, 0
	s_nop 1
	buffer_load_dwordx2 v[42:43], v192, s[52:55], s0 offen
	v_readlane_b32 s0, v8, 6
	v_dot8_i32_i4 v88, v99, v77, v88
	v_dot8_i32_i4 v89, v99, v108, v89
	v_lshl_add_u32 v11, v11, 4, v90
	s_nop 1
	buffer_load_dwordx2 v[38:39], v192, s[52:55], s0 offen
	v_readlane_b32 s0, v8, 7
	v_lshl_add_u32 v88, v88, 4, v89
	s_waitcnt vmcnt(18)
	v_dot8_i32_i4 v89, v82, v73, 0
	v_dot8_i32_i4 v90, v82, v75, 0
	s_nop 0
	buffer_load_dwordx2 v[48:49], v192, s[52:55], s0 offen
	v_readlane_b32 s0, v8, 8
	v_dot8_i32_i4 v89, v83, v77, v89
	v_dot8_i32_i4 v90, v83, v108, v90
	s_waitcnt vmcnt(18)
	v_dot8_i32_i4 v83, v56, v73, 0
	s_nop 0
	buffer_load_dwordx2 v[34:35], v192, s[52:55], s0 offen
	v_readlane_b32 s0, v8, 9
	v_lshl_add_u32 v82, v89, 4, v90
	v_dot8_i32_i4 v89, v56, v75, 0
	v_dot8_i32_i4 v83, v57, v77, v83
	s_nop 1
	buffer_load_dwordx2 v[26:27], v192, s[52:55], s0 offen
	v_readlane_b32 s0, v8, 10
	v_dot8_i32_i4 v89, v57, v108, v89
	s_waitcnt vmcnt(19)
	v_dot8_i32_i4 v57, v52, v73, 0
	v_dot8_i32_i4 v57, v53, v77, v57
	s_nop 0
	buffer_load_dwordx2 v[22:23], v192, s[52:55], s0 offen
	v_readlane_b32 s0, v8, 11
	v_lshl_add_u32 v56, v83, 4, v89
	v_dot8_i32_i4 v83, v52, v75, 0
	v_dot8_i32_i4 v83, v53, v108, v83
	s_nop 1
	buffer_load_dwordx2 v[30:31], v192, s[52:55], s0 offen
	v_readlane_b32 s0, v8, 12
	s_nop 0
	v_lshl_add_u32 v52, v57, 4, v83
	s_waitcnt vmcnt(20)
	v_dot8_i32_i4 v53, v80, v73, 0
	s_nop 1
	buffer_load_dwordx2 v[20:21], v192, s[52:55], s0 offen
	v_readlane_b32 s0, v8, 13
	v_dot8_i32_i4 v57, v80, v75, 0
	v_dot8_i32_i4 v53, v81, v77, v53
	v_dot8_i32_i4 v57, v81, v108, v57
	s_nop 1
	buffer_load_dwordx2 v[16:17], v192, s[52:55], s0 offen
	v_readlane_b32 s0, v8, 14
	s_nop 0
	v_lshl_add_u32 v53, v53, 4, v57
	s_waitcnt vmcnt(21)
	v_dot8_i32_i4 v57, v46, v73, 0
	v_dot8_i32_i4 v80, v46, v75, 0
	s_nop 0
	buffer_load_dwordx2 v[12:13], v192, s[52:55], s0 offen
	v_readlane_b32 s0, v8, 15
	v_dot8_i32_i4 v57, v47, v77, v57
	v_dot8_i32_i4 v80, v47, v108, v80
	s_waitcnt vmcnt(21)
	v_dot8_i32_i4 v47, v40, v73, 0
	s_nop 0
	buffer_load_dwordx2 v[18:19], v192, s[52:55], s0 offen
	v_lshl_add_u32 v46, v57, 4, v80
	v_dot8_i32_i4 v57, v40, v75, 0
	v_dot8_i32_i4 v47, v41, v77, v47
	v_dot8_i32_i4 v57, v41, v108, v57
	s_waitcnt vmcnt(21)
	v_dot8_i32_i4 v41, v36, v73, 0
	v_dot8_i32_i4 v41, v37, v77, v41
	v_lshl_add_u32 v40, v47, 4, v57
	v_dot8_i32_i4 v47, v36, v75, 0
	v_dot8_i32_i4 v47, v37, v108, v47
	s_waitcnt vmcnt(20)
	v_dot8_i32_i4 v37, v44, v73, 0
	v_dot8_i32_i4 v37, v45, v77, v37
	v_lshl_add_u32 v36, v41, 4, v47
	v_dot8_i32_i4 v41, v44, v75, 0
	v_dot8_i32_i4 v41, v45, v108, v41
	s_waitcnt vmcnt(19)
	v_dot8_i32_i4 v44, v32, v75, 0
	v_dot8_i32_i4 v44, v33, v108, v44
	v_lshl_add_u32 v37, v37, 4, v41
	v_dot8_i32_i4 v41, v32, v73, 0
	v_dot8_i32_i4 v41, v33, v77, v41
	s_waitcnt vmcnt(18)
	v_dot8_i32_i4 v33, v24, v73, 0
	v_dot8_i32_i4 v33, v25, v77, v33
	v_lshl_add_u32 v32, v41, 4, v44
	v_dot8_i32_i4 v41, v24, v75, 0
	v_dot8_i32_i4 v41, v25, v108, v41
	s_waitcnt vmcnt(17)
	v_dot8_i32_i4 v25, v14, v73, 0
	s_nop 0
	v_lshl_add_u32 v24, v33, 4, v41
	v_dot8_i32_i4 v33, v14, v75, 0
	v_dot8_i32_i4 v25, v15, v77, v25
	v_dot8_i32_i4 v33, v15, v108, v33
	s_waitcnt vmcnt(16)
	v_dot8_i32_i4 v15, v28, v73, 0
	v_dot8_i32_i4 v15, v29, v77, v15
	v_lshl_add_u32 v14, v25, 4, v33
	v_dot8_i32_i4 v25, v28, v75, 0
	v_dot8_i32_i4 v25, v29, v108, v25
	s_nop 1
	s_nop 0
	v_lshl_add_u32 v15, v15, 4, v25
	s_nop 0
	v_cndmask_b32_e64 v25, v9, v5, s[40:41]
	v_cndmask_b32_e64 v5, v5, v9, s[40:41]
	s_nop 1
	v_mov_b32_dpp v5, v5 quad_perm:[1,0,3,2] row_mask:0xf bank_mask:0xf
	v_cndmask_b32_e64 v9, v88, v11, s[40:41]
	v_cndmask_b32_e64 v11, v11, v88, s[40:41]
	s_waitcnt lgkmcnt(0)
	v_add_u32_e32 v5, v25, v5
	s_nop 1
	v_mov_b32_dpp v11, v11 quad_perm:[1,0,3,2] row_mask:0xf bank_mask:0xf
	v_cndmask_b32_e64 v25, v82, v56, s[40:41]
	s_nop 1
	v_mov_b32_dpp v25, v25 quad_perm:[1,0,3,2] row_mask:0xf bank_mask:0xf
	v_cndmask_b32_e64 v28, v52, v53, s[40:41]
	s_nop 1
	v_mov_b32_dpp v28, v28 quad_perm:[1,0,3,2] row_mask:0xf bank_mask:0xf
	v_cndmask_b32_e64 v29, v46, v40, s[40:41]
	s_nop 1
	v_mov_b32_dpp v29, v29 quad_perm:[1,0,3,2] row_mask:0xf bank_mask:0xf
	v_cndmask_b32_e64 v33, v36, v37, s[40:41]
	s_nop 1
	v_mov_b32_dpp v33, v33 quad_perm:[1,0,3,2] row_mask:0xf bank_mask:0xf
	s_waitcnt lgkmcnt(0)
	v_add_u32_e32 v9, v9, v11
	v_cndmask_b32_e64 v11, v56, v82, s[40:41]
	s_waitcnt lgkmcnt(0)
	v_add_u32_e32 v11, v11, v25
	v_cndmask_b32_e64 v25, v53, v52, s[40:41]
	s_waitcnt lgkmcnt(0)
	v_add_u32_e32 v25, v25, v28
	v_cndmask_b32_e64 v28, v40, v46, s[40:41]
	s_waitcnt lgkmcnt(0)
	v_add_u32_e32 v28, v28, v29
	v_cndmask_b32_e64 v29, v37, v36, s[40:41]
	s_waitcnt lgkmcnt(0)
	v_add_u32_e32 v29, v29, v33
	v_cndmask_b32_e64 v33, v24, v32, s[40:41]
	v_cndmask_b32_e64 v24, v32, v24, s[40:41]
	v_cndmask_b32_e64 v32, v15, v14, s[40:41]
	v_cndmask_b32_e64 v14, v14, v15, s[40:41]
	v_cndmask_b32_e64 v15, v9, v5, s[42:43]
	v_cndmask_b32_e64 v5, v5, v9, s[42:43]
	s_nop 1
	v_mov_b32_dpp v5, v5 quad_perm:[2,3,0,1] row_mask:0xf bank_mask:0xf
	v_cndmask_b32_e64 v9, v25, v11, s[42:43]
	v_cndmask_b32_e64 v11, v11, v25, s[42:43]
	s_nop 1
	v_mov_b32_dpp v24, v24 quad_perm:[1,0,3,2] row_mask:0xf bank_mask:0xf
	s_nop 1
	v_mov_b32_dpp v14, v14 quad_perm:[1,0,3,2] row_mask:0xf bank_mask:0xf
	s_waitcnt lgkmcnt(0)
	v_add_u32_e32 v5, v15, v5
	s_nop 1
	v_mov_b32_dpp v11, v11 quad_perm:[2,3,0,1] row_mask:0xf bank_mask:0xf
	v_cndmask_b32_e64 v15, v28, v29, s[42:43]
	s_nop 1
	v_mov_b32_dpp v15, v15 quad_perm:[2,3,0,1] row_mask:0xf bank_mask:0xf
	s_waitcnt lgkmcnt(0)
	v_add_u32_e32 v24, v33, v24
	s_waitcnt lgkmcnt(0)
	v_add_u32_e32 v14, v32, v14
	s_waitcnt lgkmcnt(0)
	v_add_u32_e32 v9, v9, v11
	v_cndmask_b32_e64 v11, v29, v28, s[42:43]
	s_waitcnt lgkmcnt(0)
	v_add_u32_e32 v11, v11, v15
	v_cndmask_b32_e64 v15, v14, v24, s[42:43]
	v_cndmask_b32_e64 v14, v24, v14, s[42:43]
	s_nop 1
	v_mov_b32_dpp v14, v14 quad_perm:[2,3,0,1] row_mask:0xf bank_mask:0xf
	s_waitcnt lgkmcnt(0)
	v_add_u32_e32 v14, v15, v14
	v_cndmask_b32_e64 v15, v9, v5, s[44:45]
	v_cndmask_b32_e64 v5, v5, v9, s[44:45]
	v_cndmask_b32_e64 v9, v14, v11, s[44:45]
	v_cndmask_b32_e64 v11, v11, v14, s[44:45]
	s_nop 1
	v_mov_b32_dpp v5, v5 row_half_mirror row_mask:0xf bank_mask:0xf
	s_nop 1
	v_mov_b32_dpp v5, v5 quad_perm:[3,2,1,0] row_mask:0xf bank_mask:0xf
	s_nop 1
	v_mov_b32_dpp v11, v11 row_half_mirror row_mask:0xf bank_mask:0xf
	s_nop 1
	v_mov_b32_dpp v11, v11 quad_perm:[3,2,1,0] row_mask:0xf bank_mask:0xf
	s_waitcnt lgkmcnt(0)
	v_add_u32_e32 v5, v15, v5
	s_waitcnt lgkmcnt(0)
	v_add_u32_e32 v9, v9, v11
	v_cndmask_b32_e64 v11, v9, v5, s[46:47]
	v_cndmask_b32_e64 v5, v5, v9, s[46:47]
	s_nop 1
	v_mov_b32_dpp v5, v5 row_ror:8 row_mask:0xf bank_mask:0xf
	s_waitcnt lgkmcnt(0)
	v_add_u32_e32 v5, v11, v5
	ds_swizzle_b32 v9, v5 offset:swizzle(SWAP,16)
	s_waitcnt lgkmcnt(0)
	v_add_u32_e32 v5, v5, v9
	ds_bpermute_b32 v9, v0, v5
	s_and_saveexec_b64 s[0:1], s[48:49]
	s_cbranch_execz .LBB0_681
	v_ashrrev_i32_e32 v11, 31, v10
	v_lshlrev_b64 v[10:11], 2, v[10:11]
	v_lshl_add_u64 v[14:15], s[8:9], 0, v[10:11]
	v_mov_b32_e32 v14, v133
	v_lshl_add_u64 v[10:11], s[10:11], 0, v[10:11]
	v_mov_b32_e32 v15, v149
	s_nop 0
	v_mov_b32_e32 v10, v141
	s_waitcnt lgkmcnt(0)
	v_add_u32_e32 v5, v5, v9
	v_cvt_f32_i32_e32 v5, v5
	v_mul_f32_e32 v5, v5, v14
	v_mul_f32_e32 v5, v3, v5
	v_mul_f32_e32 v11, 0x3d372713, v5
	v_mul_f32_e32 v11, v5, v11
	v_mul_f32_e32 v9, 0.5, v5
	v_fmac_f32_e32 v5, v5, v11
	v_mul_f32_e32 v5, 0x3f4c422a, v5
	v_add_f32_e32 v5, v5, v5
	v_mul_f32_e32 v5, 0x3fb8aa3b, v5
	v_exp_f32_e32 v5, v5
	s_nop 0
	v_add_f32_e32 v5, 1.0, v5
	v_rcp_f32_e32 v5, v5
	s_nop 0
	v_fma_f32 v5, v5, -2.0, 1.0
	v_add_f32_e32 v5, 1.0, v5
	v_mul_f32_e32 v5, v9, v5
	v_mul_f32_e32 v5, v15, v5
	v_mul_f32_e32 v5, v10, v5
	ds_write_b32 v109, v5 offset:320
.LBB0_681:
	s_or_b64 exec, exec, s[0:1]
	s_waitcnt lgkmcnt(0)
	v_readlane_b32 s0, v4, 0
	s_waitcnt vmcnt(15)
	v_dot8_i32_i4 v5, v86, v73, 0
	v_dot8_i32_i4 v9, v86, v75, 0
	v_dot8_i32_i4 v5, v87, v77, v5
	v_dot8_i32_i4 v9, v87, v108, v9
	buffer_load_dwordx2 v[88:89], v192, s[52:55], s0 offen
	v_readlane_b32 s0, v4, 1
	s_nop 0
	v_lshl_add_u32 v5, v5, 4, v9
	s_waitcnt vmcnt(15)
	v_dot8_i32_i4 v9, v78, v73, 0
	v_dot8_i32_i4 v86, v78, v75, 0
	buffer_load_dwordx2 v[90:91], v192, s[52:55], s0 offen
	v_readlane_b32 s0, v4, 2
	v_dot8_i32_i4 v9, v79, v77, v9
	v_dot8_i32_i4 v86, v79, v108, v86
	s_waitcnt vmcnt(15)
	v_dot8_i32_i4 v78, v54, v73, 0
	v_dot8_i32_i4 v79, v54, v75, 0
	buffer_load_dwordx2 v[82:83], v192, s[52:55], s0 offen
	v_readlane_b32 s0, v4, 3
	v_dot8_i32_i4 v78, v55, v77, v78
	v_dot8_i32_i4 v79, v55, v108, v79
	s_waitcnt vmcnt(15)
	v_dot8_i32_i4 v55, v84, v73, 0
	s_nop 0
	v_lshl_add_u32 v54, v78, 4, v79
	buffer_load_dwordx2 v[92:93], v192, s[52:55], s0 offen
	v_readlane_b32 s0, v4, 4
	v_dot8_i32_i4 v78, v84, v75, 0
	v_dot8_i32_i4 v55, v85, v77, v55
	v_dot8_i32_i4 v78, v85, v108, v78
	s_nop 1
	buffer_load_dwordx2 v[80:81], v192, s[52:55], s0 offen
	v_readlane_b32 s0, v4, 5
	s_nop 0
	v_lshl_add_u32 v55, v55, 4, v78
	s_waitcnt vmcnt(16)
	v_dot8_i32_i4 v78, v50, v73, 0
	v_dot8_i32_i4 v79, v50, v75, 0
	buffer_load_dwordx2 v[52:53], v192, s[52:55], s0 offen
	v_readlane_b32 s0, v4, 6
	v_dot8_i32_i4 v78, v51, v77, v78
	v_dot8_i32_i4 v79, v51, v108, v79
	s_waitcnt vmcnt(16)
	v_dot8_i32_i4 v51, v42, v73, 0
	s_nop 0
	v_lshl_add_u32 v50, v78, 4, v79
	buffer_load_dwordx2 v[46:47], v192, s[52:55], s0 offen
	v_readlane_b32 s0, v4, 7
	v_dot8_i32_i4 v78, v42, v75, 0
	v_dot8_i32_i4 v51, v43, v77, v51
	v_dot8_i32_i4 v78, v43, v108, v78
	s_nop 1
	buffer_load_dwordx2 v[56:57], v192, s[52:55], s0 offen
	v_readlane_b32 s0, v4, 8
	s_nop 0
	v_lshl_add_u32 v42, v51, 4, v78
	s_waitcnt vmcnt(17)
	v_dot8_i32_i4 v43, v38, v73, 0
	v_dot8_i32_i4 v51, v38, v75, 0
	buffer_load_dwordx2 v[44:45], v192, s[52:55], s0 offen
	v_readlane_b32 s0, v4, 9
	v_dot8_i32_i4 v43, v39, v77, v43
	v_dot8_i32_i4 v51, v39, v108, v51
	s_waitcnt vmcnt(17)
	v_dot8_i32_i4 v39, v48, v73, 0
	s_nop 0
	v_lshl_add_u32 v38, v43, 4, v51
	buffer_load_dwordx2 v[36:37], v192, s[52:55], s0 offen
	v_readlane_b32 s0, v4, 10
	v_dot8_i32_i4 v43, v48, v75, 0
	v_dot8_i32_i4 v39, v49, v77, v39
	v_dot8_i32_i4 v43, v49, v108, v43
	s_nop 1
	buffer_load_dwordx2 v[32:33], v192, s[52:55], s0 offen
	v_readlane_b32 s0, v4, 11
	s_nop 0
	v_lshl_add_u32 v39, v39, 4, v43
	s_waitcnt vmcnt(18)
	v_dot8_i32_i4 v43, v34, v73, 0
	v_dot8_i32_i4 v48, v34, v75, 0
	buffer_load_dwordx2 v[40:41], v192, s[52:55], s0 offen
	v_readlane_b32 s0, v4, 12
	v_dot8_i32_i4 v43, v35, v77, v43
	v_dot8_i32_i4 v48, v35, v108, v48
	s_waitcnt vmcnt(18)
	v_dot8_i32_i4 v35, v26, v73, 0
	s_nop 0
	v_lshl_add_u32 v34, v43, 4, v48
	buffer_load_dwordx2 v[28:29], v192, s[52:55], s0 offen
	v_readlane_b32 s0, v4, 13
	v_dot8_i32_i4 v43, v26, v75, 0
	v_dot8_i32_i4 v35, v27, v77, v35
	v_dot8_i32_i4 v43, v27, v108, v43
	s_nop 1
	buffer_load_dwordx2 v[14:15], v192, s[52:55], s0 offen
	v_readlane_b32 s0, v4, 14
	s_nop 0
	v_lshl_add_u32 v26, v35, 4, v43
	s_waitcnt vmcnt(19)
	v_dot8_i32_i4 v27, v22, v73, 0
	v_dot8_i32_i4 v35, v22, v75, 0
	buffer_load_dwordx2 v[10:11], v192, s[52:55], s0 offen
	v_readlane_b32 s0, v4, 15
	v_dot8_i32_i4 v27, v23, v77, v27
	v_dot8_i32_i4 v35, v23, v108, v35
	s_waitcnt vmcnt(19)
	v_dot8_i32_i4 v23, v30, v73, 0
	s_nop 0
	v_lshl_add_u32 v22, v27, 4, v35
	buffer_load_dwordx2 v[24:25], v192, s[52:55], s0 offen
	v_dot8_i32_i4 v27, v30, v75, 0
	v_dot8_i32_i4 v23, v31, v77, v23
	v_dot8_i32_i4 v27, v31, v108, v27
	s_waitcnt vmcnt(19)
	v_dot8_i32_i4 v30, v20, v75, 0
	v_dot8_i32_i4 v30, v21, v108, v30
	v_lshl_add_u32 v23, v23, 4, v27
	v_dot8_i32_i4 v27, v20, v73, 0
	v_dot8_i32_i4 v27, v21, v77, v27
	s_waitcnt vmcnt(18)
	v_dot8_i32_i4 v21, v16, v73, 0
	v_dot8_i32_i4 v21, v17, v77, v21
	v_lshl_add_u32 v20, v27, 4, v30
	v_dot8_i32_i4 v27, v16, v75, 0
	v_dot8_i32_i4 v27, v17, v108, v27
	v_lshl_add_u32 v9, v9, 4, v86
	s_waitcnt vmcnt(17)
	v_dot8_i32_i4 v17, v12, v73, 0
	v_lshl_add_u32 v16, v21, 4, v27
	v_dot8_i32_i4 v21, v12, v75, 0
	v_dot8_i32_i4 v17, v13, v77, v17
	v_dot8_i32_i4 v21, v13, v108, v21
	s_waitcnt vmcnt(16)
	v_dot8_i32_i4 v13, v18, v73, 0
	v_dot8_i32_i4 v13, v19, v77, v13
	v_lshl_add_u32 v12, v17, 4, v21
	v_dot8_i32_i4 v17, v18, v75, 0
	v_dot8_i32_i4 v17, v19, v108, v17
	s_nop 1
	s_nop 0
	v_lshl_add_u32 v13, v13, 4, v17
	s_nop 0
	v_cndmask_b32_e64 v17, v9, v5, s[40:41]
	v_cndmask_b32_e64 v5, v5, v9, s[40:41]
	s_nop 1
	v_mov_b32_dpp v5, v5 quad_perm:[1,0,3,2] row_mask:0xf bank_mask:0xf
	s_waitcnt lgkmcnt(0)
	v_add_u32_e32 v5, v17, v5
	v_cndmask_b32_e64 v17, v54, v55, s[40:41]
	s_nop 1
	v_mov_b32_dpp v17, v17 quad_perm:[1,0,3,2] row_mask:0xf bank_mask:0xf
	v_cndmask_b32_e64 v18, v50, v42, s[40:41]
	s_nop 1
	v_mov_b32_dpp v18, v18 quad_perm:[1,0,3,2] row_mask:0xf bank_mask:0xf
	v_cndmask_b32_e64 v19, v38, v39, s[40:41]
	s_nop 1
	v_mov_b32_dpp v19, v19 quad_perm:[1,0,3,2] row_mask:0xf bank_mask:0xf
	v_cndmask_b32_e64 v21, v34, v26, s[40:41]
	s_nop 1
	v_mov_b32_dpp v21, v21 quad_perm:[1,0,3,2] row_mask:0xf bank_mask:0xf
	v_cndmask_b32_e64 v9, v55, v54, s[40:41]
	s_waitcnt lgkmcnt(0)
	v_add_u32_e32 v9, v9, v17
	v_cndmask_b32_e64 v17, v42, v50, s[40:41]
	s_waitcnt lgkmcnt(0)
	v_add_u32_e32 v17, v17, v18
	v_cndmask_b32_e64 v18, v39, v38, s[40:41]
	s_waitcnt lgkmcnt(0)
	v_add_u32_e32 v18, v18, v19
	v_cndmask_b32_e64 v19, v26, v34, s[40:41]
	s_waitcnt lgkmcnt(0)
	v_add_u32_e32 v19, v19, v21
	v_cndmask_b32_e64 v21, v23, v22, s[40:41]
	v_cndmask_b32_e64 v22, v22, v23, s[40:41]
	s_nop 1
	v_mov_b32_dpp v22, v22 quad_perm:[1,0,3,2] row_mask:0xf bank_mask:0xf
	s_waitcnt lgkmcnt(0)
	v_add_u32_e32 v21, v21, v22
	v_cndmask_b32_e64 v22, v16, v20, s[40:41]
	v_cndmask_b32_e64 v16, v20, v16, s[40:41]
	v_cndmask_b32_e64 v20, v13, v12, s[40:41]
	v_cndmask_b32_e64 v12, v12, v13, s[40:41]
	v_cndmask_b32_e64 v13, v9, v5, s[42:43]
	v_cndmask_b32_e64 v5, v5, v9, s[42:43]
	s_nop 1
	v_mov_b32_dpp v5, v5 quad_perm:[2,3,0,1] row_mask:0xf bank_mask:0xf
	s_nop 1
	v_mov_b32_dpp v16, v16 quad_perm:[1,0,3,2] row_mask:0xf bank_mask:0xf
	s_nop 1
	v_mov_b32_dpp v12, v12 quad_perm:[1,0,3,2] row_mask:0xf bank_mask:0xf
	v_cndmask_b32_e64 v9, v18, v17, s[42:43]
	s_waitcnt lgkmcnt(0)
	v_add_u32_e32 v5, v13, v5
	v_cndmask_b32_e64 v13, v17, v18, s[42:43]
	s_nop 1
	v_mov_b32_dpp v13, v13 quad_perm:[2,3,0,1] row_mask:0xf bank_mask:0xf
	v_cndmask_b32_e64 v17, v19, v21, s[42:43]
	s_nop 1
	v_mov_b32_dpp v17, v17 quad_perm:[2,3,0,1] row_mask:0xf bank_mask:0xf
	s_waitcnt lgkmcnt(0)
	v_add_u32_e32 v16, v22, v16
	s_waitcnt lgkmcnt(0)
	v_add_u32_e32 v12, v20, v12
	s_waitcnt lgkmcnt(0)
	v_add_u32_e32 v9, v9, v13
	v_cndmask_b32_e64 v13, v21, v19, s[42:43]
	s_waitcnt lgkmcnt(0)
	v_add_u32_e32 v13, v13, v17
	v_cndmask_b32_e64 v17, v12, v16, s[42:43]
	v_cndmask_b32_e64 v12, v16, v12, s[42:43]
	s_nop 1
	v_mov_b32_dpp v12, v12 quad_perm:[2,3,0,1] row_mask:0xf bank_mask:0xf
	v_cndmask_b32_e64 v16, v9, v5, s[44:45]
	v_cndmask_b32_e64 v5, v5, v9, s[44:45]
	s_nop 1
	v_mov_b32_dpp v5, v5 row_half_mirror row_mask:0xf bank_mask:0xf
	s_nop 1
	v_mov_b32_dpp v5, v5 quad_perm:[3,2,1,0] row_mask:0xf bank_mask:0xf
	s_waitcnt lgkmcnt(0)
	v_add_u32_e32 v12, v17, v12
	v_cndmask_b32_e64 v9, v12, v13, s[44:45]
	v_cndmask_b32_e64 v12, v13, v12, s[44:45]
	s_nop 1
	v_mov_b32_dpp v12, v12 row_half_mirror row_mask:0xf bank_mask:0xf
	s_nop 1
	v_mov_b32_dpp v12, v12 quad_perm:[3,2,1,0] row_mask:0xf bank_mask:0xf
	s_waitcnt lgkmcnt(0)
	v_add_u32_e32 v5, v16, v5
	s_waitcnt lgkmcnt(0)
	v_add_u32_e32 v9, v9, v12
	v_cndmask_b32_e64 v12, v9, v5, s[46:47]
	v_cndmask_b32_e64 v5, v5, v9, s[46:47]
	s_nop 1
	v_mov_b32_dpp v5, v5 row_ror:8 row_mask:0xf bank_mask:0xf
	s_waitcnt lgkmcnt(0)
	v_add_u32_e32 v5, v12, v5
	ds_swizzle_b32 v9, v5 offset:swizzle(SWAP,16)
	s_waitcnt lgkmcnt(0)
	v_add_u32_e32 v5, v5, v9
	ds_bpermute_b32 v12, v0, v5
	s_and_saveexec_b64 s[0:1], s[48:49]
	s_cbranch_execz .LBB0_683
	v_ashrrev_i32_e32 v9, 31, v8
	v_lshlrev_b64 v[8:9], 2, v[8:9]
	v_lshl_add_u64 v[16:17], s[8:9], 0, v[8:9]
	v_mov_b32_e32 v13, v134
	v_lshl_add_u64 v[8:9], s[10:11], 0, v[8:9]
	v_mov_b32_e32 v16, v150
	s_nop 0
	v_mov_b32_e32 v8, v142
	s_waitcnt lgkmcnt(0)
	v_add_u32_e32 v5, v5, v12
	v_cvt_f32_i32_e32 v5, v5
	v_mul_f32_e32 v5, v5, v13
	v_mul_f32_e32 v5, v3, v5
	v_mul_f32_e32 v12, 0x3d372713, v5
	v_mul_f32_e32 v12, v5, v12
	v_mul_f32_e32 v9, 0.5, v5
	v_fmac_f32_e32 v5, v5, v12
	v_mul_f32_e32 v5, 0x3f4c422a, v5
	v_add_f32_e32 v5, v5, v5
	v_mul_f32_e32 v5, 0x3fb8aa3b, v5
	v_exp_f32_e32 v5, v5
	s_nop 0
	v_add_f32_e32 v5, 1.0, v5
	v_rcp_f32_e32 v5, v5
	s_nop 0
	v_fma_f32 v5, v5, -2.0, 1.0
	v_add_f32_e32 v5, 1.0, v5
	v_mul_f32_e32 v5, v9, v5
	v_mul_f32_e32 v5, v16, v5
	v_mul_f32_e32 v5, v8, v5
	ds_write_b32 v109, v5 offset:384
.LBB0_683:
	s_or_b64 exec, exec, s[0:1]
	s_waitcnt vmcnt(15)
	v_dot8_i32_i4 v5, v88, v73, 0
	v_dot8_i32_i4 v8, v88, v75, 0
	v_dot8_i32_i4 v5, v89, v77, v5
	v_dot8_i32_i4 v8, v89, v108, v8
	s_waitcnt vmcnt(14)
	v_dot8_i32_i4 v9, v90, v75, 0
	v_dot8_i32_i4 v9, v91, v108, v9
	v_lshl_add_u32 v5, v5, 4, v8
	v_dot8_i32_i4 v8, v90, v73, 0
	v_dot8_i32_i4 v8, v91, v77, v8
	s_waitcnt lgkmcnt(0)
	s_waitcnt vmcnt(13)
	v_dot8_i32_i4 v12, v82, v75, 0
	v_dot8_i32_i4 v12, v83, v108, v12
	v_lshl_add_u32 v8, v8, 4, v9
	v_dot8_i32_i4 v9, v82, v73, 0
	v_dot8_i32_i4 v9, v83, v77, v9
	s_waitcnt vmcnt(12)
	v_dot8_i32_i4 v13, v92, v75, 0
	v_dot8_i32_i4 v13, v93, v108, v13
	v_lshl_add_u32 v9, v9, 4, v12
	v_dot8_i32_i4 v12, v92, v73, 0
	v_dot8_i32_i4 v12, v93, v77, v12
	s_waitcnt vmcnt(11)
	v_dot8_i32_i4 v16, v80, v75, 0
	v_dot8_i32_i4 v16, v81, v108, v16
	v_lshl_add_u32 v12, v12, 4, v13
	v_dot8_i32_i4 v13, v80, v73, 0
	v_dot8_i32_i4 v13, v81, v77, v13
	s_waitcnt vmcnt(10)
	v_dot8_i32_i4 v17, v52, v75, 0
	v_dot8_i32_i4 v17, v53, v108, v17
	v_lshl_add_u32 v13, v13, 4, v16
	v_dot8_i32_i4 v16, v52, v73, 0
	v_dot8_i32_i4 v16, v53, v77, v16
	s_waitcnt vmcnt(9)
	v_dot8_i32_i4 v18, v46, v75, 0
	v_dot8_i32_i4 v18, v47, v108, v18
	v_lshl_add_u32 v16, v16, 4, v17
	v_dot8_i32_i4 v17, v46, v73, 0
	v_dot8_i32_i4 v17, v47, v77, v17
	s_waitcnt vmcnt(8)
	v_dot8_i32_i4 v19, v56, v75, 0
	v_dot8_i32_i4 v19, v57, v108, v19
	v_lshl_add_u32 v17, v17, 4, v18
	v_dot8_i32_i4 v18, v56, v73, 0
	v_dot8_i32_i4 v18, v57, v77, v18
	s_waitcnt vmcnt(7)
	v_dot8_i32_i4 v20, v44, v75, 0
	v_dot8_i32_i4 v20, v45, v108, v20
	v_lshl_add_u32 v18, v18, 4, v19
	v_dot8_i32_i4 v19, v44, v73, 0
	v_dot8_i32_i4 v19, v45, v77, v19
	s_waitcnt vmcnt(6)
	v_dot8_i32_i4 v21, v36, v75, 0
	v_dot8_i32_i4 v21, v37, v108, v21
	v_lshl_add_u32 v19, v19, 4, v20
	v_dot8_i32_i4 v20, v36, v73, 0
	v_dot8_i32_i4 v20, v37, v77, v20
	s_waitcnt vmcnt(5)
	v_dot8_i32_i4 v22, v32, v75, 0
	v_dot8_i32_i4 v22, v33, v108, v22
	v_lshl_add_u32 v20, v20, 4, v21
	v_dot8_i32_i4 v21, v32, v73, 0
	v_dot8_i32_i4 v21, v33, v77, v21
	s_waitcnt vmcnt(4)
	v_dot8_i32_i4 v23, v40, v75, 0
	v_dot8_i32_i4 v23, v41, v108, v23
	v_lshl_add_u32 v21, v21, 4, v22
	v_dot8_i32_i4 v22, v40, v73, 0
	v_dot8_i32_i4 v22, v41, v77, v22
	s_waitcnt vmcnt(3)
	v_dot8_i32_i4 v26, v28, v75, 0
	v_dot8_i32_i4 v26, v29, v108, v26
	v_lshl_add_u32 v22, v22, 4, v23
	v_dot8_i32_i4 v23, v28, v73, 0
	v_dot8_i32_i4 v23, v29, v77, v23
	s_waitcnt vmcnt(2)
	v_dot8_i32_i4 v27, v14, v75, 0
	v_dot8_i32_i4 v27, v15, v108, v27
	v_lshl_add_u32 v23, v23, 4, v26
	v_dot8_i32_i4 v26, v14, v73, 0
	v_dot8_i32_i4 v26, v15, v77, v26
	s_waitcnt vmcnt(1)
	v_dot8_i32_i4 v15, v10, v73, 0
	s_nop 0
	v_lshl_add_u32 v14, v26, 4, v27
	v_dot8_i32_i4 v26, v10, v75, 0
	v_dot8_i32_i4 v15, v11, v77, v15
	v_dot8_i32_i4 v26, v11, v108, v26
	s_waitcnt vmcnt(0)
	v_dot8_i32_i4 v11, v24, v73, 0
	v_dot8_i32_i4 v11, v25, v77, v11
	v_lshl_add_u32 v10, v15, 4, v26
	v_dot8_i32_i4 v15, v24, v75, 0
	v_dot8_i32_i4 v15, v25, v108, v15
	s_nop 1
	s_nop 0
	v_lshl_add_u32 v11, v11, 4, v15
	v_cndmask_b32_e64 v15, v8, v5, s[40:41]
	v_cndmask_b32_e64 v5, v5, v8, s[40:41]
	v_cndmask_b32_e64 v8, v9, v12, s[40:41]
	s_nop 1
	v_mov_b32_dpp v8, v8 quad_perm:[1,0,3,2] row_mask:0xf bank_mask:0xf
	s_nop 1
	v_mov_b32_dpp v5, v5 quad_perm:[1,0,3,2] row_mask:0xf bank_mask:0xf
	v_cndmask_b32_e64 v9, v12, v9, s[40:41]
	v_cndmask_b32_e64 v24, v13, v16, s[40:41]
	s_waitcnt lgkmcnt(0)
	v_add_u32_e32 v8, v9, v8
	v_cndmask_b32_e64 v9, v16, v13, s[40:41]
	v_cndmask_b32_e64 v13, v17, v18, s[40:41]
	s_waitcnt lgkmcnt(0)
	v_add_u32_e32 v5, v15, v5
	s_nop 1
	v_mov_b32_dpp v13, v13 quad_perm:[1,0,3,2] row_mask:0xf bank_mask:0xf
	v_cndmask_b32_e64 v15, v19, v20, s[40:41]
	s_nop 1
	v_mov_b32_dpp v15, v15 quad_perm:[1,0,3,2] row_mask:0xf bank_mask:0xf
	v_cndmask_b32_e64 v16, v21, v22, s[40:41]
	s_nop 1
	v_mov_b32_dpp v16, v16 quad_perm:[1,0,3,2] row_mask:0xf bank_mask:0xf
	v_cndmask_b32_e64 v12, v18, v17, s[40:41]
	s_waitcnt lgkmcnt(0)
	v_add_u32_e32 v12, v12, v13
	v_cndmask_b32_e64 v13, v20, v19, s[40:41]
	s_waitcnt lgkmcnt(0)
	v_add_u32_e32 v13, v13, v15
	v_cndmask_b32_e64 v15, v22, v21, s[40:41]
	s_nop 1
	v_mov_b32_dpp v24, v24 quad_perm:[1,0,3,2] row_mask:0xf bank_mask:0xf
	s_waitcnt lgkmcnt(0)
	v_add_u32_e32 v15, v15, v16
	v_cndmask_b32_e64 v16, v14, v23, s[40:41]
	v_cndmask_b32_e64 v14, v23, v14, s[40:41]
	v_cndmask_b32_e64 v17, v10, v11, s[40:41]
	s_nop 1
	v_mov_b32_dpp v14, v14 quad_perm:[1,0,3,2] row_mask:0xf bank_mask:0xf
	s_nop 1
	v_mov_b32_dpp v17, v17 quad_perm:[1,0,3,2] row_mask:0xf bank_mask:0xf
	s_waitcnt lgkmcnt(0)
	v_add_u32_e32 v9, v9, v24
	v_cndmask_b32_e64 v10, v11, v10, s[40:41]
	v_cndmask_b32_e64 v18, v5, v8, s[42:43]
	s_waitcnt lgkmcnt(0)
	v_add_u32_e32 v14, v16, v14
	s_waitcnt lgkmcnt(0)
	v_add_u32_e32 v10, v10, v17
	v_cndmask_b32_e64 v5, v8, v5, s[42:43]
	v_cndmask_b32_e64 v8, v12, v9, s[42:43]
	v_cndmask_b32_e64 v9, v9, v12, s[42:43]
	s_nop 1
	v_mov_b32_dpp v9, v9 quad_perm:[2,3,0,1] row_mask:0xf bank_mask:0xf
	v_cndmask_b32_e64 v11, v13, v15, s[42:43]
	v_cndmask_b32_e64 v12, v14, v10, s[42:43]
	s_nop 1
	v_mov_b32_dpp v18, v18 quad_perm:[2,3,0,1] row_mask:0xf bank_mask:0xf
	s_nop 1
	v_mov_b32_dpp v11, v11 quad_perm:[2,3,0,1] row_mask:0xf bank_mask:0xf
	s_nop 1
	v_mov_b32_dpp v12, v12 quad_perm:[2,3,0,1] row_mask:0xf bank_mask:0xf
	s_waitcnt lgkmcnt(0)
	v_add_u32_e32 v8, v8, v9
	v_cndmask_b32_e64 v9, v15, v13, s[42:43]
	v_cndmask_b32_e64 v10, v10, v14, s[42:43]
	s_waitcnt lgkmcnt(0)
	v_add_u32_e32 v5, v5, v18
	s_waitcnt lgkmcnt(0)
	v_add_u32_e32 v9, v9, v11
	s_waitcnt lgkmcnt(0)
	v_add_u32_e32 v10, v10, v12
	v_cndmask_b32_e64 v11, v5, v8, s[44:45]
	v_cndmask_b32_e64 v12, v9, v10, s[44:45]
	s_nop 1
	v_mov_b32_dpp v11, v11 row_half_mirror row_mask:0xf bank_mask:0xf
	s_nop 1
	v_mov_b32_dpp v11, v11 quad_perm:[3,2,1,0] row_mask:0xf bank_mask:0xf
	s_nop 1
	v_mov_b32_dpp v12, v12 row_half_mirror row_mask:0xf bank_mask:0xf
	s_nop 1
	v_mov_b32_dpp v12, v12 quad_perm:[3,2,1,0] row_mask:0xf bank_mask:0xf
	v_cndmask_b32_e64 v5, v8, v5, s[44:45]
	v_cndmask_b32_e64 v8, v10, v9, s[44:45]
	s_waitcnt lgkmcnt(0)
	v_add_u32_e32 v5, v5, v11
	s_waitcnt lgkmcnt(0)
	v_add_u32_e32 v8, v8, v12
	v_cndmask_b32_e64 v9, v5, v8, s[46:47]
	s_nop 1
	v_mov_b32_dpp v9, v9 row_ror:8 row_mask:0xf bank_mask:0xf
	v_cndmask_b32_e64 v5, v8, v5, s[46:47]
	s_waitcnt lgkmcnt(0)
	v_add_u32_e32 v5, v5, v9
	ds_swizzle_b32 v8, v5 offset:swizzle(SWAP,16)
	s_waitcnt lgkmcnt(0)
	v_add_u32_e32 v8, v5, v8
	ds_bpermute_b32 v0, v0, v8
	s_and_saveexec_b64 s[0:1], s[48:49]
	s_cbranch_execz .LBB0_666
	v_ashrrev_i32_e32 v5, 31, v4
	v_lshlrev_b64 v[4:5], 2, v[4:5]
	v_lshl_add_u64 v[10:11], s[8:9], 0, v[4:5]
	v_mov_b32_e32 v9, v135
	v_lshl_add_u64 v[4:5], s[10:11], 0, v[4:5]
	v_mov_b32_e32 v6, v151
	s_nop 0
	v_mov_b32_e32 v4, v143
	s_waitcnt lgkmcnt(0)
	v_add_u32_e32 v0, v8, v0
	v_cvt_f32_i32_e32 v0, v0
	v_mul_f32_e32 v0, v0, v9
	v_mul_f32_e32 v0, v3, v0
	v_mul_f32_e32 v5, 0x3d372713, v0
	v_mul_f32_e32 v5, v0, v5
	v_mul_f32_e32 v3, 0.5, v0
	v_fmac_f32_e32 v0, v0, v5
	v_mul_f32_e32 v0, 0x3f4c422a, v0
	v_add_f32_e32 v0, v0, v0
	v_mul_f32_e32 v0, 0x3fb8aa3b, v0
	v_exp_f32_e32 v0, v0
	s_nop 0
	v_add_f32_e32 v0, 1.0, v0
	v_rcp_f32_e32 v0, v0
	s_nop 0
	v_fma_f32 v0, v0, -2.0, 1.0
	v_add_f32_e32 v0, 1.0, v0
	v_mul_f32_e32 v0, v3, v0
	v_mul_f32_e32 v0, v6, v0
	v_mul_f32_e32 v0, v4, v0
	ds_write_b32 v109, v0 offset:448
	s_branch .LBB0_666
